# fix-up pass wave sums via DPP / permlane swaps as well (bit-identical)
# speedup vs baseline: 1.0052x; 1.0052x over previous
; __device__ __forceinline__ int launder_i(int x) { asm volatile("" : "+v"(x)); return x; }
; #define m_norm_w KIN(8)
; __global__ void __launch_bounds__(NTHREADS, 2) fwd_megakernel(Params P) {
;     ...
;         { const int tid = launder_i(threadIdx.x), lane = tid & 63, wid = tid >> 6;
;         const bf16_t* q_mp = B_MPART; const float* q_dp = B_DPART; const bf16_t* q_hp = B_HPART; const float* q_mnw = m_norm_w; const float* q_gnw = g_norm_w; const bf16_t* q_proj = B_PROJ; bf16_t* q_hcat = B_HCAT;
;         const int step = G * NWAVES;
;         for (int it0 = bid * NWAVES + wid; it0 < T * 4; it0 += 2 * step) {
;             f32x4 v[2]; float den[2]; u32x2 mo[2]; bool ok[2];
; #pragma unroll
;             for (int q = 0; q < 2; ++q) {
;                 const int it = it0 + q * step; ok[q] = it < T * 4; const int itc = ok[q] ? it : it0;
;                 const int row = itc >> 2, h = itc & 3; const size_t o = (size_t)row * 1024 + h * 256 + 4 * lane;
;                 v[q] = (f32x4){0.f, 0.f, 0.f, 0.f}; den[q] = 0.f;
; #pragma unroll
;                 for (int dq = 0; dq < 4; ++dq) { const u32x2 p = *(const u32x2*)(q_mp + (size_t)dq * T * 1024 + o);
;                     v[q][0] += bflo(p.x); v[q][1] += bfhi(p.x); v[q][2] += bflo(p.y); v[q][3] += bfhi(p.y); den[q] += q_dp[(size_t)dq * T * 4 + (size_t)row * 4 + h]; }
;                 mo[q] = *(const u32x2*)(q_proj + (size_t)row * NP + C_MO + h * 256 + 4 * lane);
.LBB0_541:
	s_or_b64 exec, exec, s[28:29]
	v_mov_b32_e32 v9, v252
	s_waitcnt lgkmcnt(0)
	s_barrier
	v_readlane_b32 s4, v253, 2
	v_ashrrev_i32_e32 v8, 6, v9
	s_mov_b64 s[48:49], s[0:1]
	v_add_u32_e32 v1, s4, v8
	s_mov_b32 s4, 0x8000
	s_mov_b64 s[44:45], s[0:1]
	s_mov_b64 s[42:43], s[0:1]
	s_mov_b64 s[34:35], s[0:1]
	s_mov_b64 s[40:41], s[0:1]
	s_mov_b64 s[46:47], s[0:1]
	s_mov_b64 s[38:39], s[0:1]
	v_cmp_gt_i32_e32 vcc, s4, v1
	s_and_saveexec_b64 s[28:29], vcc
	s_cbranch_execz .LBB0_550
	v_and_b32_e32 v2, 64, v217
	v_add_u32_e32 v2, 64, v2
	v_xor_b32_e32 v3, 1, v217
	v_cmp_lt_i32_e32 vcc, v3, v2
	s_load_dwordx2 s[4:5], s[48:49], 0xc0
	s_load_dwordx2 s[6:7], s[44:45], 0xc0
	s_nop 0
	s_load_dwordx2 s[42:43], s[42:43], 0xc0
	s_nop 0
	s_load_dwordx2 s[8:9], s[46:47], 0xc0
	v_cndmask_b32_e32 v3, v217, v3, vcc
	v_lshlrev_b32_e32 v7, 2, v3
	v_xor_b32_e32 v3, 2, v217
	v_cmp_lt_i32_e32 vcc, v3, v2
	s_waitcnt lgkmcnt(0)
	s_add_u32 s48, s4, 0x31000000
	s_addc_u32 s49, s5, 0
	v_cndmask_b32_e32 v3, v217, v3, vcc
	v_lshlrev_b32_e32 v35, 2, v3
	v_xor_b32_e32 v3, 4, v217
	v_cmp_lt_i32_e32 vcc, v3, v2
	s_add_u32 s50, s6, 0x3b0c0000
	s_addc_u32 s51, s7, 0
	v_cndmask_b32_e32 v3, v217, v3, vcc
	v_lshlrev_b32_e32 v36, 2, v3
	v_xor_b32_e32 v3, 8, v217
	v_cmp_lt_i32_e32 vcc, v3, v2
	s_load_dwordx2 s[4:5], s[34:35], 0x40
	s_load_dwordx2 s[44:45], s[40:41], 0x60
	v_cndmask_b32_e32 v3, v217, v3, vcc
	v_lshlrev_b32_e32 v37, 2, v3
	v_xor_b32_e32 v3, 16, v217
	v_cmp_lt_i32_e32 vcc, v3, v2
	s_add_u32 s34, s8, 0x19000000
	s_load_dwordx2 s[46:47], s[38:39], 0xc0
	v_cndmask_b32_e32 v3, v217, v3, vcc
	s_addc_u32 s35, s9, 0
	v_lshlrev_b32_e32 v38, 2, v3
	v_xor_b32_e32 v3, 32, v217
	s_lshl_b32 s36, s82, 10
	v_cmp_lt_i32_e32 vcc, v3, v2
	s_lshl_b64 s[6:7], s[36:37], 2
	v_and_b32_e32 v4, 63, v9
	v_cndmask_b32_e32 v2, v217, v3, vcc
	s_waitcnt lgkmcnt(0)
	s_add_u32 s4, s4, s6
	v_lshlrev_b32_e32 v40, 2, v2
	s_addc_u32 s5, s5, s7
	v_lshlrev_b32_e32 v2, 4, v4
	v_mov_b32_e32 v3, v0
	v_lshlrev_b32_e32 v10, 3, v4
	v_mov_b32_e32 v11, v0
	v_bfe_u32 v9, v9, 6, 2
	v_lshlrev_b32_e32 v6, 2, v4
	v_lshl_add_u64 v[2:3], s[4:5], 0, v[2:3]
	v_lshl_add_u64 v[4:5], s[46:47], 0, v[10:11]
	s_mov_b64 s[4:5], 0x2a000000
	v_lshlrev_b32_e32 v12, 9, v9
	v_mov_b32_e32 v13, v0
	v_lshl_add_u64 v[4:5], v[4:5], 0, s[4:5]
	v_lshl_add_u64 v[12:13], s[48:49], 0, v[12:13]
	v_readlane_b32 s4, v254, 52
	v_lshlrev_b32_e32 v14, 8, v9
	v_lshl_add_u64 v[10:11], v[12:13], 0, v[10:11]
	v_lshlrev_b32_e32 v12, 2, v9
	v_mov_b32_e32 v13, v0
	v_lshl_add_u32 v39, v8, 8, s4
	v_lshl_add_u64 v[12:13], s[50:51], 0, v[12:13]
	s_mov_b64 s[52:53], 0
	v_lshlrev_b32_e32 v14, 1, v14
	v_mov_b32_e32 v41, v39
	v_mov_b32_e32 v42, v1
	s_cmpk_lg_i32 s78, 0x100
	s_cbranch_scc1 .LBB0_544
	v_readfirstlane_b32 s4, v1
	v_lshlrev_b32_e32 v8, 1, v6
	v_mov_b32_e32 v19, 0
	s_and_b32 s5, s4, 3
	s_lshr_b32 s4, s4, 2
	s_lshl_b32 s6, s4, 11
	s_lshl_b32 s7, s5, 9
	s_add_u32 s6, s6, s7
	v_add_u32_e32 v15, s6, v8
	v_mov_b32_e32 v33, v15
	s_lshl_b32 s6, s4, 4
	s_lshl_b32 s8, s5, 2
	s_add_u32 s6, s6, s8
	v_mov_b32_e32 v16, s6
	s_mul_i32 s8, s4, s25
	s_add_u32 s8, s8, s7
	s_add_u32 s8, s8, 0x1800
	v_add_u32_e32 v17, s8, v8
	s_lshl_b32 s9, s5, 10
	v_mov_b32_e32 v18, s9
	v_lshl_add_u64 v[18:19], v[2:3], 0, v[18:19]
	global_load_dwordx4 v[20:23], v[18:19], off
	s_add_u32 s4, s48, 0x1000000
	s_addc_u32 s5, s49, 0
	s_add_u32 s6, s48, 0x2000000
	s_addc_u32 s7, s49, 0
	s_add_u32 s8, s48, 0x3000000
	s_addc_u32 s9, s49, 0
	s_add_u32 s38, s46, 0x2a000000
	s_addc_u32 s39, s47, 0
	global_load_dwordx2 v[54:55], v15, s[48:49]
	global_load_dwordx2 v[56:57], v15, s[4:5]
	global_load_dwordx2 v[58:59], v15, s[6:7]
	global_load_dwordx2 v[60:61], v15, s[8:9]
	v_add_u32_e32 v24, 0x20000, v16
	v_add_u32_e32 v25, 0x40000, v16
	v_add_u32_e32 v26, 0x60000, v16
	global_load_dword v62, v16, s[50:51]
	global_load_dword v63, v24, s[50:51]
	global_load_dword v64, v25, s[50:51]
	global_load_dword v65, v26, s[50:51]
	global_load_dwordx2 v[66:67], v17, s[34:35]
	v_add_u32_e32 v15, 0x100000, v15
	v_add_u32_e32 v16, 0x2000, v16
	v_add_u32_e32 v17, 0x1100000, v17
	global_load_dwordx2 v[68:69], v15, s[48:49]
	global_load_dwordx2 v[70:71], v15, s[4:5]
	global_load_dwordx2 v[72:73], v15, s[6:7]
	global_load_dwordx2 v[74:75], v15, s[8:9]
	v_add_u32_e32 v24, 0x20000, v16
	v_add_u32_e32 v25, 0x40000, v16
	v_add_u32_e32 v26, 0x60000, v16
	global_load_dword v76, v16, s[50:51]
	global_load_dword v77, v24, s[50:51]
	global_load_dword v78, v25, s[50:51]
	global_load_dword v79, v26, s[50:51]
	global_load_dwordx2 v[80:81], v17, s[34:35]
	v_add_u32_e32 v15, 0x100000, v15
	v_add_u32_e32 v16, 0x2000, v16
	v_add_u32_e32 v17, 0x1100000, v17
	global_load_dwordx2 v[82:83], v15, s[48:49]
	global_load_dwordx2 v[84:85], v15, s[4:5]
	global_load_dwordx2 v[86:87], v15, s[6:7]
	global_load_dwordx2 v[88:89], v15, s[8:9]
	v_add_u32_e32 v24, 0x20000, v16
	v_add_u32_e32 v25, 0x40000, v16
	v_add_u32_e32 v26, 0x60000, v16
	global_load_dword v90, v16, s[50:51]
	global_load_dword v91, v24, s[50:51]
	global_load_dword v92, v25, s[50:51]
	global_load_dword v93, v26, s[50:51]
	global_load_dwordx2 v[94:95], v17, s[34:35]
	v_add_u32_e32 v15, 0x100000, v15
	v_add_u32_e32 v16, 0x2000, v16
	v_add_u32_e32 v17, 0x1100000, v17
	global_load_dwordx2 v[96:97], v15, s[48:49]
	global_load_dwordx2 v[98:99], v15, s[4:5]
	global_load_dwordx2 v[100:101], v15, s[6:7]
	global_load_dwordx2 v[102:103], v15, s[8:9]
	v_add_u32_e32 v24, 0x20000, v16
	v_add_u32_e32 v25, 0x40000, v16
	v_add_u32_e32 v26, 0x60000, v16
	global_load_dword v104, v16, s[50:51]
	global_load_dword v105, v24, s[50:51]
	global_load_dword v106, v25, s[50:51]
	global_load_dword v107, v26, s[50:51]
; __global__ void __launch_bounds__(NTHREADS, 2) fwd_megakernel(Params P) {
;     ...
;             for (int q = 0; q < 2; ++q) {
;                 const int it = it0 + q * step; ok[q] = it < T * 4; const int itc = ok[q] ? it : it0;
;                 const int row = itc >> 2, h = itc & 3; const size_t o = (size_t)row * 1024 + h * 256 + 4 * lane;
;                 v[q] = (f32x4){0.f, 0.f, 0.f, 0.f}; den[q] = 0.f;
; #pragma unroll
;                 for (int dq = 0; dq < 4; ++dq) { const u32x2 p = *(const u32x2*)(q_mp + (size_t)dq * T * 1024 + o);
;                     v[q][0] += bflo(p.x); v[q][1] += bfhi(p.x); v[q][2] += bflo(p.y); v[q][3] += bfhi(p.y); den[q] += q_dp[(size_t)dq * T * 4 + (size_t)row * 4 + h]; }
;                 mo[q] = *(const u32x2*)(q_proj + (size_t)row * NP + C_MO + h * 256 + 4 * lane);
;             }
; #pragma unroll
;             for (int q = 0; q < 2; ++q) {
;                 const int it = it0 + q * step; const int itc = ok[q] ? it : it0; const int row = itc >> 2, h = itc & 3;
;                 const f32x4 x = v[q] * (1.0f / fmaxf(fabsf(den[q]), 1.0f));
;                 const float ss = wave_sum((x[0] * x[0] + x[1] * x[1]) + (x[2] * x[2] + x[3] * x[3]));
;                 const float rsn = 1.0f / sqrtf(ss * (1.0f / 256.0f) + NORM_EPS);
	global_load_dwordx2 v[108:109], v17, s[34:35]
	v_add_u32_e32 v15, 0x100000, v15
	v_add_u32_e32 v16, 0x2000, v16
	v_add_u32_e32 v17, 0x1100000, v17
	global_load_dwordx2 v[110:111], v15, s[48:49]
	global_load_dwordx2 v[112:113], v15, s[4:5]
	global_load_dwordx2 v[114:115], v15, s[6:7]
	global_load_dwordx2 v[116:117], v15, s[8:9]
	v_add_u32_e32 v24, 0x20000, v16
	v_add_u32_e32 v25, 0x40000, v16
	v_add_u32_e32 v26, 0x60000, v16
	global_load_dword v118, v16, s[50:51]
	global_load_dword v119, v24, s[50:51]
	global_load_dword v120, v25, s[50:51]
	global_load_dword v121, v26, s[50:51]
	global_load_dwordx2 v[122:123], v17, s[34:35]
	v_add_u32_e32 v15, 0x100000, v15
	v_add_u32_e32 v16, 0x2000, v16
	v_add_u32_e32 v17, 0x1100000, v17
	global_load_dwordx2 v[124:125], v15, s[48:49]
	global_load_dwordx2 v[126:127], v15, s[4:5]
	global_load_dwordx2 v[128:129], v15, s[6:7]
	global_load_dwordx2 v[130:131], v15, s[8:9]
	v_add_u32_e32 v24, 0x20000, v16
	v_add_u32_e32 v25, 0x40000, v16
	v_add_u32_e32 v26, 0x60000, v16
	global_load_dword v132, v16, s[50:51]
	global_load_dword v133, v24, s[50:51]
	global_load_dword v134, v25, s[50:51]
	global_load_dword v135, v26, s[50:51]
	global_load_dwordx2 v[136:137], v17, s[34:35]
	v_add_u32_e32 v15, 0x100000, v15
	v_add_u32_e32 v16, 0x2000, v16
	v_add_u32_e32 v17, 0x1100000, v17
	global_load_dwordx2 v[138:139], v15, s[48:49]
	global_load_dwordx2 v[140:141], v15, s[4:5]
	global_load_dwordx2 v[142:143], v15, s[6:7]
	global_load_dwordx2 v[144:145], v15, s[8:9]
	v_add_u32_e32 v24, 0x20000, v16
	v_add_u32_e32 v25, 0x40000, v16
	v_add_u32_e32 v26, 0x60000, v16
	global_load_dword v146, v16, s[50:51]
	global_load_dword v147, v24, s[50:51]
	global_load_dword v148, v25, s[50:51]
	global_load_dword v149, v26, s[50:51]
	global_load_dwordx2 v[150:151], v17, s[34:35]
	v_add_u32_e32 v15, 0x100000, v15
	v_add_u32_e32 v16, 0x2000, v16
	v_add_u32_e32 v17, 0x1100000, v17
	global_load_dwordx2 v[152:153], v15, s[48:49]
	global_load_dwordx2 v[154:155], v15, s[4:5]
	global_load_dwordx2 v[156:157], v15, s[6:7]
	global_load_dwordx2 v[158:159], v15, s[8:9]
	v_add_u32_e32 v24, 0x20000, v16
	v_add_u32_e32 v25, 0x40000, v16
	v_add_u32_e32 v26, 0x60000, v16
	global_load_dword v160, v16, s[50:51]
	global_load_dword v161, v24, s[50:51]
	global_load_dword v162, v25, s[50:51]
	global_load_dword v163, v26, s[50:51]
	global_load_dwordx2 v[164:165], v17, s[34:35]
	v_add_u32_e32 v15, 0x100000, v15
	v_add_u32_e32 v16, 0x2000, v16
	v_add_u32_e32 v17, 0x1100000, v17
	s_waitcnt vmcnt(36)
	v_lshlrev_b32_e32 v166, 16, v54
	v_and_b32_e32 v167, 0xffff0000, v54
	v_lshlrev_b32_e32 v168, 16, v55
	v_and_b32_e32 v169, 0xffff0000, v55
	v_lshlrev_b32_e32 v190, 16, v56
	v_and_b32_e32 v191, 0xffff0000, v56
	v_lshlrev_b32_e32 v192, 16, v57
	v_and_b32_e32 v193, 0xffff0000, v57
	v_pk_add_f32 v[166:167], v[166:167], v[190:191]
	v_pk_add_f32 v[168:169], v[168:169], v[192:193]
	v_lshlrev_b32_e32 v190, 16, v58
	v_and_b32_e32 v191, 0xffff0000, v58
	v_lshlrev_b32_e32 v192, 16, v59
	v_and_b32_e32 v193, 0xffff0000, v59
	v_pk_add_f32 v[166:167], v[166:167], v[190:191]
	v_pk_add_f32 v[168:169], v[168:169], v[192:193]
	v_lshlrev_b32_e32 v190, 16, v60
	v_and_b32_e32 v191, 0xffff0000, v60
	v_lshlrev_b32_e32 v192, 16, v61
	v_and_b32_e32 v193, 0xffff0000, v61
	v_pk_add_f32 v[166:167], v[166:167], v[190:191]
	v_pk_add_f32 v[168:169], v[168:169], v[192:193]
	v_add_f32_e32 v194, 0, v62
	v_add_f32_e32 v194, v194, v63
	v_add_f32_e32 v194, v194, v64
	v_add_f32_e32 v194, v194, v65
	v_max_f32_e64 v194, |v194|, 1.0
	v_div_scale_f32 v196, s[52:53], v194, v194, 1.0
	v_rcp_f32_e32 v197, v196
	s_nop 0
	v_fma_f32 v198, -v196, v197, 1.0
	v_fmac_f32_e32 v197, v198, v197
	v_div_scale_f32 v198, vcc, 1.0, v194, 1.0
	v_mul_f32_e32 v199, v198, v197
	v_fma_f32 v195, -v196, v199, v198
	v_fmac_f32_e32 v199, v195, v197
	v_fma_f32 v196, -v196, v199, v198
	v_div_fmas_f32 v196, v196, v197, v199
	v_div_fixup_f32 v195, v196, v194, 1.0
	v_mul_f32_e32 v166, v166, v195
	v_mul_f32_e32 v167, v167, v195
	v_mul_f32_e32 v168, v168, v195
	v_mul_f32_e32 v169, v169, v195
	v_mul_f32_e32 v190, v166, v166
	v_mul_f32_e32 v191, v167, v167
	v_mul_f32_e32 v192, v168, v168
	v_mul_f32_e32 v193, v169, v169
	v_add_f32_e32 v190, v191, v190
	v_add_f32_e32 v192, v192, v193
	v_add_f32_e32 v170, v190, v192
	v_lshlrev_b32_e32 v172, 16, v68
	v_and_b32_e32 v173, 0xffff0000, v68
	v_lshlrev_b32_e32 v174, 16, v69
	v_and_b32_e32 v175, 0xffff0000, v69
	v_lshlrev_b32_e32 v190, 16, v70
	v_and_b32_e32 v191, 0xffff0000, v70
	v_lshlrev_b32_e32 v192, 16, v71
	v_and_b32_e32 v193, 0xffff0000, v71
	v_pk_add_f32 v[172:173], v[172:173], v[190:191]
	v_pk_add_f32 v[174:175], v[174:175], v[192:193]
	v_lshlrev_b32_e32 v190, 16, v72
	v_and_b32_e32 v191, 0xffff0000, v72
	v_lshlrev_b32_e32 v192, 16, v73
	v_and_b32_e32 v193, 0xffff0000, v73
	v_pk_add_f32 v[172:173], v[172:173], v[190:191]
	v_pk_add_f32 v[174:175], v[174:175], v[192:193]
	v_lshlrev_b32_e32 v190, 16, v74
	v_and_b32_e32 v191, 0xffff0000, v74
	v_lshlrev_b32_e32 v192, 16, v75
	v_and_b32_e32 v193, 0xffff0000, v75
	v_pk_add_f32 v[172:173], v[172:173], v[190:191]
	v_pk_add_f32 v[174:175], v[174:175], v[192:193]
	v_add_f32_e32 v194, 0, v76
	v_add_f32_e32 v194, v194, v77
	v_add_f32_e32 v194, v194, v78
	v_add_f32_e32 v194, v194, v79
	v_max_f32_e64 v194, |v194|, 1.0
	v_div_scale_f32 v196, s[52:53], v194, v194, 1.0
	v_rcp_f32_e32 v197, v196
	s_nop 0
	v_fma_f32 v198, -v196, v197, 1.0
	v_fmac_f32_e32 v197, v198, v197
	v_div_scale_f32 v198, vcc, 1.0, v194, 1.0
	v_mul_f32_e32 v199, v198, v197
	v_fma_f32 v195, -v196, v199, v198
	v_fmac_f32_e32 v199, v195, v197
	v_fma_f32 v196, -v196, v199, v198
	v_div_fmas_f32 v196, v196, v197, v199
; __global__ void __launch_bounds__(NTHREADS, 2) fwd_megakernel(Params P) {
;     ...
;                 const int it = it0 + q * step; ok[q] = it < T * 4; const int itc = ok[q] ? it : it0;
;                 const int row = itc >> 2, h = itc & 3; const size_t o = (size_t)row * 1024 + h * 256 + 4 * lane;
;                 v[q] = (f32x4){0.f, 0.f, 0.f, 0.f}; den[q] = 0.f;
; #pragma unroll
;                 for (int dq = 0; dq < 4; ++dq) { const u32x2 p = *(const u32x2*)(q_mp + (size_t)dq * T * 1024 + o);
;                     v[q][0] += bflo(p.x); v[q][1] += bfhi(p.x); v[q][2] += bflo(p.y); v[q][3] += bfhi(p.y); den[q] += q_dp[(size_t)dq * T * 4 + (size_t)row * 4 + h]; }
;                 mo[q] = *(const u32x2*)(q_proj + (size_t)row * NP + C_MO + h * 256 + 4 * lane);
;             }
; #pragma unroll
;             for (int q = 0; q < 2; ++q) {
;                 const int it = it0 + q * step; const int itc = ok[q] ? it : it0; const int row = itc >> 2, h = itc & 3;
;                 const f32x4 x = v[q] * (1.0f / fmaxf(fabsf(den[q]), 1.0f));
;                 const float ss = wave_sum((x[0] * x[0] + x[1] * x[1]) + (x[2] * x[2] + x[3] * x[3]));
;                 const float rsn = 1.0f / sqrtf(ss * (1.0f / 256.0f) + NORM_EPS);
	v_div_fixup_f32 v195, v196, v194, 1.0
	v_mul_f32_e32 v172, v172, v195
	v_mul_f32_e32 v173, v173, v195
	v_mul_f32_e32 v174, v174, v195
	v_mul_f32_e32 v175, v175, v195
	v_mul_f32_e32 v191, v175, v175
	v_mul_f32_e32 v190, v173, v173
	v_fmac_f32_e32 v190, v172, v172
	v_fmac_f32_e32 v191, v174, v174
	v_add_f32_e32 v176, v190, v191
	v_lshlrev_b32_e32 v178, 16, v82
	v_and_b32_e32 v179, 0xffff0000, v82
	v_lshlrev_b32_e32 v180, 16, v83
	v_and_b32_e32 v181, 0xffff0000, v83
	v_lshlrev_b32_e32 v190, 16, v84
	v_and_b32_e32 v191, 0xffff0000, v84
	v_lshlrev_b32_e32 v192, 16, v85
	v_and_b32_e32 v193, 0xffff0000, v85
	v_pk_add_f32 v[178:179], v[178:179], v[190:191]
	v_pk_add_f32 v[180:181], v[180:181], v[192:193]
	v_lshlrev_b32_e32 v190, 16, v86
	v_and_b32_e32 v191, 0xffff0000, v86
	v_lshlrev_b32_e32 v192, 16, v87
	v_and_b32_e32 v193, 0xffff0000, v87
	v_pk_add_f32 v[178:179], v[178:179], v[190:191]
	v_pk_add_f32 v[180:181], v[180:181], v[192:193]
	v_lshlrev_b32_e32 v190, 16, v88
	v_and_b32_e32 v191, 0xffff0000, v88
	v_lshlrev_b32_e32 v192, 16, v89
	v_and_b32_e32 v193, 0xffff0000, v89
	v_pk_add_f32 v[178:179], v[178:179], v[190:191]
	v_pk_add_f32 v[180:181], v[180:181], v[192:193]
	v_add_f32_e32 v194, 0, v90
	v_add_f32_e32 v194, v194, v91
	v_add_f32_e32 v194, v194, v92
	v_add_f32_e32 v194, v194, v93
	v_max_f32_e64 v194, |v194|, 1.0
	v_div_scale_f32 v196, s[52:53], v194, v194, 1.0
	v_rcp_f32_e32 v197, v196
	s_nop 0
	v_fma_f32 v198, -v196, v197, 1.0
	v_fmac_f32_e32 v197, v198, v197
	v_div_scale_f32 v198, vcc, 1.0, v194, 1.0
	v_mul_f32_e32 v199, v198, v197
	v_fma_f32 v195, -v196, v199, v198
	v_fmac_f32_e32 v199, v195, v197
	v_fma_f32 v196, -v196, v199, v198
	v_div_fmas_f32 v196, v196, v197, v199
	v_div_fixup_f32 v195, v196, v194, 1.0
	v_mul_f32_e32 v178, v178, v195
	v_mul_f32_e32 v179, v179, v195
	v_mul_f32_e32 v180, v180, v195
	v_mul_f32_e32 v181, v181, v195
	v_mul_f32_e32 v190, v178, v178
	v_mul_f32_e32 v191, v179, v179
	v_mul_f32_e32 v192, v180, v180
	v_mul_f32_e32 v193, v181, v181
	v_add_f32_e32 v190, v191, v190
	v_add_f32_e32 v192, v192, v193
	v_add_f32_e32 v182, v190, v192
	v_lshlrev_b32_e32 v184, 16, v96
	v_and_b32_e32 v185, 0xffff0000, v96
	v_lshlrev_b32_e32 v186, 16, v97
	v_and_b32_e32 v187, 0xffff0000, v97
	v_lshlrev_b32_e32 v190, 16, v98
	v_and_b32_e32 v191, 0xffff0000, v98
	v_lshlrev_b32_e32 v192, 16, v99
	v_and_b32_e32 v193, 0xffff0000, v99
	v_pk_add_f32 v[184:185], v[184:185], v[190:191]
	v_pk_add_f32 v[186:187], v[186:187], v[192:193]
	v_lshlrev_b32_e32 v190, 16, v100
	v_and_b32_e32 v191, 0xffff0000, v100
	v_lshlrev_b32_e32 v192, 16, v101
	v_and_b32_e32 v193, 0xffff0000, v101
	v_pk_add_f32 v[184:185], v[184:185], v[190:191]
	v_pk_add_f32 v[186:187], v[186:187], v[192:193]
	v_lshlrev_b32_e32 v190, 16, v102
	v_and_b32_e32 v191, 0xffff0000, v102
	v_lshlrev_b32_e32 v192, 16, v103
	v_and_b32_e32 v193, 0xffff0000, v103
	v_pk_add_f32 v[184:185], v[184:185], v[190:191]
	v_pk_add_f32 v[186:187], v[186:187], v[192:193]
	v_add_f32_e32 v194, 0, v104
	v_add_f32_e32 v194, v194, v105
	v_add_f32_e32 v194, v194, v106
	v_add_f32_e32 v194, v194, v107
	v_max_f32_e64 v194, |v194|, 1.0
	v_div_scale_f32 v196, s[52:53], v194, v194, 1.0
	v_rcp_f32_e32 v197, v196
	s_nop 0
	v_fma_f32 v198, -v196, v197, 1.0
	v_fmac_f32_e32 v197, v198, v197
	v_div_scale_f32 v198, vcc, 1.0, v194, 1.0
	v_mul_f32_e32 v199, v198, v197
	v_fma_f32 v195, -v196, v199, v198
	v_fmac_f32_e32 v199, v195, v197
	v_fma_f32 v196, -v196, v199, v198
	v_div_fmas_f32 v196, v196, v197, v199
	v_div_fixup_f32 v195, v196, v194, 1.0
	v_mul_f32_e32 v184, v184, v195
	v_mul_f32_e32 v185, v185, v195
	v_mul_f32_e32 v186, v186, v195
	v_mul_f32_e32 v187, v187, v195
	v_mul_f32_e32 v191, v187, v187
	v_mul_f32_e32 v190, v185, v185
	v_fmac_f32_e32 v190, v184, v184
	v_fmac_f32_e32 v191, v186, v186
	v_add_f32_e32 v188, v190, v191
	s_nop 1
	v_mov_b32_dpp v171, v170 quad_perm:[1,0,3,2] row_mask:0xf bank_mask:0xf
	v_mov_b32_dpp v177, v176 quad_perm:[1,0,3,2] row_mask:0xf bank_mask:0xf
	v_mov_b32_dpp v183, v182 quad_perm:[1,0,3,2] row_mask:0xf bank_mask:0xf
	v_mov_b32_dpp v189, v188 quad_perm:[1,0,3,2] row_mask:0xf bank_mask:0xf
	v_add_f32_e32 v170, v170, v171
	v_add_f32_e32 v176, v176, v177
	v_add_f32_e32 v182, v182, v183
	v_add_f32_e32 v188, v188, v189
	s_nop 1
	v_mov_b32_dpp v171, v170 quad_perm:[2,3,0,1] row_mask:0xf bank_mask:0xf
	v_mov_b32_dpp v177, v176 quad_perm:[2,3,0,1] row_mask:0xf bank_mask:0xf
	v_mov_b32_dpp v183, v182 quad_perm:[2,3,0,1] row_mask:0xf bank_mask:0xf
	v_mov_b32_dpp v189, v188 quad_perm:[2,3,0,1] row_mask:0xf bank_mask:0xf
	v_add_f32_e32 v170, v170, v171
	v_add_f32_e32 v176, v176, v177
	v_add_f32_e32 v182, v182, v183
	v_add_f32_e32 v188, v188, v189
	s_nop 1
	v_mov_b32_dpp v171, v170 row_half_mirror row_mask:0xf bank_mask:0xf
	v_mov_b32_dpp v177, v176 row_half_mirror row_mask:0xf bank_mask:0xf
	v_mov_b32_dpp v183, v182 row_half_mirror row_mask:0xf bank_mask:0xf
	v_mov_b32_dpp v189, v188 row_half_mirror row_mask:0xf bank_mask:0xf
	v_add_f32_e32 v170, v170, v171
	v_add_f32_e32 v176, v176, v177
	v_add_f32_e32 v182, v182, v183
	v_add_f32_e32 v188, v188, v189
	s_nop 1
	v_mov_b32_dpp v171, v170 row_mirror row_mask:0xf bank_mask:0xf
	v_mov_b32_dpp v177, v176 row_mirror row_mask:0xf bank_mask:0xf
	v_mov_b32_dpp v183, v182 row_mirror row_mask:0xf bank_mask:0xf
	v_mov_b32_dpp v189, v188 row_mirror row_mask:0xf bank_mask:0xf
	v_add_f32_e32 v170, v170, v171
	v_add_f32_e32 v176, v176, v177
	v_add_f32_e32 v182, v182, v183
	v_add_f32_e32 v188, v188, v189
	v_mov_b32_e32 v171, v170
	v_mov_b32_e32 v177, v176
	v_mov_b32_e32 v183, v182
	v_mov_b32_e32 v189, v188
	s_nop 1
	v_permlane16_swap_b32 v171, v170
; __device__ __forceinline__ unsigned pk2(float lo, float hi) { f32x2_t v = {lo, hi}; bf16x2_t b = __builtin_convertvector(v, bf16x2_t); return __builtin_bit_cast(unsigned, b); }
; __device__ __forceinline__ float sigmoidf_(float x) { return __builtin_amdgcn_rcpf(1.0f + __expf(-x)); }
; __global__ void __launch_bounds__(NTHREADS, 2) fwd_megakernel(Params P) {
;     ...
;                 const f32x4 x = v[q] * (1.0f / fmaxf(fabsf(den[q]), 1.0f));
;                 const float ss = wave_sum((x[0] * x[0] + x[1] * x[1]) + (x[2] * x[2] + x[3] * x[3]));
;                 const float rsn = 1.0f / sqrtf(ss * (1.0f / 256.0f) + NORM_EPS);
;                 const f32x4 wn = *(const f32x4*)(q_mnw + l * 1024 + h * 256 + 4 * lane);
;                 u32x2 ow;
;                 ow.x = pk2(x[0] * rsn * wn[0] * sigmoidf_(bflo(mo[q].x)), x[1] * rsn * wn[1] * sigmoidf_(bfhi(mo[q].x)));
;                 ow.y = pk2(x[2] * rsn * wn[2] * sigmoidf_(bflo(mo[q].y)), x[3] * rsn * wn[3] * sigmoidf_(bfhi(mo[q].y)));
;                 if (ok[q]) *(u32x2*)(q_hcat + (size_t)row * 1024 + h * 256 + 4 * lane) = ow;
	v_permlane16_swap_b32 v177, v176
	v_permlane16_swap_b32 v183, v182
	v_permlane16_swap_b32 v189, v188
	v_add_f32_e32 v170, v170, v171
	v_add_f32_e32 v176, v176, v177
	v_add_f32_e32 v182, v182, v183
	v_add_f32_e32 v188, v188, v189
	v_mov_b32_e32 v171, v170
	v_mov_b32_e32 v177, v176
	v_mov_b32_e32 v183, v182
	v_mov_b32_e32 v189, v188
	s_nop 1
	v_permlane32_swap_b32 v171, v170
	v_permlane32_swap_b32 v177, v176
	v_permlane32_swap_b32 v183, v182
	v_permlane32_swap_b32 v189, v188
	v_add_f32_e32 v170, v170, v171
	v_add_f32_e32 v176, v176, v177
	v_add_f32_e32 v182, v182, v183
	v_add_f32_e32 v188, v188, v189
	v_fmamk_f32 v170, v170, 0x3b800000, v214
	v_cmp_gt_f32_e32 vcc, s66, v170
	v_mul_f32_e32 v190, 0x4f800000, v170
	s_nop 0
	v_cndmask_b32_e32 v170, v170, v190, vcc
	v_sqrt_f32_e32 v190, v170
	s_nop 0
	v_add_u32_e32 v191, -1, v190
	v_fma_f32 v192, -v191, v190, v170
	v_cmp_ge_f32_e64 s[40:41], 0, v192
	v_add_u32_e32 v192, 1, v190
	s_nop 0
	v_cndmask_b32_e64 v191, v190, v191, s[40:41]
	v_fma_f32 v190, -v192, v190, v170
	v_cmp_lt_f32_e64 s[40:41], 0, v190
	s_nop 1
	v_cndmask_b32_e64 v190, v191, v192, s[40:41]
	v_mul_f32_e32 v191, 0x37800000, v190
	v_cndmask_b32_e32 v190, v190, v191, vcc
	v_cmp_class_f32_e32 vcc, v170, v215
	s_nop 1
	v_cndmask_b32_e32 v170, v190, v170, vcc
	v_div_scale_f32 v196, s[52:53], v170, v170, 1.0
	v_rcp_f32_e32 v197, v196
	s_nop 0
	v_fma_f32 v198, -v196, v197, 1.0
	v_fmac_f32_e32 v197, v198, v197
	v_div_scale_f32 v198, vcc, 1.0, v170, 1.0
	v_mul_f32_e32 v199, v198, v197
	v_fma_f32 v195, -v196, v199, v198
	v_fmac_f32_e32 v199, v195, v197
	v_fma_f32 v196, -v196, v199, v198
	v_div_fmas_f32 v196, v196, v197, v199
	v_div_fixup_f32 v195, v196, v170, 1.0
	v_mul_f32_e32 v166, v166, v195
	v_mul_f32_e32 v167, v167, v195
	v_mul_f32_e32 v168, v168, v195
	v_mul_f32_e32 v169, v169, v195
	v_mul_f32_e32 v166, v166, v20
	v_mul_f32_e32 v167, v167, v21
	v_mul_f32_e32 v168, v168, v22
	v_mul_f32_e32 v169, v169, v23
	v_lshlrev_b32_e32 v190, 16, v66
	v_and_b32_e32 v191, 0xffff0000, v66
	v_lshlrev_b32_e32 v192, 16, v67
	v_and_b32_e32 v193, 0xffff0000, v67
	v_mul_f32_e32 v190, 0xbfb8aa3b, v190
	v_mul_f32_e32 v191, 0xbfb8aa3b, v191
	v_mul_f32_e32 v192, 0xbfb8aa3b, v192
	v_mul_f32_e32 v193, 0xbfb8aa3b, v193
	v_exp_f32_e32 v190, v190
	v_exp_f32_e32 v191, v191
	v_exp_f32_e32 v192, v192
	v_exp_f32_e32 v193, v193
	v_add_f32_e32 v190, 1.0, v190
	v_add_f32_e32 v191, 1.0, v191
	v_add_f32_e32 v192, 1.0, v192
	v_add_f32_e32 v193, 1.0, v193
	v_rcp_f32_e32 v190, v190
	v_rcp_f32_e32 v191, v191
	v_rcp_f32_e32 v192, v192
	v_rcp_f32_e32 v193, v193
	v_mul_f32_e32 v166, v190, v166
	v_mul_f32_e32 v167, v191, v167
	v_mul_f32_e32 v168, v192, v168
	v_mul_f32_e32 v169, v193, v169
	v_cvt_pk_bf16_f32 v194, v166, v167
	v_cvt_pk_bf16_f32 v195, v168, v169
	global_store_dwordx2 v33, v[194:195], s[38:39]
	v_add_u32_e32 v33, 0x100000, v33
	v_fmamk_f32 v176, v176, 0x3b800000, v214
	v_cmp_gt_f32_e32 vcc, s66, v176
	v_mul_f32_e32 v190, 0x4f800000, v176
	s_nop 0
	v_cndmask_b32_e32 v176, v176, v190, vcc
	v_sqrt_f32_e32 v190, v176
	s_nop 0
	v_add_u32_e32 v191, -1, v190
	v_fma_f32 v192, -v191, v190, v176
	v_cmp_ge_f32_e64 s[40:41], 0, v192
	v_add_u32_e32 v192, 1, v190
	s_nop 0
	v_cndmask_b32_e64 v191, v190, v191, s[40:41]
	v_fma_f32 v190, -v192, v190, v176
	v_cmp_lt_f32_e64 s[40:41], 0, v190
	s_nop 1
	v_cndmask_b32_e64 v190, v191, v192, s[40:41]
	v_mul_f32_e32 v191, 0x37800000, v190
	v_cndmask_b32_e32 v190, v190, v191, vcc
	v_cmp_class_f32_e32 vcc, v176, v215
	s_nop 1
	v_cndmask_b32_e32 v176, v190, v176, vcc
	v_div_scale_f32 v196, s[52:53], v176, v176, 1.0
	v_rcp_f32_e32 v197, v196
	s_nop 0
	v_fma_f32 v198, -v196, v197, 1.0
	v_fmac_f32_e32 v197, v198, v197
	v_div_scale_f32 v198, vcc, 1.0, v176, 1.0
	v_mul_f32_e32 v199, v198, v197
	v_fma_f32 v195, -v196, v199, v198
	v_fmac_f32_e32 v199, v195, v197
	v_fma_f32 v196, -v196, v199, v198
	v_div_fmas_f32 v196, v196, v197, v199
	v_div_fixup_f32 v195, v196, v176, 1.0
	v_mul_f32_e32 v172, v172, v195
	v_mul_f32_e32 v173, v173, v195
	v_mul_f32_e32 v174, v174, v195
	v_mul_f32_e32 v175, v175, v195
	v_mul_f32_e32 v172, v172, v20
	v_mul_f32_e32 v173, v173, v21
	v_mul_f32_e32 v174, v174, v22
	v_mul_f32_e32 v175, v175, v23
	v_lshlrev_b32_e32 v190, 16, v80
	v_and_b32_e32 v191, 0xffff0000, v80
	v_lshlrev_b32_e32 v192, 16, v81
	v_and_b32_e32 v193, 0xffff0000, v81
	v_mul_f32_e32 v190, 0xbfb8aa3b, v190
	v_mul_f32_e32 v191, 0xbfb8aa3b, v191
	v_mul_f32_e32 v192, 0xbfb8aa3b, v192
	v_mul_f32_e32 v193, 0xbfb8aa3b, v193
	v_exp_f32_e32 v190, v190
	v_exp_f32_e32 v191, v191
	v_exp_f32_e32 v192, v192
	v_exp_f32_e32 v193, v193
	v_add_f32_e32 v190, 1.0, v190
	v_add_f32_e32 v191, 1.0, v191
	v_add_f32_e32 v192, 1.0, v192
	v_add_f32_e32 v193, 1.0, v193
	v_rcp_f32_e32 v190, v190
	v_rcp_f32_e32 v191, v191
	v_rcp_f32_e32 v192, v192
	v_rcp_f32_e32 v193, v193
	v_mul_f32_e32 v172, v190, v172
	v_mul_f32_e32 v173, v191, v173
	v_mul_f32_e32 v174, v192, v174
	v_mul_f32_e32 v175, v193, v175
	v_cvt_pk_bf16_f32 v194, v172, v173
	v_cvt_pk_bf16_f32 v195, v174, v175
	global_store_dwordx2 v33, v[194:195], s[38:39]
	v_add_u32_e32 v33, 0x100000, v33
	v_fmamk_f32 v182, v182, 0x3b800000, v214
	v_cmp_gt_f32_e32 vcc, s66, v182
	v_mul_f32_e32 v190, 0x4f800000, v182
	s_nop 0
	v_cndmask_b32_e32 v182, v182, v190, vcc
	v_sqrt_f32_e32 v190, v182
	s_nop 0
	v_add_u32_e32 v191, -1, v190
	v_fma_f32 v192, -v191, v190, v182
	v_cmp_ge_f32_e64 s[40:41], 0, v192
	v_add_u32_e32 v192, 1, v190
	s_nop 0
	v_cndmask_b32_e64 v191, v190, v191, s[40:41]
	v_fma_f32 v190, -v192, v190, v182
	v_cmp_lt_f32_e64 s[40:41], 0, v190
	s_nop 1
	v_cndmask_b32_e64 v190, v191, v192, s[40:41]
	v_mul_f32_e32 v191, 0x37800000, v190
; __device__ __forceinline__ unsigned pk2(float lo, float hi) { f32x2_t v = {lo, hi}; bf16x2_t b = __builtin_convertvector(v, bf16x2_t); return __builtin_bit_cast(unsigned, b); }
; __device__ __forceinline__ float sigmoidf_(float x) { return __builtin_amdgcn_rcpf(1.0f + __expf(-x)); }
; __global__ void __launch_bounds__(NTHREADS, 2) fwd_megakernel(Params P) {
;     ...
;             for (int q = 0; q < 2; ++q) {
;                 const int it = it0 + q * step; ok[q] = it < T * 4; const int itc = ok[q] ? it : it0;
;                 const int row = itc >> 2, h = itc & 3; const size_t o = (size_t)row * 1024 + h * 256 + 4 * lane;
;                 v[q] = (f32x4){0.f, 0.f, 0.f, 0.f}; den[q] = 0.f;
; #pragma unroll
;                 for (int dq = 0; dq < 4; ++dq) { const u32x2 p = *(const u32x2*)(q_mp + (size_t)dq * T * 1024 + o);
;                     v[q][0] += bflo(p.x); v[q][1] += bfhi(p.x); v[q][2] += bflo(p.y); v[q][3] += bfhi(p.y); den[q] += q_dp[(size_t)dq * T * 4 + (size_t)row * 4 + h]; }
;                 mo[q] = *(const u32x2*)(q_proj + (size_t)row * NP + C_MO + h * 256 + 4 * lane);
;     ...
;                 const float rsn = 1.0f / sqrtf(ss * (1.0f / 256.0f) + NORM_EPS);
;                 const f32x4 wn = *(const f32x4*)(q_mnw + l * 1024 + h * 256 + 4 * lane);
;                 u32x2 ow;
;                 ow.x = pk2(x[0] * rsn * wn[0] * sigmoidf_(bflo(mo[q].x)), x[1] * rsn * wn[1] * sigmoidf_(bfhi(mo[q].x)));
;                 ow.y = pk2(x[2] * rsn * wn[2] * sigmoidf_(bflo(mo[q].y)), x[3] * rsn * wn[3] * sigmoidf_(bfhi(mo[q].y)));
;                 if (ok[q]) *(u32x2*)(q_hcat + (size_t)row * 1024 + h * 256 + 4 * lane) = ow;
	v_cndmask_b32_e32 v190, v190, v191, vcc
	v_cmp_class_f32_e32 vcc, v182, v215
	s_nop 1
	v_cndmask_b32_e32 v182, v190, v182, vcc
	v_div_scale_f32 v196, s[52:53], v182, v182, 1.0
	v_rcp_f32_e32 v197, v196
	s_nop 0
	v_fma_f32 v198, -v196, v197, 1.0
	v_fmac_f32_e32 v197, v198, v197
	v_div_scale_f32 v198, vcc, 1.0, v182, 1.0
	v_mul_f32_e32 v199, v198, v197
	v_fma_f32 v195, -v196, v199, v198
	v_fmac_f32_e32 v199, v195, v197
	v_fma_f32 v196, -v196, v199, v198
	v_div_fmas_f32 v196, v196, v197, v199
	v_div_fixup_f32 v195, v196, v182, 1.0
	v_mul_f32_e32 v178, v178, v195
	v_mul_f32_e32 v179, v179, v195
	v_mul_f32_e32 v180, v180, v195
	v_mul_f32_e32 v181, v181, v195
	v_mul_f32_e32 v178, v178, v20
	v_mul_f32_e32 v179, v179, v21
	v_mul_f32_e32 v180, v180, v22
	v_mul_f32_e32 v181, v181, v23
	v_lshlrev_b32_e32 v190, 16, v94
	v_and_b32_e32 v191, 0xffff0000, v94
	v_lshlrev_b32_e32 v192, 16, v95
	v_and_b32_e32 v193, 0xffff0000, v95
	v_mul_f32_e32 v190, 0xbfb8aa3b, v190
	v_mul_f32_e32 v191, 0xbfb8aa3b, v191
	v_mul_f32_e32 v192, 0xbfb8aa3b, v192
	v_mul_f32_e32 v193, 0xbfb8aa3b, v193
	v_exp_f32_e32 v190, v190
	v_exp_f32_e32 v191, v191
	v_exp_f32_e32 v192, v192
	v_exp_f32_e32 v193, v193
	v_add_f32_e32 v190, 1.0, v190
	v_add_f32_e32 v191, 1.0, v191
	v_add_f32_e32 v192, 1.0, v192
	v_add_f32_e32 v193, 1.0, v193
	v_rcp_f32_e32 v190, v190
	v_rcp_f32_e32 v191, v191
	v_rcp_f32_e32 v192, v192
	v_rcp_f32_e32 v193, v193
	v_mul_f32_e32 v178, v190, v178
	v_mul_f32_e32 v179, v191, v179
	v_mul_f32_e32 v180, v192, v180
	v_mul_f32_e32 v181, v193, v181
	v_cvt_pk_bf16_f32 v194, v178, v179
	v_cvt_pk_bf16_f32 v195, v180, v181
	global_store_dwordx2 v33, v[194:195], s[38:39]
	v_add_u32_e32 v33, 0x100000, v33
	v_fmamk_f32 v188, v188, 0x3b800000, v214
	v_cmp_gt_f32_e32 vcc, s66, v188
	v_mul_f32_e32 v190, 0x4f800000, v188
	s_nop 0
	v_cndmask_b32_e32 v188, v188, v190, vcc
	v_sqrt_f32_e32 v190, v188
	s_nop 0
	v_add_u32_e32 v191, -1, v190
	v_fma_f32 v192, -v191, v190, v188
	v_cmp_ge_f32_e64 s[40:41], 0, v192
	v_add_u32_e32 v192, 1, v190
	s_nop 0
	v_cndmask_b32_e64 v191, v190, v191, s[40:41]
	v_fma_f32 v190, -v192, v190, v188
	v_cmp_lt_f32_e64 s[40:41], 0, v190
	s_nop 1
	v_cndmask_b32_e64 v190, v191, v192, s[40:41]
	v_mul_f32_e32 v191, 0x37800000, v190
	v_cndmask_b32_e32 v190, v190, v191, vcc
	v_cmp_class_f32_e32 vcc, v188, v215
	s_nop 1
	v_cndmask_b32_e32 v188, v190, v188, vcc
	v_div_scale_f32 v196, s[52:53], v188, v188, 1.0
	v_rcp_f32_e32 v197, v196
	s_nop 0
	v_fma_f32 v198, -v196, v197, 1.0
	v_fmac_f32_e32 v197, v198, v197
	v_div_scale_f32 v198, vcc, 1.0, v188, 1.0
	v_mul_f32_e32 v199, v198, v197
	v_fma_f32 v195, -v196, v199, v198
	v_fmac_f32_e32 v199, v195, v197
	v_fma_f32 v196, -v196, v199, v198
	v_div_fmas_f32 v196, v196, v197, v199
	v_div_fixup_f32 v195, v196, v188, 1.0
	v_mul_f32_e32 v184, v184, v195
	v_mul_f32_e32 v185, v185, v195
	v_mul_f32_e32 v186, v186, v195
	v_mul_f32_e32 v187, v187, v195
	v_mul_f32_e32 v184, v184, v20
	v_mul_f32_e32 v185, v185, v21
	v_mul_f32_e32 v186, v186, v22
	v_mul_f32_e32 v187, v187, v23
	v_lshlrev_b32_e32 v190, 16, v108
	v_and_b32_e32 v191, 0xffff0000, v108
	v_lshlrev_b32_e32 v192, 16, v109
	v_and_b32_e32 v193, 0xffff0000, v109
	v_mul_f32_e32 v190, 0xbfb8aa3b, v190
	v_mul_f32_e32 v191, 0xbfb8aa3b, v191
	v_mul_f32_e32 v192, 0xbfb8aa3b, v192
	v_mul_f32_e32 v193, 0xbfb8aa3b, v193
	v_exp_f32_e32 v190, v190
	v_exp_f32_e32 v191, v191
	v_exp_f32_e32 v192, v192
	v_exp_f32_e32 v193, v193
	v_add_f32_e32 v190, 1.0, v190
	v_add_f32_e32 v191, 1.0, v191
	v_add_f32_e32 v192, 1.0, v192
	v_add_f32_e32 v193, 1.0, v193
	v_rcp_f32_e32 v190, v190
	v_rcp_f32_e32 v191, v191
	v_rcp_f32_e32 v192, v192
	v_rcp_f32_e32 v193, v193
	v_mul_f32_e32 v184, v190, v184
	v_mul_f32_e32 v185, v191, v185
	v_mul_f32_e32 v186, v192, v186
	v_mul_f32_e32 v187, v193, v187
	v_cvt_pk_bf16_f32 v194, v184, v185
	v_cvt_pk_bf16_f32 v195, v186, v187
	global_store_dwordx2 v33, v[194:195], s[38:39]
	v_add_u32_e32 v33, 0x100000, v33
	global_load_dwordx2 v[54:55], v15, s[48:49]
	global_load_dwordx2 v[56:57], v15, s[4:5]
	global_load_dwordx2 v[58:59], v15, s[6:7]
	global_load_dwordx2 v[60:61], v15, s[8:9]
	v_add_u32_e32 v24, 0x20000, v16
	v_add_u32_e32 v25, 0x40000, v16
	v_add_u32_e32 v26, 0x60000, v16
	global_load_dword v62, v16, s[50:51]
	global_load_dword v63, v24, s[50:51]
	global_load_dword v64, v25, s[50:51]
	global_load_dword v65, v26, s[50:51]
	global_load_dwordx2 v[66:67], v17, s[34:35]
	v_add_u32_e32 v15, 0x100000, v15
	v_add_u32_e32 v16, 0x2000, v16
	v_add_u32_e32 v17, 0x1100000, v17
	global_load_dwordx2 v[68:69], v15, s[48:49]
	global_load_dwordx2 v[70:71], v15, s[4:5]
	global_load_dwordx2 v[72:73], v15, s[6:7]
	global_load_dwordx2 v[74:75], v15, s[8:9]
	v_add_u32_e32 v24, 0x20000, v16
	v_add_u32_e32 v25, 0x40000, v16
	v_add_u32_e32 v26, 0x60000, v16
	global_load_dword v76, v16, s[50:51]
	global_load_dword v77, v24, s[50:51]
	global_load_dword v78, v25, s[50:51]
	global_load_dword v79, v26, s[50:51]
	global_load_dwordx2 v[80:81], v17, s[34:35]
	v_add_u32_e32 v15, 0x100000, v15
	v_add_u32_e32 v16, 0x2000, v16
	v_add_u32_e32 v17, 0x1100000, v17
	global_load_dwordx2 v[82:83], v15, s[48:49]
	global_load_dwordx2 v[84:85], v15, s[4:5]
	global_load_dwordx2 v[86:87], v15, s[6:7]
	global_load_dwordx2 v[88:89], v15, s[8:9]
	v_add_u32_e32 v24, 0x20000, v16
	v_add_u32_e32 v25, 0x40000, v16
	v_add_u32_e32 v26, 0x60000, v16
	global_load_dword v90, v16, s[50:51]
	global_load_dword v91, v24, s[50:51]
	global_load_dword v92, v25, s[50:51]
	global_load_dword v93, v26, s[50:51]
	global_load_dwordx2 v[94:95], v17, s[34:35]
	v_add_u32_e32 v15, 0x100000, v15
	v_add_u32_e32 v16, 0x2000, v16
	v_add_u32_e32 v17, 0x1100000, v17
	global_load_dwordx2 v[96:97], v15, s[48:49]
	global_load_dwordx2 v[98:99], v15, s[4:5]
	global_load_dwordx2 v[100:101], v15, s[6:7]
	global_load_dwordx2 v[102:103], v15, s[8:9]
	v_add_u32_e32 v24, 0x20000, v16
	v_add_u32_e32 v25, 0x40000, v16
	v_add_u32_e32 v26, 0x60000, v16
	global_load_dword v104, v16, s[50:51]
	global_load_dword v105, v24, s[50:51]
	global_load_dword v106, v25, s[50:51]
	global_load_dword v107, v26, s[50:51]
	global_load_dwordx2 v[108:109], v17, s[34:35]
	v_add_u32_e32 v15, 0x100000, v15
	v_add_u32_e32 v16, 0x2000, v16
	v_add_u32_e32 v17, 0x1100000, v17
	s_waitcnt vmcnt(40)
; __global__ void __launch_bounds__(NTHREADS, 2) fwd_megakernel(Params P) {
;     ...
;             for (int q = 0; q < 2; ++q) {
;                 const int it = it0 + q * step; ok[q] = it < T * 4; const int itc = ok[q] ? it : it0;
;                 const int row = itc >> 2, h = itc & 3; const size_t o = (size_t)row * 1024 + h * 256 + 4 * lane;
;                 v[q] = (f32x4){0.f, 0.f, 0.f, 0.f}; den[q] = 0.f;
; #pragma unroll
;                 for (int dq = 0; dq < 4; ++dq) { const u32x2 p = *(const u32x2*)(q_mp + (size_t)dq * T * 1024 + o);
;                     v[q][0] += bflo(p.x); v[q][1] += bfhi(p.x); v[q][2] += bflo(p.y); v[q][3] += bfhi(p.y); den[q] += q_dp[(size_t)dq * T * 4 + (size_t)row * 4 + h]; }
;                 mo[q] = *(const u32x2*)(q_proj + (size_t)row * NP + C_MO + h * 256 + 4 * lane);
;             }
; #pragma unroll
;             for (int q = 0; q < 2; ++q) {
;                 const int it = it0 + q * step; const int itc = ok[q] ? it : it0; const int row = itc >> 2, h = itc & 3;
;                 const f32x4 x = v[q] * (1.0f / fmaxf(fabsf(den[q]), 1.0f));
;                 const float ss = wave_sum((x[0] * x[0] + x[1] * x[1]) + (x[2] * x[2] + x[3] * x[3]));
	v_lshlrev_b32_e32 v166, 16, v110
	v_and_b32_e32 v167, 0xffff0000, v110
	v_lshlrev_b32_e32 v168, 16, v111
	v_and_b32_e32 v169, 0xffff0000, v111
	v_lshlrev_b32_e32 v190, 16, v112
	v_and_b32_e32 v191, 0xffff0000, v112
	v_lshlrev_b32_e32 v192, 16, v113
	v_and_b32_e32 v193, 0xffff0000, v113
	v_pk_add_f32 v[166:167], v[166:167], v[190:191]
	v_pk_add_f32 v[168:169], v[168:169], v[192:193]
	v_lshlrev_b32_e32 v190, 16, v114
	v_and_b32_e32 v191, 0xffff0000, v114
	v_lshlrev_b32_e32 v192, 16, v115
	v_and_b32_e32 v193, 0xffff0000, v115
	v_pk_add_f32 v[166:167], v[166:167], v[190:191]
	v_pk_add_f32 v[168:169], v[168:169], v[192:193]
	v_lshlrev_b32_e32 v190, 16, v116
	v_and_b32_e32 v191, 0xffff0000, v116
	v_lshlrev_b32_e32 v192, 16, v117
	v_and_b32_e32 v193, 0xffff0000, v117
	v_pk_add_f32 v[166:167], v[166:167], v[190:191]
	v_pk_add_f32 v[168:169], v[168:169], v[192:193]
	v_add_f32_e32 v194, 0, v118
	v_add_f32_e32 v194, v194, v119
	v_add_f32_e32 v194, v194, v120
	v_add_f32_e32 v194, v194, v121
	v_max_f32_e64 v194, |v194|, 1.0
	v_div_scale_f32 v196, s[52:53], v194, v194, 1.0
	v_rcp_f32_e32 v197, v196
	s_nop 0
	v_fma_f32 v198, -v196, v197, 1.0
	v_fmac_f32_e32 v197, v198, v197
	v_div_scale_f32 v198, vcc, 1.0, v194, 1.0
	v_mul_f32_e32 v199, v198, v197
	v_fma_f32 v195, -v196, v199, v198
	v_fmac_f32_e32 v199, v195, v197
	v_fma_f32 v196, -v196, v199, v198
	v_div_fmas_f32 v196, v196, v197, v199
	v_div_fixup_f32 v195, v196, v194, 1.0
	v_mul_f32_e32 v166, v166, v195
	v_mul_f32_e32 v167, v167, v195
	v_mul_f32_e32 v168, v168, v195
	v_mul_f32_e32 v169, v169, v195
	v_mul_f32_e32 v190, v166, v166
	v_mul_f32_e32 v191, v167, v167
	v_mul_f32_e32 v192, v168, v168
	v_mul_f32_e32 v193, v169, v169
	v_add_f32_e32 v190, v191, v190
	v_add_f32_e32 v192, v192, v193
	v_add_f32_e32 v170, v190, v192
	v_lshlrev_b32_e32 v172, 16, v124
	v_and_b32_e32 v173, 0xffff0000, v124
	v_lshlrev_b32_e32 v174, 16, v125
	v_and_b32_e32 v175, 0xffff0000, v125
	v_lshlrev_b32_e32 v190, 16, v126
	v_and_b32_e32 v191, 0xffff0000, v126
	v_lshlrev_b32_e32 v192, 16, v127
	v_and_b32_e32 v193, 0xffff0000, v127
	v_pk_add_f32 v[172:173], v[172:173], v[190:191]
	v_pk_add_f32 v[174:175], v[174:175], v[192:193]
	v_lshlrev_b32_e32 v190, 16, v128
	v_and_b32_e32 v191, 0xffff0000, v128
	v_lshlrev_b32_e32 v192, 16, v129
	v_and_b32_e32 v193, 0xffff0000, v129
	v_pk_add_f32 v[172:173], v[172:173], v[190:191]
	v_pk_add_f32 v[174:175], v[174:175], v[192:193]
	v_lshlrev_b32_e32 v190, 16, v130
	v_and_b32_e32 v191, 0xffff0000, v130
	v_lshlrev_b32_e32 v192, 16, v131
	v_and_b32_e32 v193, 0xffff0000, v131
	v_pk_add_f32 v[172:173], v[172:173], v[190:191]
	v_pk_add_f32 v[174:175], v[174:175], v[192:193]
	v_add_f32_e32 v194, 0, v132
	v_add_f32_e32 v194, v194, v133
	v_add_f32_e32 v194, v194, v134
	v_add_f32_e32 v194, v194, v135
	v_max_f32_e64 v194, |v194|, 1.0
	v_div_scale_f32 v196, s[52:53], v194, v194, 1.0
	v_rcp_f32_e32 v197, v196
	s_nop 0
	v_fma_f32 v198, -v196, v197, 1.0
	v_fmac_f32_e32 v197, v198, v197
	v_div_scale_f32 v198, vcc, 1.0, v194, 1.0
	v_mul_f32_e32 v199, v198, v197
	v_fma_f32 v195, -v196, v199, v198
	v_fmac_f32_e32 v199, v195, v197
	v_fma_f32 v196, -v196, v199, v198
	v_div_fmas_f32 v196, v196, v197, v199
	v_div_fixup_f32 v195, v196, v194, 1.0
	v_mul_f32_e32 v172, v172, v195
	v_mul_f32_e32 v173, v173, v195
	v_mul_f32_e32 v174, v174, v195
	v_mul_f32_e32 v175, v175, v195
	v_mul_f32_e32 v191, v175, v175
	v_mul_f32_e32 v190, v173, v173
	v_fmac_f32_e32 v190, v172, v172
	v_fmac_f32_e32 v191, v174, v174
	v_add_f32_e32 v176, v190, v191
	v_lshlrev_b32_e32 v178, 16, v138
	v_and_b32_e32 v179, 0xffff0000, v138
	v_lshlrev_b32_e32 v180, 16, v139
	v_and_b32_e32 v181, 0xffff0000, v139
	v_lshlrev_b32_e32 v190, 16, v140
	v_and_b32_e32 v191, 0xffff0000, v140
	v_lshlrev_b32_e32 v192, 16, v141
	v_and_b32_e32 v193, 0xffff0000, v141
	v_pk_add_f32 v[178:179], v[178:179], v[190:191]
	v_pk_add_f32 v[180:181], v[180:181], v[192:193]
	v_lshlrev_b32_e32 v190, 16, v142
	v_and_b32_e32 v191, 0xffff0000, v142
	v_lshlrev_b32_e32 v192, 16, v143
	v_and_b32_e32 v193, 0xffff0000, v143
	v_pk_add_f32 v[178:179], v[178:179], v[190:191]
	v_pk_add_f32 v[180:181], v[180:181], v[192:193]
	v_lshlrev_b32_e32 v190, 16, v144
	v_and_b32_e32 v191, 0xffff0000, v144
	v_lshlrev_b32_e32 v192, 16, v145
	v_and_b32_e32 v193, 0xffff0000, v145
	v_pk_add_f32 v[178:179], v[178:179], v[190:191]
	v_pk_add_f32 v[180:181], v[180:181], v[192:193]
	v_add_f32_e32 v194, 0, v146
	v_add_f32_e32 v194, v194, v147
	v_add_f32_e32 v194, v194, v148
	v_add_f32_e32 v194, v194, v149
	v_max_f32_e64 v194, |v194|, 1.0
	v_div_scale_f32 v196, s[52:53], v194, v194, 1.0
	v_rcp_f32_e32 v197, v196
	s_nop 0
	v_fma_f32 v198, -v196, v197, 1.0
	v_fmac_f32_e32 v197, v198, v197
	v_div_scale_f32 v198, vcc, 1.0, v194, 1.0
	v_mul_f32_e32 v199, v198, v197
	v_fma_f32 v195, -v196, v199, v198
	v_fmac_f32_e32 v199, v195, v197
	v_fma_f32 v196, -v196, v199, v198
	v_div_fmas_f32 v196, v196, v197, v199
	v_div_fixup_f32 v195, v196, v194, 1.0
	v_mul_f32_e32 v178, v178, v195
	v_mul_f32_e32 v179, v179, v195
	v_mul_f32_e32 v180, v180, v195
	v_mul_f32_e32 v181, v181, v195
	v_mul_f32_e32 v190, v178, v178
	v_mul_f32_e32 v191, v179, v179
	v_mul_f32_e32 v192, v180, v180
	v_mul_f32_e32 v193, v181, v181
	v_add_f32_e32 v190, v191, v190
	v_add_f32_e32 v192, v192, v193
	v_add_f32_e32 v182, v190, v192
	v_lshlrev_b32_e32 v184, 16, v152
	v_and_b32_e32 v185, 0xffff0000, v152
	v_lshlrev_b32_e32 v186, 16, v153
	v_and_b32_e32 v187, 0xffff0000, v153
	v_lshlrev_b32_e32 v190, 16, v154
	v_and_b32_e32 v191, 0xffff0000, v154
	v_lshlrev_b32_e32 v192, 16, v155
	v_and_b32_e32 v193, 0xffff0000, v155
	v_pk_add_f32 v[184:185], v[184:185], v[190:191]
; __device__ __forceinline__ unsigned pk2(float lo, float hi) { f32x2_t v = {lo, hi}; bf16x2_t b = __builtin_convertvector(v, bf16x2_t); return __builtin_bit_cast(unsigned, b); }
; __device__ __forceinline__ float sigmoidf_(float x) { return __builtin_amdgcn_rcpf(1.0f + __expf(-x)); }
; __global__ void __launch_bounds__(NTHREADS, 2) fwd_megakernel(Params P) {
;     ...
;                 const f32x4 x = v[q] * (1.0f / fmaxf(fabsf(den[q]), 1.0f));
;                 const float ss = wave_sum((x[0] * x[0] + x[1] * x[1]) + (x[2] * x[2] + x[3] * x[3]));
;                 const float rsn = 1.0f / sqrtf(ss * (1.0f / 256.0f) + NORM_EPS);
;                 const f32x4 wn = *(const f32x4*)(q_mnw + l * 1024 + h * 256 + 4 * lane);
;                 u32x2 ow;
;                 ow.x = pk2(x[0] * rsn * wn[0] * sigmoidf_(bflo(mo[q].x)), x[1] * rsn * wn[1] * sigmoidf_(bfhi(mo[q].x)));
;                 ow.y = pk2(x[2] * rsn * wn[2] * sigmoidf_(bflo(mo[q].y)), x[3] * rsn * wn[3] * sigmoidf_(bfhi(mo[q].y)));
	v_pk_add_f32 v[186:187], v[186:187], v[192:193]
	v_lshlrev_b32_e32 v190, 16, v156
	v_and_b32_e32 v191, 0xffff0000, v156
	v_lshlrev_b32_e32 v192, 16, v157
	v_and_b32_e32 v193, 0xffff0000, v157
	v_pk_add_f32 v[184:185], v[184:185], v[190:191]
	v_pk_add_f32 v[186:187], v[186:187], v[192:193]
	v_lshlrev_b32_e32 v190, 16, v158
	v_and_b32_e32 v191, 0xffff0000, v158
	v_lshlrev_b32_e32 v192, 16, v159
	v_and_b32_e32 v193, 0xffff0000, v159
	v_pk_add_f32 v[184:185], v[184:185], v[190:191]
	v_pk_add_f32 v[186:187], v[186:187], v[192:193]
	v_add_f32_e32 v194, 0, v160
	v_add_f32_e32 v194, v194, v161
	v_add_f32_e32 v194, v194, v162
	v_add_f32_e32 v194, v194, v163
	v_max_f32_e64 v194, |v194|, 1.0
	v_div_scale_f32 v196, s[52:53], v194, v194, 1.0
	v_rcp_f32_e32 v197, v196
	s_nop 0
	v_fma_f32 v198, -v196, v197, 1.0
	v_fmac_f32_e32 v197, v198, v197
	v_div_scale_f32 v198, vcc, 1.0, v194, 1.0
	v_mul_f32_e32 v199, v198, v197
	v_fma_f32 v195, -v196, v199, v198
	v_fmac_f32_e32 v199, v195, v197
	v_fma_f32 v196, -v196, v199, v198
	v_div_fmas_f32 v196, v196, v197, v199
	v_div_fixup_f32 v195, v196, v194, 1.0
	v_mul_f32_e32 v184, v184, v195
	v_mul_f32_e32 v185, v185, v195
	v_mul_f32_e32 v186, v186, v195
	v_mul_f32_e32 v187, v187, v195
	v_mul_f32_e32 v191, v187, v187
	v_mul_f32_e32 v190, v185, v185
	v_fmac_f32_e32 v190, v184, v184
	v_fmac_f32_e32 v191, v186, v186
	v_add_f32_e32 v188, v190, v191
	s_nop 1
	v_mov_b32_dpp v171, v170 quad_perm:[1,0,3,2] row_mask:0xf bank_mask:0xf
	v_mov_b32_dpp v177, v176 quad_perm:[1,0,3,2] row_mask:0xf bank_mask:0xf
	v_mov_b32_dpp v183, v182 quad_perm:[1,0,3,2] row_mask:0xf bank_mask:0xf
	v_mov_b32_dpp v189, v188 quad_perm:[1,0,3,2] row_mask:0xf bank_mask:0xf
	v_add_f32_e32 v170, v170, v171
	v_add_f32_e32 v176, v176, v177
	v_add_f32_e32 v182, v182, v183
	v_add_f32_e32 v188, v188, v189
	s_nop 1
	v_mov_b32_dpp v171, v170 quad_perm:[2,3,0,1] row_mask:0xf bank_mask:0xf
	v_mov_b32_dpp v177, v176 quad_perm:[2,3,0,1] row_mask:0xf bank_mask:0xf
	v_mov_b32_dpp v183, v182 quad_perm:[2,3,0,1] row_mask:0xf bank_mask:0xf
	v_mov_b32_dpp v189, v188 quad_perm:[2,3,0,1] row_mask:0xf bank_mask:0xf
	v_add_f32_e32 v170, v170, v171
	v_add_f32_e32 v176, v176, v177
	v_add_f32_e32 v182, v182, v183
	v_add_f32_e32 v188, v188, v189
	s_nop 1
	v_mov_b32_dpp v171, v170 row_half_mirror row_mask:0xf bank_mask:0xf
	v_mov_b32_dpp v177, v176 row_half_mirror row_mask:0xf bank_mask:0xf
	v_mov_b32_dpp v183, v182 row_half_mirror row_mask:0xf bank_mask:0xf
	v_mov_b32_dpp v189, v188 row_half_mirror row_mask:0xf bank_mask:0xf
	v_add_f32_e32 v170, v170, v171
	v_add_f32_e32 v176, v176, v177
	v_add_f32_e32 v182, v182, v183
	v_add_f32_e32 v188, v188, v189
	s_nop 1
	v_mov_b32_dpp v171, v170 row_mirror row_mask:0xf bank_mask:0xf
	v_mov_b32_dpp v177, v176 row_mirror row_mask:0xf bank_mask:0xf
	v_mov_b32_dpp v183, v182 row_mirror row_mask:0xf bank_mask:0xf
	v_mov_b32_dpp v189, v188 row_mirror row_mask:0xf bank_mask:0xf
	v_add_f32_e32 v170, v170, v171
	v_add_f32_e32 v176, v176, v177
	v_add_f32_e32 v182, v182, v183
	v_add_f32_e32 v188, v188, v189
	v_mov_b32_e32 v171, v170
	v_mov_b32_e32 v177, v176
	v_mov_b32_e32 v183, v182
	v_mov_b32_e32 v189, v188
	s_nop 1
	v_permlane16_swap_b32 v171, v170
	v_permlane16_swap_b32 v177, v176
	v_permlane16_swap_b32 v183, v182
	v_permlane16_swap_b32 v189, v188
	v_add_f32_e32 v170, v170, v171
	v_add_f32_e32 v176, v176, v177
	v_add_f32_e32 v182, v182, v183
	v_add_f32_e32 v188, v188, v189
	v_mov_b32_e32 v171, v170
	v_mov_b32_e32 v177, v176
	v_mov_b32_e32 v183, v182
	v_mov_b32_e32 v189, v188
	s_nop 1
	v_permlane32_swap_b32 v171, v170
	v_permlane32_swap_b32 v177, v176
	v_permlane32_swap_b32 v183, v182
	v_permlane32_swap_b32 v189, v188
	v_add_f32_e32 v170, v170, v171
	v_add_f32_e32 v176, v176, v177
	v_add_f32_e32 v182, v182, v183
	v_add_f32_e32 v188, v188, v189
	v_fmamk_f32 v170, v170, 0x3b800000, v214
	v_cmp_gt_f32_e32 vcc, s66, v170
	v_mul_f32_e32 v190, 0x4f800000, v170
	s_nop 0
	v_cndmask_b32_e32 v170, v170, v190, vcc
	v_sqrt_f32_e32 v190, v170
	s_nop 0
	v_add_u32_e32 v191, -1, v190
	v_fma_f32 v192, -v191, v190, v170
	v_cmp_ge_f32_e64 s[40:41], 0, v192
	v_add_u32_e32 v192, 1, v190
	s_nop 0
	v_cndmask_b32_e64 v191, v190, v191, s[40:41]
	v_fma_f32 v190, -v192, v190, v170
	v_cmp_lt_f32_e64 s[40:41], 0, v190
	s_nop 1
	v_cndmask_b32_e64 v190, v191, v192, s[40:41]
	v_mul_f32_e32 v191, 0x37800000, v190
	v_cndmask_b32_e32 v190, v190, v191, vcc
	v_cmp_class_f32_e32 vcc, v170, v215
	s_nop 1
	v_cndmask_b32_e32 v170, v190, v170, vcc
	v_div_scale_f32 v196, s[52:53], v170, v170, 1.0
	v_rcp_f32_e32 v197, v196
	s_nop 0
	v_fma_f32 v198, -v196, v197, 1.0
	v_fmac_f32_e32 v197, v198, v197
	v_div_scale_f32 v198, vcc, 1.0, v170, 1.0
	v_mul_f32_e32 v199, v198, v197
	v_fma_f32 v195, -v196, v199, v198
	v_fmac_f32_e32 v199, v195, v197
	v_fma_f32 v196, -v196, v199, v198
	v_div_fmas_f32 v196, v196, v197, v199
	v_div_fixup_f32 v195, v196, v170, 1.0
	v_mul_f32_e32 v166, v166, v195
	v_mul_f32_e32 v167, v167, v195
	v_mul_f32_e32 v168, v168, v195
	v_mul_f32_e32 v169, v169, v195
	v_mul_f32_e32 v166, v166, v20
	v_mul_f32_e32 v167, v167, v21
	v_mul_f32_e32 v168, v168, v22
	v_mul_f32_e32 v169, v169, v23
	v_lshlrev_b32_e32 v190, 16, v122
	v_and_b32_e32 v191, 0xffff0000, v122
	v_lshlrev_b32_e32 v192, 16, v123
	v_and_b32_e32 v193, 0xffff0000, v123
	v_mul_f32_e32 v190, 0xbfb8aa3b, v190
	v_mul_f32_e32 v191, 0xbfb8aa3b, v191
	v_mul_f32_e32 v192, 0xbfb8aa3b, v192
	v_mul_f32_e32 v193, 0xbfb8aa3b, v193
	v_exp_f32_e32 v190, v190
	v_exp_f32_e32 v191, v191
	v_exp_f32_e32 v192, v192
	v_exp_f32_e32 v193, v193
	v_add_f32_e32 v190, 1.0, v190
	v_add_f32_e32 v191, 1.0, v191
	v_add_f32_e32 v192, 1.0, v192
; __device__ __forceinline__ unsigned pk2(float lo, float hi) { f32x2_t v = {lo, hi}; bf16x2_t b = __builtin_convertvector(v, bf16x2_t); return __builtin_bit_cast(unsigned, b); }
; __device__ __forceinline__ float sigmoidf_(float x) { return __builtin_amdgcn_rcpf(1.0f + __expf(-x)); }
; __global__ void __launch_bounds__(NTHREADS, 2) fwd_megakernel(Params P) {
;     ...
;                 const float rsn = 1.0f / sqrtf(ss * (1.0f / 256.0f) + NORM_EPS);
;                 const f32x4 wn = *(const f32x4*)(q_mnw + l * 1024 + h * 256 + 4 * lane);
;                 u32x2 ow;
;                 ow.x = pk2(x[0] * rsn * wn[0] * sigmoidf_(bflo(mo[q].x)), x[1] * rsn * wn[1] * sigmoidf_(bfhi(mo[q].x)));
;                 ow.y = pk2(x[2] * rsn * wn[2] * sigmoidf_(bflo(mo[q].y)), x[3] * rsn * wn[3] * sigmoidf_(bfhi(mo[q].y)));
;                 if (ok[q]) *(u32x2*)(q_hcat + (size_t)row * 1024 + h * 256 + 4 * lane) = ow;
	v_add_f32_e32 v193, 1.0, v193
	v_rcp_f32_e32 v190, v190
	v_rcp_f32_e32 v191, v191
	v_rcp_f32_e32 v192, v192
	v_rcp_f32_e32 v193, v193
	v_mul_f32_e32 v166, v190, v166
	v_mul_f32_e32 v167, v191, v167
	v_mul_f32_e32 v168, v192, v168
	v_mul_f32_e32 v169, v193, v169
	v_cvt_pk_bf16_f32 v194, v166, v167
	v_cvt_pk_bf16_f32 v195, v168, v169
	global_store_dwordx2 v33, v[194:195], s[38:39]
	v_add_u32_e32 v33, 0x100000, v33
	v_fmamk_f32 v176, v176, 0x3b800000, v214
	v_cmp_gt_f32_e32 vcc, s66, v176
	v_mul_f32_e32 v190, 0x4f800000, v176
	s_nop 0
	v_cndmask_b32_e32 v176, v176, v190, vcc
	v_sqrt_f32_e32 v190, v176
	s_nop 0
	v_add_u32_e32 v191, -1, v190
	v_fma_f32 v192, -v191, v190, v176
	v_cmp_ge_f32_e64 s[40:41], 0, v192
	v_add_u32_e32 v192, 1, v190
	s_nop 0
	v_cndmask_b32_e64 v191, v190, v191, s[40:41]
	v_fma_f32 v190, -v192, v190, v176
	v_cmp_lt_f32_e64 s[40:41], 0, v190
	s_nop 1
	v_cndmask_b32_e64 v190, v191, v192, s[40:41]
	v_mul_f32_e32 v191, 0x37800000, v190
	v_cndmask_b32_e32 v190, v190, v191, vcc
	v_cmp_class_f32_e32 vcc, v176, v215
	s_nop 1
	v_cndmask_b32_e32 v176, v190, v176, vcc
	v_div_scale_f32 v196, s[52:53], v176, v176, 1.0
	v_rcp_f32_e32 v197, v196
	s_nop 0
	v_fma_f32 v198, -v196, v197, 1.0
	v_fmac_f32_e32 v197, v198, v197
	v_div_scale_f32 v198, vcc, 1.0, v176, 1.0
	v_mul_f32_e32 v199, v198, v197
	v_fma_f32 v195, -v196, v199, v198
	v_fmac_f32_e32 v199, v195, v197
	v_fma_f32 v196, -v196, v199, v198
	v_div_fmas_f32 v196, v196, v197, v199
	v_div_fixup_f32 v195, v196, v176, 1.0
	v_mul_f32_e32 v172, v172, v195
	v_mul_f32_e32 v173, v173, v195
	v_mul_f32_e32 v174, v174, v195
	v_mul_f32_e32 v175, v175, v195
	v_mul_f32_e32 v172, v172, v20
	v_mul_f32_e32 v173, v173, v21
	v_mul_f32_e32 v174, v174, v22
	v_mul_f32_e32 v175, v175, v23
	v_lshlrev_b32_e32 v190, 16, v136
	v_and_b32_e32 v191, 0xffff0000, v136
	v_lshlrev_b32_e32 v192, 16, v137
	v_and_b32_e32 v193, 0xffff0000, v137
	v_mul_f32_e32 v190, 0xbfb8aa3b, v190
	v_mul_f32_e32 v191, 0xbfb8aa3b, v191
	v_mul_f32_e32 v192, 0xbfb8aa3b, v192
	v_mul_f32_e32 v193, 0xbfb8aa3b, v193
	v_exp_f32_e32 v190, v190
	v_exp_f32_e32 v191, v191
	v_exp_f32_e32 v192, v192
	v_exp_f32_e32 v193, v193
	v_add_f32_e32 v190, 1.0, v190
	v_add_f32_e32 v191, 1.0, v191
	v_add_f32_e32 v192, 1.0, v192
	v_add_f32_e32 v193, 1.0, v193
	v_rcp_f32_e32 v190, v190
	v_rcp_f32_e32 v191, v191
	v_rcp_f32_e32 v192, v192
	v_rcp_f32_e32 v193, v193
	v_mul_f32_e32 v172, v190, v172
	v_mul_f32_e32 v173, v191, v173
	v_mul_f32_e32 v174, v192, v174
	v_mul_f32_e32 v175, v193, v175
	v_cvt_pk_bf16_f32 v194, v172, v173
	v_cvt_pk_bf16_f32 v195, v174, v175
	global_store_dwordx2 v33, v[194:195], s[38:39]
	v_add_u32_e32 v33, 0x100000, v33
	v_fmamk_f32 v182, v182, 0x3b800000, v214
	v_cmp_gt_f32_e32 vcc, s66, v182
	v_mul_f32_e32 v190, 0x4f800000, v182
	s_nop 0
	v_cndmask_b32_e32 v182, v182, v190, vcc
	v_sqrt_f32_e32 v190, v182
	s_nop 0
	v_add_u32_e32 v191, -1, v190
	v_fma_f32 v192, -v191, v190, v182
	v_cmp_ge_f32_e64 s[40:41], 0, v192
	v_add_u32_e32 v192, 1, v190
	s_nop 0
	v_cndmask_b32_e64 v191, v190, v191, s[40:41]
	v_fma_f32 v190, -v192, v190, v182
	v_cmp_lt_f32_e64 s[40:41], 0, v190
	s_nop 1
	v_cndmask_b32_e64 v190, v191, v192, s[40:41]
	v_mul_f32_e32 v191, 0x37800000, v190
	v_cndmask_b32_e32 v190, v190, v191, vcc
	v_cmp_class_f32_e32 vcc, v182, v215
	s_nop 1
	v_cndmask_b32_e32 v182, v190, v182, vcc
	v_div_scale_f32 v196, s[52:53], v182, v182, 1.0
	v_rcp_f32_e32 v197, v196
	s_nop 0
	v_fma_f32 v198, -v196, v197, 1.0
	v_fmac_f32_e32 v197, v198, v197
	v_div_scale_f32 v198, vcc, 1.0, v182, 1.0
	v_mul_f32_e32 v199, v198, v197
	v_fma_f32 v195, -v196, v199, v198
	v_fmac_f32_e32 v199, v195, v197
	v_fma_f32 v196, -v196, v199, v198
	v_div_fmas_f32 v196, v196, v197, v199
	v_div_fixup_f32 v195, v196, v182, 1.0
	v_mul_f32_e32 v178, v178, v195
	v_mul_f32_e32 v179, v179, v195
	v_mul_f32_e32 v180, v180, v195
	v_mul_f32_e32 v181, v181, v195
	v_mul_f32_e32 v178, v178, v20
	v_mul_f32_e32 v179, v179, v21
	v_mul_f32_e32 v180, v180, v22
	v_mul_f32_e32 v181, v181, v23
	v_lshlrev_b32_e32 v190, 16, v150
	v_and_b32_e32 v191, 0xffff0000, v150
	v_lshlrev_b32_e32 v192, 16, v151
	v_and_b32_e32 v193, 0xffff0000, v151
	v_mul_f32_e32 v190, 0xbfb8aa3b, v190
	v_mul_f32_e32 v191, 0xbfb8aa3b, v191
	v_mul_f32_e32 v192, 0xbfb8aa3b, v192
	v_mul_f32_e32 v193, 0xbfb8aa3b, v193
	v_exp_f32_e32 v190, v190
	v_exp_f32_e32 v191, v191
	v_exp_f32_e32 v192, v192
	v_exp_f32_e32 v193, v193
	v_add_f32_e32 v190, 1.0, v190
	v_add_f32_e32 v191, 1.0, v191
	v_add_f32_e32 v192, 1.0, v192
	v_add_f32_e32 v193, 1.0, v193
	v_rcp_f32_e32 v190, v190
	v_rcp_f32_e32 v191, v191
	v_rcp_f32_e32 v192, v192
	v_rcp_f32_e32 v193, v193
	v_mul_f32_e32 v178, v190, v178
	v_mul_f32_e32 v179, v191, v179
	v_mul_f32_e32 v180, v192, v180
	v_mul_f32_e32 v181, v193, v181
	v_cvt_pk_bf16_f32 v194, v178, v179
	v_cvt_pk_bf16_f32 v195, v180, v181
	global_store_dwordx2 v33, v[194:195], s[38:39]
	v_add_u32_e32 v33, 0x100000, v33
	v_fmamk_f32 v188, v188, 0x3b800000, v214
	v_cmp_gt_f32_e32 vcc, s66, v188
	v_mul_f32_e32 v190, 0x4f800000, v188
	s_nop 0
	v_cndmask_b32_e32 v188, v188, v190, vcc
	v_sqrt_f32_e32 v190, v188
	s_nop 0
	v_add_u32_e32 v191, -1, v190
	v_fma_f32 v192, -v191, v190, v188
	v_cmp_ge_f32_e64 s[40:41], 0, v192
	v_add_u32_e32 v192, 1, v190
	s_nop 0
	v_cndmask_b32_e64 v191, v190, v191, s[40:41]
	v_fma_f32 v190, -v192, v190, v188
	v_cmp_lt_f32_e64 s[40:41], 0, v190
	s_nop 1
	v_cndmask_b32_e64 v190, v191, v192, s[40:41]
	v_mul_f32_e32 v191, 0x37800000, v190
	v_cndmask_b32_e32 v190, v190, v191, vcc
	v_cmp_class_f32_e32 vcc, v188, v215
	s_nop 1
	v_cndmask_b32_e32 v188, v190, v188, vcc
	v_div_scale_f32 v196, s[52:53], v188, v188, 1.0
; __device__ __forceinline__ unsigned pk2(float lo, float hi) { f32x2_t v = {lo, hi}; bf16x2_t b = __builtin_convertvector(v, bf16x2_t); return __builtin_bit_cast(unsigned, b); }
; __device__ __forceinline__ float sigmoidf_(float x) { return __builtin_amdgcn_rcpf(1.0f + __expf(-x)); }
; __global__ void __launch_bounds__(NTHREADS, 2) fwd_megakernel(Params P) {
;     ...
;             for (int q = 0; q < 2; ++q) {
;                 const int it = it0 + q * step; ok[q] = it < T * 4; const int itc = ok[q] ? it : it0;
;                 const int row = itc >> 2, h = itc & 3; const size_t o = (size_t)row * 1024 + h * 256 + 4 * lane;
;                 v[q] = (f32x4){0.f, 0.f, 0.f, 0.f}; den[q] = 0.f;
; #pragma unroll
;                 for (int dq = 0; dq < 4; ++dq) { const u32x2 p = *(const u32x2*)(q_mp + (size_t)dq * T * 1024 + o);
;                     v[q][0] += bflo(p.x); v[q][1] += bfhi(p.x); v[q][2] += bflo(p.y); v[q][3] += bfhi(p.y); den[q] += q_dp[(size_t)dq * T * 4 + (size_t)row * 4 + h]; }
;                 mo[q] = *(const u32x2*)(q_proj + (size_t)row * NP + C_MO + h * 256 + 4 * lane);
;             }
; #pragma unroll
;             for (int q = 0; q < 2; ++q) {
;                 const int it = it0 + q * step; const int itc = ok[q] ? it : it0; const int row = itc >> 2, h = itc & 3;
;                 const f32x4 x = v[q] * (1.0f / fmaxf(fabsf(den[q]), 1.0f));
;                 const float ss = wave_sum((x[0] * x[0] + x[1] * x[1]) + (x[2] * x[2] + x[3] * x[3]));
;                 const float rsn = 1.0f / sqrtf(ss * (1.0f / 256.0f) + NORM_EPS);
;                 const f32x4 wn = *(const f32x4*)(q_mnw + l * 1024 + h * 256 + 4 * lane);
;                 u32x2 ow;
;                 ow.x = pk2(x[0] * rsn * wn[0] * sigmoidf_(bflo(mo[q].x)), x[1] * rsn * wn[1] * sigmoidf_(bfhi(mo[q].x)));
;                 ow.y = pk2(x[2] * rsn * wn[2] * sigmoidf_(bflo(mo[q].y)), x[3] * rsn * wn[3] * sigmoidf_(bfhi(mo[q].y)));
;                 if (ok[q]) *(u32x2*)(q_hcat + (size_t)row * 1024 + h * 256 + 4 * lane) = ow;
	v_rcp_f32_e32 v197, v196
	s_nop 0
	v_fma_f32 v198, -v196, v197, 1.0
	v_fmac_f32_e32 v197, v198, v197
	v_div_scale_f32 v198, vcc, 1.0, v188, 1.0
	v_mul_f32_e32 v199, v198, v197
	v_fma_f32 v195, -v196, v199, v198
	v_fmac_f32_e32 v199, v195, v197
	v_fma_f32 v196, -v196, v199, v198
	v_div_fmas_f32 v196, v196, v197, v199
	v_div_fixup_f32 v195, v196, v188, 1.0
	v_mul_f32_e32 v184, v184, v195
	v_mul_f32_e32 v185, v185, v195
	v_mul_f32_e32 v186, v186, v195
	v_mul_f32_e32 v187, v187, v195
	v_mul_f32_e32 v184, v184, v20
	v_mul_f32_e32 v185, v185, v21
	v_mul_f32_e32 v186, v186, v22
	v_mul_f32_e32 v187, v187, v23
	v_lshlrev_b32_e32 v190, 16, v164
	v_and_b32_e32 v191, 0xffff0000, v164
	v_lshlrev_b32_e32 v192, 16, v165
	v_and_b32_e32 v193, 0xffff0000, v165
	v_mul_f32_e32 v190, 0xbfb8aa3b, v190
	v_mul_f32_e32 v191, 0xbfb8aa3b, v191
	v_mul_f32_e32 v192, 0xbfb8aa3b, v192
	v_mul_f32_e32 v193, 0xbfb8aa3b, v193
	v_exp_f32_e32 v190, v190
	v_exp_f32_e32 v191, v191
	v_exp_f32_e32 v192, v192
	v_exp_f32_e32 v193, v193
	v_add_f32_e32 v190, 1.0, v190
	v_add_f32_e32 v191, 1.0, v191
	v_add_f32_e32 v192, 1.0, v192
	v_add_f32_e32 v193, 1.0, v193
	v_rcp_f32_e32 v190, v190
	v_rcp_f32_e32 v191, v191
	v_rcp_f32_e32 v192, v192
	v_rcp_f32_e32 v193, v193
	v_mul_f32_e32 v184, v190, v184
	v_mul_f32_e32 v185, v191, v185
	v_mul_f32_e32 v186, v192, v186
	v_mul_f32_e32 v187, v193, v187
	v_cvt_pk_bf16_f32 v194, v184, v185
	v_cvt_pk_bf16_f32 v195, v186, v187
	global_store_dwordx2 v33, v[194:195], s[38:39]
	v_add_u32_e32 v33, 0x100000, v33
	global_load_dwordx2 v[110:111], v15, s[48:49]
	global_load_dwordx2 v[112:113], v15, s[4:5]
	global_load_dwordx2 v[114:115], v15, s[6:7]
	global_load_dwordx2 v[116:117], v15, s[8:9]
	v_add_u32_e32 v24, 0x20000, v16
	v_add_u32_e32 v25, 0x40000, v16
	v_add_u32_e32 v26, 0x60000, v16
	global_load_dword v118, v16, s[50:51]
	global_load_dword v119, v24, s[50:51]
	global_load_dword v120, v25, s[50:51]
	global_load_dword v121, v26, s[50:51]
	global_load_dwordx2 v[122:123], v17, s[34:35]
	v_add_u32_e32 v15, 0x100000, v15
	v_add_u32_e32 v16, 0x2000, v16
	v_add_u32_e32 v17, 0x1100000, v17
	global_load_dwordx2 v[124:125], v15, s[48:49]
	global_load_dwordx2 v[126:127], v15, s[4:5]
	global_load_dwordx2 v[128:129], v15, s[6:7]
	global_load_dwordx2 v[130:131], v15, s[8:9]
	v_add_u32_e32 v24, 0x20000, v16
	v_add_u32_e32 v25, 0x40000, v16
	v_add_u32_e32 v26, 0x60000, v16
	global_load_dword v132, v16, s[50:51]
	global_load_dword v133, v24, s[50:51]
	global_load_dword v134, v25, s[50:51]
	global_load_dword v135, v26, s[50:51]
	global_load_dwordx2 v[136:137], v17, s[34:35]
	v_add_u32_e32 v15, 0x100000, v15
	v_add_u32_e32 v16, 0x2000, v16
	v_add_u32_e32 v17, 0x1100000, v17
	global_load_dwordx2 v[138:139], v15, s[48:49]
	global_load_dwordx2 v[140:141], v15, s[4:5]
	global_load_dwordx2 v[142:143], v15, s[6:7]
	global_load_dwordx2 v[144:145], v15, s[8:9]
	v_add_u32_e32 v24, 0x20000, v16
	v_add_u32_e32 v25, 0x40000, v16
	v_add_u32_e32 v26, 0x60000, v16
	global_load_dword v146, v16, s[50:51]
	global_load_dword v147, v24, s[50:51]
	global_load_dword v148, v25, s[50:51]
	global_load_dword v149, v26, s[50:51]
	global_load_dwordx2 v[150:151], v17, s[34:35]
	v_add_u32_e32 v15, 0x100000, v15
	v_add_u32_e32 v16, 0x2000, v16
	v_add_u32_e32 v17, 0x1100000, v17
	global_load_dwordx2 v[152:153], v15, s[48:49]
	global_load_dwordx2 v[154:155], v15, s[4:5]
	global_load_dwordx2 v[156:157], v15, s[6:7]
	global_load_dwordx2 v[158:159], v15, s[8:9]
	v_add_u32_e32 v24, 0x20000, v16
	v_add_u32_e32 v25, 0x40000, v16
	v_add_u32_e32 v26, 0x60000, v16
	global_load_dword v160, v16, s[50:51]
	global_load_dword v161, v24, s[50:51]
	global_load_dword v162, v25, s[50:51]
	global_load_dword v163, v26, s[50:51]
	global_load_dwordx2 v[164:165], v17, s[34:35]
	v_add_u32_e32 v15, 0x100000, v15
	v_add_u32_e32 v16, 0x2000, v16
	v_add_u32_e32 v17, 0x1100000, v17
	s_waitcnt vmcnt(40)
	v_lshlrev_b32_e32 v166, 16, v54
	v_and_b32_e32 v167, 0xffff0000, v54
	v_lshlrev_b32_e32 v168, 16, v55
	v_and_b32_e32 v169, 0xffff0000, v55
	v_lshlrev_b32_e32 v190, 16, v56
	v_and_b32_e32 v191, 0xffff0000, v56
	v_lshlrev_b32_e32 v192, 16, v57
	v_and_b32_e32 v193, 0xffff0000, v57
	v_pk_add_f32 v[166:167], v[166:167], v[190:191]
	v_pk_add_f32 v[168:169], v[168:169], v[192:193]
	v_lshlrev_b32_e32 v190, 16, v58
	v_and_b32_e32 v191, 0xffff0000, v58
	v_lshlrev_b32_e32 v192, 16, v59
	v_and_b32_e32 v193, 0xffff0000, v59
	v_pk_add_f32 v[166:167], v[166:167], v[190:191]
	v_pk_add_f32 v[168:169], v[168:169], v[192:193]
	v_lshlrev_b32_e32 v190, 16, v60
	v_and_b32_e32 v191, 0xffff0000, v60
	v_lshlrev_b32_e32 v192, 16, v61
	v_and_b32_e32 v193, 0xffff0000, v61
	v_pk_add_f32 v[166:167], v[166:167], v[190:191]
	v_pk_add_f32 v[168:169], v[168:169], v[192:193]
	v_add_f32_e32 v194, 0, v62
	v_add_f32_e32 v194, v194, v63
	v_add_f32_e32 v194, v194, v64
	v_add_f32_e32 v194, v194, v65
	v_max_f32_e64 v194, |v194|, 1.0
	v_div_scale_f32 v196, s[52:53], v194, v194, 1.0
	v_rcp_f32_e32 v197, v196
	s_nop 0
	v_fma_f32 v198, -v196, v197, 1.0
	v_fmac_f32_e32 v197, v198, v197
	v_div_scale_f32 v198, vcc, 1.0, v194, 1.0
	v_mul_f32_e32 v199, v198, v197
	v_fma_f32 v195, -v196, v199, v198
	v_fmac_f32_e32 v199, v195, v197
	v_fma_f32 v196, -v196, v199, v198
	v_div_fmas_f32 v196, v196, v197, v199
	v_div_fixup_f32 v195, v196, v194, 1.0
	v_mul_f32_e32 v166, v166, v195
	v_mul_f32_e32 v167, v167, v195
	v_mul_f32_e32 v168, v168, v195
	v_mul_f32_e32 v169, v169, v195
	v_mul_f32_e32 v190, v166, v166
	v_mul_f32_e32 v191, v167, v167
	v_mul_f32_e32 v192, v168, v168
	v_mul_f32_e32 v193, v169, v169
	v_add_f32_e32 v190, v191, v190
	v_add_f32_e32 v192, v192, v193
	v_add_f32_e32 v170, v190, v192
; __device__ __forceinline__ float wave_sum(float v) {
; #pragma unroll
;     for (int o = 1; o < 64; o <<= 1) v += __shfl_xor(v, o);
;     return v;
; __global__ void __launch_bounds__(NTHREADS, 2) fwd_megakernel(Params P) {
;     ...
;                 for (int dq = 0; dq < 4; ++dq) { const u32x2 p = *(const u32x2*)(q_mp + (size_t)dq * T * 1024 + o);
;                     v[q][0] += bflo(p.x); v[q][1] += bfhi(p.x); v[q][2] += bflo(p.y); v[q][3] += bfhi(p.y); den[q] += q_dp[(size_t)dq * T * 4 + (size_t)row * 4 + h]; }
;                 mo[q] = *(const u32x2*)(q_proj + (size_t)row * NP + C_MO + h * 256 + 4 * lane);
;             }
; #pragma unroll
;             for (int q = 0; q < 2; ++q) {
;                 const int it = it0 + q * step; const int itc = ok[q] ? it : it0; const int row = itc >> 2, h = itc & 3;
;                 const f32x4 x = v[q] * (1.0f / fmaxf(fabsf(den[q]), 1.0f));
;                 const float ss = wave_sum((x[0] * x[0] + x[1] * x[1]) + (x[2] * x[2] + x[3] * x[3]));
	v_lshlrev_b32_e32 v172, 16, v68
	v_and_b32_e32 v173, 0xffff0000, v68
	v_lshlrev_b32_e32 v174, 16, v69
	v_and_b32_e32 v175, 0xffff0000, v69
	v_lshlrev_b32_e32 v190, 16, v70
	v_and_b32_e32 v191, 0xffff0000, v70
	v_lshlrev_b32_e32 v192, 16, v71
	v_and_b32_e32 v193, 0xffff0000, v71
	v_pk_add_f32 v[172:173], v[172:173], v[190:191]
	v_pk_add_f32 v[174:175], v[174:175], v[192:193]
	v_lshlrev_b32_e32 v190, 16, v72
	v_and_b32_e32 v191, 0xffff0000, v72
	v_lshlrev_b32_e32 v192, 16, v73
	v_and_b32_e32 v193, 0xffff0000, v73
	v_pk_add_f32 v[172:173], v[172:173], v[190:191]
	v_pk_add_f32 v[174:175], v[174:175], v[192:193]
	v_lshlrev_b32_e32 v190, 16, v74
	v_and_b32_e32 v191, 0xffff0000, v74
	v_lshlrev_b32_e32 v192, 16, v75
	v_and_b32_e32 v193, 0xffff0000, v75
	v_pk_add_f32 v[172:173], v[172:173], v[190:191]
	v_pk_add_f32 v[174:175], v[174:175], v[192:193]
	v_add_f32_e32 v194, 0, v76
	v_add_f32_e32 v194, v194, v77
	v_add_f32_e32 v194, v194, v78
	v_add_f32_e32 v194, v194, v79
	v_max_f32_e64 v194, |v194|, 1.0
	v_div_scale_f32 v196, s[52:53], v194, v194, 1.0
	v_rcp_f32_e32 v197, v196
	s_nop 0
	v_fma_f32 v198, -v196, v197, 1.0
	v_fmac_f32_e32 v197, v198, v197
	v_div_scale_f32 v198, vcc, 1.0, v194, 1.0
	v_mul_f32_e32 v199, v198, v197
	v_fma_f32 v195, -v196, v199, v198
	v_fmac_f32_e32 v199, v195, v197
	v_fma_f32 v196, -v196, v199, v198
	v_div_fmas_f32 v196, v196, v197, v199
	v_div_fixup_f32 v195, v196, v194, 1.0
	v_mul_f32_e32 v172, v172, v195
	v_mul_f32_e32 v173, v173, v195
	v_mul_f32_e32 v174, v174, v195
	v_mul_f32_e32 v175, v175, v195
	v_mul_f32_e32 v191, v175, v175
	v_mul_f32_e32 v190, v173, v173
	v_fmac_f32_e32 v190, v172, v172
	v_fmac_f32_e32 v191, v174, v174
	v_add_f32_e32 v176, v190, v191
	v_lshlrev_b32_e32 v178, 16, v82
	v_and_b32_e32 v179, 0xffff0000, v82
	v_lshlrev_b32_e32 v180, 16, v83
	v_and_b32_e32 v181, 0xffff0000, v83
	v_lshlrev_b32_e32 v190, 16, v84
	v_and_b32_e32 v191, 0xffff0000, v84
	v_lshlrev_b32_e32 v192, 16, v85
	v_and_b32_e32 v193, 0xffff0000, v85
	v_pk_add_f32 v[178:179], v[178:179], v[190:191]
	v_pk_add_f32 v[180:181], v[180:181], v[192:193]
	v_lshlrev_b32_e32 v190, 16, v86
	v_and_b32_e32 v191, 0xffff0000, v86
	v_lshlrev_b32_e32 v192, 16, v87
	v_and_b32_e32 v193, 0xffff0000, v87
	v_pk_add_f32 v[178:179], v[178:179], v[190:191]
	v_pk_add_f32 v[180:181], v[180:181], v[192:193]
	v_lshlrev_b32_e32 v190, 16, v88
	v_and_b32_e32 v191, 0xffff0000, v88
	v_lshlrev_b32_e32 v192, 16, v89
	v_and_b32_e32 v193, 0xffff0000, v89
	v_pk_add_f32 v[178:179], v[178:179], v[190:191]
	v_pk_add_f32 v[180:181], v[180:181], v[192:193]
	v_add_f32_e32 v194, 0, v90
	v_add_f32_e32 v194, v194, v91
	v_add_f32_e32 v194, v194, v92
	v_add_f32_e32 v194, v194, v93
	v_max_f32_e64 v194, |v194|, 1.0
	v_div_scale_f32 v196, s[52:53], v194, v194, 1.0
	v_rcp_f32_e32 v197, v196
	s_nop 0
	v_fma_f32 v198, -v196, v197, 1.0
	v_fmac_f32_e32 v197, v198, v197
	v_div_scale_f32 v198, vcc, 1.0, v194, 1.0
	v_mul_f32_e32 v199, v198, v197
	v_fma_f32 v195, -v196, v199, v198
	v_fmac_f32_e32 v199, v195, v197
	v_fma_f32 v196, -v196, v199, v198
	v_div_fmas_f32 v196, v196, v197, v199
	v_div_fixup_f32 v195, v196, v194, 1.0
	v_mul_f32_e32 v178, v178, v195
	v_mul_f32_e32 v179, v179, v195
	v_mul_f32_e32 v180, v180, v195
	v_mul_f32_e32 v181, v181, v195
	v_mul_f32_e32 v190, v178, v178
	v_mul_f32_e32 v191, v179, v179
	v_mul_f32_e32 v192, v180, v180
	v_mul_f32_e32 v193, v181, v181
	v_add_f32_e32 v190, v191, v190
	v_add_f32_e32 v192, v192, v193
	v_add_f32_e32 v182, v190, v192
	v_lshlrev_b32_e32 v184, 16, v96
	v_and_b32_e32 v185, 0xffff0000, v96
	v_lshlrev_b32_e32 v186, 16, v97
	v_and_b32_e32 v187, 0xffff0000, v97
	v_lshlrev_b32_e32 v190, 16, v98
	v_and_b32_e32 v191, 0xffff0000, v98
	v_lshlrev_b32_e32 v192, 16, v99
	v_and_b32_e32 v193, 0xffff0000, v99
	v_pk_add_f32 v[184:185], v[184:185], v[190:191]
	v_pk_add_f32 v[186:187], v[186:187], v[192:193]
	v_lshlrev_b32_e32 v190, 16, v100
	v_and_b32_e32 v191, 0xffff0000, v100
	v_lshlrev_b32_e32 v192, 16, v101
	v_and_b32_e32 v193, 0xffff0000, v101
	v_pk_add_f32 v[184:185], v[184:185], v[190:191]
	v_pk_add_f32 v[186:187], v[186:187], v[192:193]
	v_lshlrev_b32_e32 v190, 16, v102
	v_and_b32_e32 v191, 0xffff0000, v102
	v_lshlrev_b32_e32 v192, 16, v103
	v_and_b32_e32 v193, 0xffff0000, v103
	v_pk_add_f32 v[184:185], v[184:185], v[190:191]
	v_pk_add_f32 v[186:187], v[186:187], v[192:193]
	v_add_f32_e32 v194, 0, v104
	v_add_f32_e32 v194, v194, v105
	v_add_f32_e32 v194, v194, v106
	v_add_f32_e32 v194, v194, v107
	v_max_f32_e64 v194, |v194|, 1.0
	v_div_scale_f32 v196, s[52:53], v194, v194, 1.0
	v_rcp_f32_e32 v197, v196
	s_nop 0
	v_fma_f32 v198, -v196, v197, 1.0
	v_fmac_f32_e32 v197, v198, v197
	v_div_scale_f32 v198, vcc, 1.0, v194, 1.0
	v_mul_f32_e32 v199, v198, v197
	v_fma_f32 v195, -v196, v199, v198
	v_fmac_f32_e32 v199, v195, v197
	v_fma_f32 v196, -v196, v199, v198
	v_div_fmas_f32 v196, v196, v197, v199
	v_div_fixup_f32 v195, v196, v194, 1.0
	v_mul_f32_e32 v184, v184, v195
	v_mul_f32_e32 v185, v185, v195
	v_mul_f32_e32 v186, v186, v195
	v_mul_f32_e32 v187, v187, v195
	v_mul_f32_e32 v191, v187, v187
	v_mul_f32_e32 v190, v185, v185
	v_fmac_f32_e32 v190, v184, v184
	v_fmac_f32_e32 v191, v186, v186
	v_add_f32_e32 v188, v190, v191
	s_nop 1
	v_mov_b32_dpp v171, v170 quad_perm:[1,0,3,2] row_mask:0xf bank_mask:0xf
	v_mov_b32_dpp v177, v176 quad_perm:[1,0,3,2] row_mask:0xf bank_mask:0xf
	v_mov_b32_dpp v183, v182 quad_perm:[1,0,3,2] row_mask:0xf bank_mask:0xf
	v_mov_b32_dpp v189, v188 quad_perm:[1,0,3,2] row_mask:0xf bank_mask:0xf
	v_add_f32_e32 v170, v170, v171
	v_add_f32_e32 v176, v176, v177
	v_add_f32_e32 v182, v182, v183
	v_add_f32_e32 v188, v188, v189
	s_nop 1
; __device__ __forceinline__ unsigned pk2(float lo, float hi) { f32x2_t v = {lo, hi}; bf16x2_t b = __builtin_convertvector(v, bf16x2_t); return __builtin_bit_cast(unsigned, b); }
; __device__ __forceinline__ float sigmoidf_(float x) { return __builtin_amdgcn_rcpf(1.0f + __expf(-x)); }
; __device__ __forceinline__ float wave_sum(float v) {
; #pragma unroll
;     for (int o = 1; o < 64; o <<= 1) v += __shfl_xor(v, o);
;     return v;
; __global__ void __launch_bounds__(NTHREADS, 2) fwd_megakernel(Params P) {
;     ...
;                 const f32x4 x = v[q] * (1.0f / fmaxf(fabsf(den[q]), 1.0f));
;                 const float ss = wave_sum((x[0] * x[0] + x[1] * x[1]) + (x[2] * x[2] + x[3] * x[3]));
;                 const float rsn = 1.0f / sqrtf(ss * (1.0f / 256.0f) + NORM_EPS);
;                 const f32x4 wn = *(const f32x4*)(q_mnw + l * 1024 + h * 256 + 4 * lane);
;                 u32x2 ow;
;                 ow.x = pk2(x[0] * rsn * wn[0] * sigmoidf_(bflo(mo[q].x)), x[1] * rsn * wn[1] * sigmoidf_(bfhi(mo[q].x)));
;                 ow.y = pk2(x[2] * rsn * wn[2] * sigmoidf_(bflo(mo[q].y)), x[3] * rsn * wn[3] * sigmoidf_(bfhi(mo[q].y)));
;                 if (ok[q]) *(u32x2*)(q_hcat + (size_t)row * 1024 + h * 256 + 4 * lane) = ow;
	v_mov_b32_dpp v171, v170 quad_perm:[2,3,0,1] row_mask:0xf bank_mask:0xf
	v_mov_b32_dpp v177, v176 quad_perm:[2,3,0,1] row_mask:0xf bank_mask:0xf
	v_mov_b32_dpp v183, v182 quad_perm:[2,3,0,1] row_mask:0xf bank_mask:0xf
	v_mov_b32_dpp v189, v188 quad_perm:[2,3,0,1] row_mask:0xf bank_mask:0xf
	v_add_f32_e32 v170, v170, v171
	v_add_f32_e32 v176, v176, v177
	v_add_f32_e32 v182, v182, v183
	v_add_f32_e32 v188, v188, v189
	s_nop 1
	v_mov_b32_dpp v171, v170 row_half_mirror row_mask:0xf bank_mask:0xf
	v_mov_b32_dpp v177, v176 row_half_mirror row_mask:0xf bank_mask:0xf
	v_mov_b32_dpp v183, v182 row_half_mirror row_mask:0xf bank_mask:0xf
	v_mov_b32_dpp v189, v188 row_half_mirror row_mask:0xf bank_mask:0xf
	v_add_f32_e32 v170, v170, v171
	v_add_f32_e32 v176, v176, v177
	v_add_f32_e32 v182, v182, v183
	v_add_f32_e32 v188, v188, v189
	s_nop 1
	v_mov_b32_dpp v171, v170 row_mirror row_mask:0xf bank_mask:0xf
	v_mov_b32_dpp v177, v176 row_mirror row_mask:0xf bank_mask:0xf
	v_mov_b32_dpp v183, v182 row_mirror row_mask:0xf bank_mask:0xf
	v_mov_b32_dpp v189, v188 row_mirror row_mask:0xf bank_mask:0xf
	v_add_f32_e32 v170, v170, v171
	v_add_f32_e32 v176, v176, v177
	v_add_f32_e32 v182, v182, v183
	v_add_f32_e32 v188, v188, v189
	v_mov_b32_e32 v171, v170
	v_mov_b32_e32 v177, v176
	v_mov_b32_e32 v183, v182
	v_mov_b32_e32 v189, v188
	s_nop 1
	v_permlane16_swap_b32 v171, v170
	v_permlane16_swap_b32 v177, v176
	v_permlane16_swap_b32 v183, v182
	v_permlane16_swap_b32 v189, v188
	v_add_f32_e32 v170, v170, v171
	v_add_f32_e32 v176, v176, v177
	v_add_f32_e32 v182, v182, v183
	v_add_f32_e32 v188, v188, v189
	v_mov_b32_e32 v171, v170
	v_mov_b32_e32 v177, v176
	v_mov_b32_e32 v183, v182
	v_mov_b32_e32 v189, v188
	s_nop 1
	v_permlane32_swap_b32 v171, v170
	v_permlane32_swap_b32 v177, v176
	v_permlane32_swap_b32 v183, v182
	v_permlane32_swap_b32 v189, v188
	v_add_f32_e32 v170, v170, v171
	v_add_f32_e32 v176, v176, v177
	v_add_f32_e32 v182, v182, v183
	v_add_f32_e32 v188, v188, v189
	v_fmamk_f32 v170, v170, 0x3b800000, v214
	v_cmp_gt_f32_e32 vcc, s66, v170
	v_mul_f32_e32 v190, 0x4f800000, v170
	s_nop 0
	v_cndmask_b32_e32 v170, v170, v190, vcc
	v_sqrt_f32_e32 v190, v170
	s_nop 0
	v_add_u32_e32 v191, -1, v190
	v_fma_f32 v192, -v191, v190, v170
	v_cmp_ge_f32_e64 s[40:41], 0, v192
	v_add_u32_e32 v192, 1, v190
	s_nop 0
	v_cndmask_b32_e64 v191, v190, v191, s[40:41]
	v_fma_f32 v190, -v192, v190, v170
	v_cmp_lt_f32_e64 s[40:41], 0, v190
	s_nop 1
	v_cndmask_b32_e64 v190, v191, v192, s[40:41]
	v_mul_f32_e32 v191, 0x37800000, v190
	v_cndmask_b32_e32 v190, v190, v191, vcc
	v_cmp_class_f32_e32 vcc, v170, v215
	s_nop 1
	v_cndmask_b32_e32 v170, v190, v170, vcc
	v_div_scale_f32 v196, s[52:53], v170, v170, 1.0
	v_rcp_f32_e32 v197, v196
	s_nop 0
	v_fma_f32 v198, -v196, v197, 1.0
	v_fmac_f32_e32 v197, v198, v197
	v_div_scale_f32 v198, vcc, 1.0, v170, 1.0
	v_mul_f32_e32 v199, v198, v197
	v_fma_f32 v195, -v196, v199, v198
	v_fmac_f32_e32 v199, v195, v197
	v_fma_f32 v196, -v196, v199, v198
	v_div_fmas_f32 v196, v196, v197, v199
	v_div_fixup_f32 v195, v196, v170, 1.0
	v_mul_f32_e32 v166, v166, v195
	v_mul_f32_e32 v167, v167, v195
	v_mul_f32_e32 v168, v168, v195
	v_mul_f32_e32 v169, v169, v195
	v_mul_f32_e32 v166, v166, v20
	v_mul_f32_e32 v167, v167, v21
	v_mul_f32_e32 v168, v168, v22
	v_mul_f32_e32 v169, v169, v23
	v_lshlrev_b32_e32 v190, 16, v66
	v_and_b32_e32 v191, 0xffff0000, v66
	v_lshlrev_b32_e32 v192, 16, v67
	v_and_b32_e32 v193, 0xffff0000, v67
	v_mul_f32_e32 v190, 0xbfb8aa3b, v190
	v_mul_f32_e32 v191, 0xbfb8aa3b, v191
	v_mul_f32_e32 v192, 0xbfb8aa3b, v192
	v_mul_f32_e32 v193, 0xbfb8aa3b, v193
	v_exp_f32_e32 v190, v190
	v_exp_f32_e32 v191, v191
	v_exp_f32_e32 v192, v192
	v_exp_f32_e32 v193, v193
	v_add_f32_e32 v190, 1.0, v190
	v_add_f32_e32 v191, 1.0, v191
	v_add_f32_e32 v192, 1.0, v192
	v_add_f32_e32 v193, 1.0, v193
	v_rcp_f32_e32 v190, v190
	v_rcp_f32_e32 v191, v191
	v_rcp_f32_e32 v192, v192
	v_rcp_f32_e32 v193, v193
	v_mul_f32_e32 v166, v190, v166
	v_mul_f32_e32 v167, v191, v167
	v_mul_f32_e32 v168, v192, v168
	v_mul_f32_e32 v169, v193, v169
	v_cvt_pk_bf16_f32 v194, v166, v167
	v_cvt_pk_bf16_f32 v195, v168, v169
	global_store_dwordx2 v33, v[194:195], s[38:39]
	v_add_u32_e32 v33, 0x100000, v33
	v_fmamk_f32 v176, v176, 0x3b800000, v214
	v_cmp_gt_f32_e32 vcc, s66, v176
	v_mul_f32_e32 v190, 0x4f800000, v176
	s_nop 0
	v_cndmask_b32_e32 v176, v176, v190, vcc
	v_sqrt_f32_e32 v190, v176
	s_nop 0
	v_add_u32_e32 v191, -1, v190
	v_fma_f32 v192, -v191, v190, v176
	v_cmp_ge_f32_e64 s[40:41], 0, v192
	v_add_u32_e32 v192, 1, v190
	s_nop 0
	v_cndmask_b32_e64 v191, v190, v191, s[40:41]
	v_fma_f32 v190, -v192, v190, v176
	v_cmp_lt_f32_e64 s[40:41], 0, v190
	s_nop 1
	v_cndmask_b32_e64 v190, v191, v192, s[40:41]
	v_mul_f32_e32 v191, 0x37800000, v190
	v_cndmask_b32_e32 v190, v190, v191, vcc
	v_cmp_class_f32_e32 vcc, v176, v215
	s_nop 1
	v_cndmask_b32_e32 v176, v190, v176, vcc
	v_div_scale_f32 v196, s[52:53], v176, v176, 1.0
	v_rcp_f32_e32 v197, v196
	s_nop 0
	v_fma_f32 v198, -v196, v197, 1.0
	v_fmac_f32_e32 v197, v198, v197
	v_div_scale_f32 v198, vcc, 1.0, v176, 1.0
	v_mul_f32_e32 v199, v198, v197
	v_fma_f32 v195, -v196, v199, v198
	v_fmac_f32_e32 v199, v195, v197
	v_fma_f32 v196, -v196, v199, v198
	v_div_fmas_f32 v196, v196, v197, v199
	v_div_fixup_f32 v195, v196, v176, 1.0
	v_mul_f32_e32 v172, v172, v195
	v_mul_f32_e32 v173, v173, v195
	v_mul_f32_e32 v174, v174, v195
	v_mul_f32_e32 v175, v175, v195
	v_mul_f32_e32 v172, v172, v20
	v_mul_f32_e32 v173, v173, v21
	v_mul_f32_e32 v174, v174, v22
	v_mul_f32_e32 v175, v175, v23
	v_lshlrev_b32_e32 v190, 16, v80
	v_and_b32_e32 v191, 0xffff0000, v80
; __device__ __forceinline__ unsigned pk2(float lo, float hi) { f32x2_t v = {lo, hi}; bf16x2_t b = __builtin_convertvector(v, bf16x2_t); return __builtin_bit_cast(unsigned, b); }
; __device__ __forceinline__ float sigmoidf_(float x) { return __builtin_amdgcn_rcpf(1.0f + __expf(-x)); }
; __global__ void __launch_bounds__(NTHREADS, 2) fwd_megakernel(Params P) {
;     ...
;                 const float rsn = 1.0f / sqrtf(ss * (1.0f / 256.0f) + NORM_EPS);
;                 const f32x4 wn = *(const f32x4*)(q_mnw + l * 1024 + h * 256 + 4 * lane);
;                 u32x2 ow;
;                 ow.x = pk2(x[0] * rsn * wn[0] * sigmoidf_(bflo(mo[q].x)), x[1] * rsn * wn[1] * sigmoidf_(bfhi(mo[q].x)));
;                 ow.y = pk2(x[2] * rsn * wn[2] * sigmoidf_(bflo(mo[q].y)), x[3] * rsn * wn[3] * sigmoidf_(bfhi(mo[q].y)));
;                 if (ok[q]) *(u32x2*)(q_hcat + (size_t)row * 1024 + h * 256 + 4 * lane) = ow;
	v_lshlrev_b32_e32 v192, 16, v81
	v_and_b32_e32 v193, 0xffff0000, v81
	v_mul_f32_e32 v190, 0xbfb8aa3b, v190
	v_mul_f32_e32 v191, 0xbfb8aa3b, v191
	v_mul_f32_e32 v192, 0xbfb8aa3b, v192
	v_mul_f32_e32 v193, 0xbfb8aa3b, v193
	v_exp_f32_e32 v190, v190
	v_exp_f32_e32 v191, v191
	v_exp_f32_e32 v192, v192
	v_exp_f32_e32 v193, v193
	v_add_f32_e32 v190, 1.0, v190
	v_add_f32_e32 v191, 1.0, v191
	v_add_f32_e32 v192, 1.0, v192
	v_add_f32_e32 v193, 1.0, v193
	v_rcp_f32_e32 v190, v190
	v_rcp_f32_e32 v191, v191
	v_rcp_f32_e32 v192, v192
	v_rcp_f32_e32 v193, v193
	v_mul_f32_e32 v172, v190, v172
	v_mul_f32_e32 v173, v191, v173
	v_mul_f32_e32 v174, v192, v174
	v_mul_f32_e32 v175, v193, v175
	v_cvt_pk_bf16_f32 v194, v172, v173
	v_cvt_pk_bf16_f32 v195, v174, v175
	global_store_dwordx2 v33, v[194:195], s[38:39]
	v_add_u32_e32 v33, 0x100000, v33
	v_fmamk_f32 v182, v182, 0x3b800000, v214
	v_cmp_gt_f32_e32 vcc, s66, v182
	v_mul_f32_e32 v190, 0x4f800000, v182
	s_nop 0
	v_cndmask_b32_e32 v182, v182, v190, vcc
	v_sqrt_f32_e32 v190, v182
	s_nop 0
	v_add_u32_e32 v191, -1, v190
	v_fma_f32 v192, -v191, v190, v182
	v_cmp_ge_f32_e64 s[40:41], 0, v192
	v_add_u32_e32 v192, 1, v190
	s_nop 0
	v_cndmask_b32_e64 v191, v190, v191, s[40:41]
	v_fma_f32 v190, -v192, v190, v182
	v_cmp_lt_f32_e64 s[40:41], 0, v190
	s_nop 1
	v_cndmask_b32_e64 v190, v191, v192, s[40:41]
	v_mul_f32_e32 v191, 0x37800000, v190
	v_cndmask_b32_e32 v190, v190, v191, vcc
	v_cmp_class_f32_e32 vcc, v182, v215
	s_nop 1
	v_cndmask_b32_e32 v182, v190, v182, vcc
	v_div_scale_f32 v196, s[52:53], v182, v182, 1.0
	v_rcp_f32_e32 v197, v196
	s_nop 0
	v_fma_f32 v198, -v196, v197, 1.0
	v_fmac_f32_e32 v197, v198, v197
	v_div_scale_f32 v198, vcc, 1.0, v182, 1.0
	v_mul_f32_e32 v199, v198, v197
	v_fma_f32 v195, -v196, v199, v198
	v_fmac_f32_e32 v199, v195, v197
	v_fma_f32 v196, -v196, v199, v198
	v_div_fmas_f32 v196, v196, v197, v199
	v_div_fixup_f32 v195, v196, v182, 1.0
	v_mul_f32_e32 v178, v178, v195
	v_mul_f32_e32 v179, v179, v195
	v_mul_f32_e32 v180, v180, v195
	v_mul_f32_e32 v181, v181, v195
	v_mul_f32_e32 v178, v178, v20
	v_mul_f32_e32 v179, v179, v21
	v_mul_f32_e32 v180, v180, v22
	v_mul_f32_e32 v181, v181, v23
	v_lshlrev_b32_e32 v190, 16, v94
	v_and_b32_e32 v191, 0xffff0000, v94
	v_lshlrev_b32_e32 v192, 16, v95
	v_and_b32_e32 v193, 0xffff0000, v95
	v_mul_f32_e32 v190, 0xbfb8aa3b, v190
	v_mul_f32_e32 v191, 0xbfb8aa3b, v191
	v_mul_f32_e32 v192, 0xbfb8aa3b, v192
	v_mul_f32_e32 v193, 0xbfb8aa3b, v193
	v_exp_f32_e32 v190, v190
	v_exp_f32_e32 v191, v191
	v_exp_f32_e32 v192, v192
	v_exp_f32_e32 v193, v193
	v_add_f32_e32 v190, 1.0, v190
	v_add_f32_e32 v191, 1.0, v191
	v_add_f32_e32 v192, 1.0, v192
	v_add_f32_e32 v193, 1.0, v193
	v_rcp_f32_e32 v190, v190
	v_rcp_f32_e32 v191, v191
	v_rcp_f32_e32 v192, v192
	v_rcp_f32_e32 v193, v193
	v_mul_f32_e32 v178, v190, v178
	v_mul_f32_e32 v179, v191, v179
	v_mul_f32_e32 v180, v192, v180
	v_mul_f32_e32 v181, v193, v181
	v_cvt_pk_bf16_f32 v194, v178, v179
	v_cvt_pk_bf16_f32 v195, v180, v181
	global_store_dwordx2 v33, v[194:195], s[38:39]
	v_add_u32_e32 v33, 0x100000, v33
	v_fmamk_f32 v188, v188, 0x3b800000, v214
	v_cmp_gt_f32_e32 vcc, s66, v188
	v_mul_f32_e32 v190, 0x4f800000, v188
	s_nop 0
	v_cndmask_b32_e32 v188, v188, v190, vcc
	v_sqrt_f32_e32 v190, v188
	s_nop 0
	v_add_u32_e32 v191, -1, v190
	v_fma_f32 v192, -v191, v190, v188
	v_cmp_ge_f32_e64 s[40:41], 0, v192
	v_add_u32_e32 v192, 1, v190
	s_nop 0
	v_cndmask_b32_e64 v191, v190, v191, s[40:41]
	v_fma_f32 v190, -v192, v190, v188
	v_cmp_lt_f32_e64 s[40:41], 0, v190
	s_nop 1
	v_cndmask_b32_e64 v190, v191, v192, s[40:41]
	v_mul_f32_e32 v191, 0x37800000, v190
	v_cndmask_b32_e32 v190, v190, v191, vcc
	v_cmp_class_f32_e32 vcc, v188, v215
	s_nop 1
	v_cndmask_b32_e32 v188, v190, v188, vcc
	v_div_scale_f32 v196, s[52:53], v188, v188, 1.0
	v_rcp_f32_e32 v197, v196
	s_nop 0
	v_fma_f32 v198, -v196, v197, 1.0
	v_fmac_f32_e32 v197, v198, v197
	v_div_scale_f32 v198, vcc, 1.0, v188, 1.0
	v_mul_f32_e32 v199, v198, v197
	v_fma_f32 v195, -v196, v199, v198
	v_fmac_f32_e32 v199, v195, v197
	v_fma_f32 v196, -v196, v199, v198
	v_div_fmas_f32 v196, v196, v197, v199
	v_div_fixup_f32 v195, v196, v188, 1.0
	v_mul_f32_e32 v184, v184, v195
	v_mul_f32_e32 v185, v185, v195
	v_mul_f32_e32 v186, v186, v195
	v_mul_f32_e32 v187, v187, v195
	v_mul_f32_e32 v184, v184, v20
	v_mul_f32_e32 v185, v185, v21
	v_mul_f32_e32 v186, v186, v22
	v_mul_f32_e32 v187, v187, v23
	v_lshlrev_b32_e32 v190, 16, v108
	v_and_b32_e32 v191, 0xffff0000, v108
	v_lshlrev_b32_e32 v192, 16, v109
	v_and_b32_e32 v193, 0xffff0000, v109
	v_mul_f32_e32 v190, 0xbfb8aa3b, v190
	v_mul_f32_e32 v191, 0xbfb8aa3b, v191
	v_mul_f32_e32 v192, 0xbfb8aa3b, v192
	v_mul_f32_e32 v193, 0xbfb8aa3b, v193
	v_exp_f32_e32 v190, v190
	v_exp_f32_e32 v191, v191
	v_exp_f32_e32 v192, v192
	v_exp_f32_e32 v193, v193
	v_add_f32_e32 v190, 1.0, v190
	v_add_f32_e32 v191, 1.0, v191
	v_add_f32_e32 v192, 1.0, v192
	v_add_f32_e32 v193, 1.0, v193
	v_rcp_f32_e32 v190, v190
	v_rcp_f32_e32 v191, v191
	v_rcp_f32_e32 v192, v192
	v_rcp_f32_e32 v193, v193
	v_mul_f32_e32 v184, v190, v184
	v_mul_f32_e32 v185, v191, v185
	v_mul_f32_e32 v186, v192, v186
	v_mul_f32_e32 v187, v193, v187
	v_cvt_pk_bf16_f32 v194, v184, v185
	v_cvt_pk_bf16_f32 v195, v186, v187
	global_store_dwordx2 v33, v[194:195], s[38:39]
	v_add_u32_e32 v33, 0x100000, v33
	s_waitcnt vmcnt(0)
; __global__ void __launch_bounds__(NTHREADS, 2) fwd_megakernel(Params P) {
;     ...
;                 for (int dq = 0; dq < 4; ++dq) { const u32x2 p = *(const u32x2*)(q_mp + (size_t)dq * T * 1024 + o);
;                     v[q][0] += bflo(p.x); v[q][1] += bfhi(p.x); v[q][2] += bflo(p.y); v[q][3] += bfhi(p.y); den[q] += q_dp[(size_t)dq * T * 4 + (size_t)row * 4 + h]; }
;                 mo[q] = *(const u32x2*)(q_proj + (size_t)row * NP + C_MO + h * 256 + 4 * lane);
;             }
; #pragma unroll
;             for (int q = 0; q < 2; ++q) {
;                 const int it = it0 + q * step; const int itc = ok[q] ? it : it0; const int row = itc >> 2, h = itc & 3;
;                 const f32x4 x = v[q] * (1.0f / fmaxf(fabsf(den[q]), 1.0f));
;                 const float ss = wave_sum((x[0] * x[0] + x[1] * x[1]) + (x[2] * x[2] + x[3] * x[3]));
	v_lshlrev_b32_e32 v166, 16, v110
	v_and_b32_e32 v167, 0xffff0000, v110
	v_lshlrev_b32_e32 v168, 16, v111
	v_and_b32_e32 v169, 0xffff0000, v111
	v_lshlrev_b32_e32 v190, 16, v112
	v_and_b32_e32 v191, 0xffff0000, v112
	v_lshlrev_b32_e32 v192, 16, v113
	v_and_b32_e32 v193, 0xffff0000, v113
	v_pk_add_f32 v[166:167], v[166:167], v[190:191]
	v_pk_add_f32 v[168:169], v[168:169], v[192:193]
	v_lshlrev_b32_e32 v190, 16, v114
	v_and_b32_e32 v191, 0xffff0000, v114
	v_lshlrev_b32_e32 v192, 16, v115
	v_and_b32_e32 v193, 0xffff0000, v115
	v_pk_add_f32 v[166:167], v[166:167], v[190:191]
	v_pk_add_f32 v[168:169], v[168:169], v[192:193]
	v_lshlrev_b32_e32 v190, 16, v116
	v_and_b32_e32 v191, 0xffff0000, v116
	v_lshlrev_b32_e32 v192, 16, v117
	v_and_b32_e32 v193, 0xffff0000, v117
	v_pk_add_f32 v[166:167], v[166:167], v[190:191]
	v_pk_add_f32 v[168:169], v[168:169], v[192:193]
	v_add_f32_e32 v194, 0, v118
	v_add_f32_e32 v194, v194, v119
	v_add_f32_e32 v194, v194, v120
	v_add_f32_e32 v194, v194, v121
	v_max_f32_e64 v194, |v194|, 1.0
	v_div_scale_f32 v196, s[52:53], v194, v194, 1.0
	v_rcp_f32_e32 v197, v196
	s_nop 0
	v_fma_f32 v198, -v196, v197, 1.0
	v_fmac_f32_e32 v197, v198, v197
	v_div_scale_f32 v198, vcc, 1.0, v194, 1.0
	v_mul_f32_e32 v199, v198, v197
	v_fma_f32 v195, -v196, v199, v198
	v_fmac_f32_e32 v199, v195, v197
	v_fma_f32 v196, -v196, v199, v198
	v_div_fmas_f32 v196, v196, v197, v199
	v_div_fixup_f32 v195, v196, v194, 1.0
	v_mul_f32_e32 v166, v166, v195
	v_mul_f32_e32 v167, v167, v195
	v_mul_f32_e32 v168, v168, v195
	v_mul_f32_e32 v169, v169, v195
	v_mul_f32_e32 v190, v166, v166
	v_mul_f32_e32 v191, v167, v167
	v_mul_f32_e32 v192, v168, v168
	v_mul_f32_e32 v193, v169, v169
	v_add_f32_e32 v190, v191, v190
	v_add_f32_e32 v192, v192, v193
	v_add_f32_e32 v170, v190, v192
	v_lshlrev_b32_e32 v172, 16, v124
	v_and_b32_e32 v173, 0xffff0000, v124
	v_lshlrev_b32_e32 v174, 16, v125
	v_and_b32_e32 v175, 0xffff0000, v125
	v_lshlrev_b32_e32 v190, 16, v126
	v_and_b32_e32 v191, 0xffff0000, v126
	v_lshlrev_b32_e32 v192, 16, v127
	v_and_b32_e32 v193, 0xffff0000, v127
	v_pk_add_f32 v[172:173], v[172:173], v[190:191]
	v_pk_add_f32 v[174:175], v[174:175], v[192:193]
	v_lshlrev_b32_e32 v190, 16, v128
	v_and_b32_e32 v191, 0xffff0000, v128
	v_lshlrev_b32_e32 v192, 16, v129
	v_and_b32_e32 v193, 0xffff0000, v129
	v_pk_add_f32 v[172:173], v[172:173], v[190:191]
	v_pk_add_f32 v[174:175], v[174:175], v[192:193]
	v_lshlrev_b32_e32 v190, 16, v130
	v_and_b32_e32 v191, 0xffff0000, v130
	v_lshlrev_b32_e32 v192, 16, v131
	v_and_b32_e32 v193, 0xffff0000, v131
	v_pk_add_f32 v[172:173], v[172:173], v[190:191]
	v_pk_add_f32 v[174:175], v[174:175], v[192:193]
	v_add_f32_e32 v194, 0, v132
	v_add_f32_e32 v194, v194, v133
	v_add_f32_e32 v194, v194, v134
	v_add_f32_e32 v194, v194, v135
	v_max_f32_e64 v194, |v194|, 1.0
	v_div_scale_f32 v196, s[52:53], v194, v194, 1.0
	v_rcp_f32_e32 v197, v196
	s_nop 0
	v_fma_f32 v198, -v196, v197, 1.0
	v_fmac_f32_e32 v197, v198, v197
	v_div_scale_f32 v198, vcc, 1.0, v194, 1.0
	v_mul_f32_e32 v199, v198, v197
	v_fma_f32 v195, -v196, v199, v198
	v_fmac_f32_e32 v199, v195, v197
	v_fma_f32 v196, -v196, v199, v198
	v_div_fmas_f32 v196, v196, v197, v199
	v_div_fixup_f32 v195, v196, v194, 1.0
	v_mul_f32_e32 v172, v172, v195
	v_mul_f32_e32 v173, v173, v195
	v_mul_f32_e32 v174, v174, v195
	v_mul_f32_e32 v175, v175, v195
	v_mul_f32_e32 v191, v175, v175
	v_mul_f32_e32 v190, v173, v173
	v_fmac_f32_e32 v190, v172, v172
	v_fmac_f32_e32 v191, v174, v174
	v_add_f32_e32 v176, v190, v191
	v_lshlrev_b32_e32 v178, 16, v138
	v_and_b32_e32 v179, 0xffff0000, v138
	v_lshlrev_b32_e32 v180, 16, v139
	v_and_b32_e32 v181, 0xffff0000, v139
	v_lshlrev_b32_e32 v190, 16, v140
	v_and_b32_e32 v191, 0xffff0000, v140
	v_lshlrev_b32_e32 v192, 16, v141
	v_and_b32_e32 v193, 0xffff0000, v141
	v_pk_add_f32 v[178:179], v[178:179], v[190:191]
	v_pk_add_f32 v[180:181], v[180:181], v[192:193]
	v_lshlrev_b32_e32 v190, 16, v142
	v_and_b32_e32 v191, 0xffff0000, v142
	v_lshlrev_b32_e32 v192, 16, v143
	v_and_b32_e32 v193, 0xffff0000, v143
	v_pk_add_f32 v[178:179], v[178:179], v[190:191]
	v_pk_add_f32 v[180:181], v[180:181], v[192:193]
	v_lshlrev_b32_e32 v190, 16, v144
	v_and_b32_e32 v191, 0xffff0000, v144
	v_lshlrev_b32_e32 v192, 16, v145
	v_and_b32_e32 v193, 0xffff0000, v145
	v_pk_add_f32 v[178:179], v[178:179], v[190:191]
	v_pk_add_f32 v[180:181], v[180:181], v[192:193]
	v_add_f32_e32 v194, 0, v146
	v_add_f32_e32 v194, v194, v147
	v_add_f32_e32 v194, v194, v148
	v_add_f32_e32 v194, v194, v149
	v_max_f32_e64 v194, |v194|, 1.0
	v_div_scale_f32 v196, s[52:53], v194, v194, 1.0
	v_rcp_f32_e32 v197, v196
	s_nop 0
	v_fma_f32 v198, -v196, v197, 1.0
	v_fmac_f32_e32 v197, v198, v197
	v_div_scale_f32 v198, vcc, 1.0, v194, 1.0
	v_mul_f32_e32 v199, v198, v197
	v_fma_f32 v195, -v196, v199, v198
	v_fmac_f32_e32 v199, v195, v197
	v_fma_f32 v196, -v196, v199, v198
	v_div_fmas_f32 v196, v196, v197, v199
	v_div_fixup_f32 v195, v196, v194, 1.0
	v_mul_f32_e32 v178, v178, v195
	v_mul_f32_e32 v179, v179, v195
	v_mul_f32_e32 v180, v180, v195
	v_mul_f32_e32 v181, v181, v195
	v_mul_f32_e32 v190, v178, v178
	v_mul_f32_e32 v191, v179, v179
	v_mul_f32_e32 v192, v180, v180
	v_mul_f32_e32 v193, v181, v181
	v_add_f32_e32 v190, v191, v190
	v_add_f32_e32 v192, v192, v193
	v_add_f32_e32 v182, v190, v192
	v_lshlrev_b32_e32 v184, 16, v152
	v_and_b32_e32 v185, 0xffff0000, v152
	v_lshlrev_b32_e32 v186, 16, v153
	v_and_b32_e32 v187, 0xffff0000, v153
	v_lshlrev_b32_e32 v190, 16, v154
	v_and_b32_e32 v191, 0xffff0000, v154
	v_lshlrev_b32_e32 v192, 16, v155
	v_and_b32_e32 v193, 0xffff0000, v155
	v_pk_add_f32 v[184:185], v[184:185], v[190:191]
; __device__ __forceinline__ unsigned pk2(float lo, float hi) { f32x2_t v = {lo, hi}; bf16x2_t b = __builtin_convertvector(v, bf16x2_t); return __builtin_bit_cast(unsigned, b); }
; __device__ __forceinline__ float sigmoidf_(float x) { return __builtin_amdgcn_rcpf(1.0f + __expf(-x)); }
; __device__ __forceinline__ float wave_sum(float v) {
; #pragma unroll
;     for (int o = 1; o < 64; o <<= 1) v += __shfl_xor(v, o);
;     return v;
; __global__ void __launch_bounds__(NTHREADS, 2) fwd_megakernel(Params P) {
;     ...
;                 const f32x4 x = v[q] * (1.0f / fmaxf(fabsf(den[q]), 1.0f));
;                 const float ss = wave_sum((x[0] * x[0] + x[1] * x[1]) + (x[2] * x[2] + x[3] * x[3]));
;                 const float rsn = 1.0f / sqrtf(ss * (1.0f / 256.0f) + NORM_EPS);
;                 const f32x4 wn = *(const f32x4*)(q_mnw + l * 1024 + h * 256 + 4 * lane);
;                 u32x2 ow;
;                 ow.x = pk2(x[0] * rsn * wn[0] * sigmoidf_(bflo(mo[q].x)), x[1] * rsn * wn[1] * sigmoidf_(bfhi(mo[q].x)));
;                 ow.y = pk2(x[2] * rsn * wn[2] * sigmoidf_(bflo(mo[q].y)), x[3] * rsn * wn[3] * sigmoidf_(bfhi(mo[q].y)));
;                 if (ok[q]) *(u32x2*)(q_hcat + (size_t)row * 1024 + h * 256 + 4 * lane) = ow;
	v_pk_add_f32 v[186:187], v[186:187], v[192:193]
	v_lshlrev_b32_e32 v190, 16, v156
	v_and_b32_e32 v191, 0xffff0000, v156
	v_lshlrev_b32_e32 v192, 16, v157
	v_and_b32_e32 v193, 0xffff0000, v157
	v_pk_add_f32 v[184:185], v[184:185], v[190:191]
	v_pk_add_f32 v[186:187], v[186:187], v[192:193]
	v_lshlrev_b32_e32 v190, 16, v158
	v_and_b32_e32 v191, 0xffff0000, v158
	v_lshlrev_b32_e32 v192, 16, v159
	v_and_b32_e32 v193, 0xffff0000, v159
	v_pk_add_f32 v[184:185], v[184:185], v[190:191]
	v_pk_add_f32 v[186:187], v[186:187], v[192:193]
	v_add_f32_e32 v194, 0, v160
	v_add_f32_e32 v194, v194, v161
	v_add_f32_e32 v194, v194, v162
	v_add_f32_e32 v194, v194, v163
	v_max_f32_e64 v194, |v194|, 1.0
	v_div_scale_f32 v196, s[52:53], v194, v194, 1.0
	v_rcp_f32_e32 v197, v196
	s_nop 0
	v_fma_f32 v198, -v196, v197, 1.0
	v_fmac_f32_e32 v197, v198, v197
	v_div_scale_f32 v198, vcc, 1.0, v194, 1.0
	v_mul_f32_e32 v199, v198, v197
	v_fma_f32 v195, -v196, v199, v198
	v_fmac_f32_e32 v199, v195, v197
	v_fma_f32 v196, -v196, v199, v198
	v_div_fmas_f32 v196, v196, v197, v199
	v_div_fixup_f32 v195, v196, v194, 1.0
	v_mul_f32_e32 v184, v184, v195
	v_mul_f32_e32 v185, v185, v195
	v_mul_f32_e32 v186, v186, v195
	v_mul_f32_e32 v187, v187, v195
	v_mul_f32_e32 v191, v187, v187
	v_mul_f32_e32 v190, v185, v185
	v_fmac_f32_e32 v190, v184, v184
	v_fmac_f32_e32 v191, v186, v186
	v_add_f32_e32 v188, v190, v191
	s_nop 1
	v_mov_b32_dpp v171, v170 quad_perm:[1,0,3,2] row_mask:0xf bank_mask:0xf
	v_mov_b32_dpp v177, v176 quad_perm:[1,0,3,2] row_mask:0xf bank_mask:0xf
	v_mov_b32_dpp v183, v182 quad_perm:[1,0,3,2] row_mask:0xf bank_mask:0xf
	v_mov_b32_dpp v189, v188 quad_perm:[1,0,3,2] row_mask:0xf bank_mask:0xf
	v_add_f32_e32 v170, v170, v171
	v_add_f32_e32 v176, v176, v177
	v_add_f32_e32 v182, v182, v183
	v_add_f32_e32 v188, v188, v189
	s_nop 1
	v_mov_b32_dpp v171, v170 quad_perm:[2,3,0,1] row_mask:0xf bank_mask:0xf
	v_mov_b32_dpp v177, v176 quad_perm:[2,3,0,1] row_mask:0xf bank_mask:0xf
	v_mov_b32_dpp v183, v182 quad_perm:[2,3,0,1] row_mask:0xf bank_mask:0xf
	v_mov_b32_dpp v189, v188 quad_perm:[2,3,0,1] row_mask:0xf bank_mask:0xf
	v_add_f32_e32 v170, v170, v171
	v_add_f32_e32 v176, v176, v177
	v_add_f32_e32 v182, v182, v183
	v_add_f32_e32 v188, v188, v189
	s_nop 1
	v_mov_b32_dpp v171, v170 row_half_mirror row_mask:0xf bank_mask:0xf
	v_mov_b32_dpp v177, v176 row_half_mirror row_mask:0xf bank_mask:0xf
	v_mov_b32_dpp v183, v182 row_half_mirror row_mask:0xf bank_mask:0xf
	v_mov_b32_dpp v189, v188 row_half_mirror row_mask:0xf bank_mask:0xf
	v_add_f32_e32 v170, v170, v171
	v_add_f32_e32 v176, v176, v177
	v_add_f32_e32 v182, v182, v183
	v_add_f32_e32 v188, v188, v189
	s_nop 1
	v_mov_b32_dpp v171, v170 row_mirror row_mask:0xf bank_mask:0xf
	v_mov_b32_dpp v177, v176 row_mirror row_mask:0xf bank_mask:0xf
	v_mov_b32_dpp v183, v182 row_mirror row_mask:0xf bank_mask:0xf
	v_mov_b32_dpp v189, v188 row_mirror row_mask:0xf bank_mask:0xf
	v_add_f32_e32 v170, v170, v171
	v_add_f32_e32 v176, v176, v177
	v_add_f32_e32 v182, v182, v183
	v_add_f32_e32 v188, v188, v189
	v_mov_b32_e32 v171, v170
	v_mov_b32_e32 v177, v176
	v_mov_b32_e32 v183, v182
	v_mov_b32_e32 v189, v188
	s_nop 1
	v_permlane16_swap_b32 v171, v170
	v_permlane16_swap_b32 v177, v176
	v_permlane16_swap_b32 v183, v182
	v_permlane16_swap_b32 v189, v188
	v_add_f32_e32 v170, v170, v171
	v_add_f32_e32 v176, v176, v177
	v_add_f32_e32 v182, v182, v183
	v_add_f32_e32 v188, v188, v189
	v_mov_b32_e32 v171, v170
	v_mov_b32_e32 v177, v176
	v_mov_b32_e32 v183, v182
	v_mov_b32_e32 v189, v188
	s_nop 1
	v_permlane32_swap_b32 v171, v170
	v_permlane32_swap_b32 v177, v176
	v_permlane32_swap_b32 v183, v182
	v_permlane32_swap_b32 v189, v188
	v_add_f32_e32 v170, v170, v171
	v_add_f32_e32 v176, v176, v177
	v_add_f32_e32 v182, v182, v183
	v_add_f32_e32 v188, v188, v189
	v_fmamk_f32 v170, v170, 0x3b800000, v214
	v_cmp_gt_f32_e32 vcc, s66, v170
	v_mul_f32_e32 v190, 0x4f800000, v170
	s_nop 0
	v_cndmask_b32_e32 v170, v170, v190, vcc
	v_sqrt_f32_e32 v190, v170
	s_nop 0
	v_add_u32_e32 v191, -1, v190
	v_fma_f32 v192, -v191, v190, v170
	v_cmp_ge_f32_e64 s[40:41], 0, v192
	v_add_u32_e32 v192, 1, v190
	s_nop 0
	v_cndmask_b32_e64 v191, v190, v191, s[40:41]
	v_fma_f32 v190, -v192, v190, v170
	v_cmp_lt_f32_e64 s[40:41], 0, v190
	s_nop 1
	v_cndmask_b32_e64 v190, v191, v192, s[40:41]
	v_mul_f32_e32 v191, 0x37800000, v190
	v_cndmask_b32_e32 v190, v190, v191, vcc
	v_cmp_class_f32_e32 vcc, v170, v215
	s_nop 1
	v_cndmask_b32_e32 v170, v190, v170, vcc
	v_div_scale_f32 v196, s[52:53], v170, v170, 1.0
	v_rcp_f32_e32 v197, v196
	s_nop 0
	v_fma_f32 v198, -v196, v197, 1.0
	v_fmac_f32_e32 v197, v198, v197
	v_div_scale_f32 v198, vcc, 1.0, v170, 1.0
	v_mul_f32_e32 v199, v198, v197
	v_fma_f32 v195, -v196, v199, v198
	v_fmac_f32_e32 v199, v195, v197
	v_fma_f32 v196, -v196, v199, v198
	v_div_fmas_f32 v196, v196, v197, v199
	v_div_fixup_f32 v195, v196, v170, 1.0
	v_mul_f32_e32 v166, v166, v195
	v_mul_f32_e32 v167, v167, v195
	v_mul_f32_e32 v168, v168, v195
	v_mul_f32_e32 v169, v169, v195
	v_mul_f32_e32 v166, v166, v20
	v_mul_f32_e32 v167, v167, v21
	v_mul_f32_e32 v168, v168, v22
	v_mul_f32_e32 v169, v169, v23
	v_lshlrev_b32_e32 v190, 16, v122
	v_and_b32_e32 v191, 0xffff0000, v122
	v_lshlrev_b32_e32 v192, 16, v123
	v_and_b32_e32 v193, 0xffff0000, v123
	v_mul_f32_e32 v190, 0xbfb8aa3b, v190
	v_mul_f32_e32 v191, 0xbfb8aa3b, v191
	v_mul_f32_e32 v192, 0xbfb8aa3b, v192
	v_mul_f32_e32 v193, 0xbfb8aa3b, v193
	v_exp_f32_e32 v190, v190
	v_exp_f32_e32 v191, v191
	v_exp_f32_e32 v192, v192
	v_exp_f32_e32 v193, v193
	v_add_f32_e32 v190, 1.0, v190
	v_add_f32_e32 v191, 1.0, v191
	v_add_f32_e32 v192, 1.0, v192
; __device__ __forceinline__ unsigned pk2(float lo, float hi) { f32x2_t v = {lo, hi}; bf16x2_t b = __builtin_convertvector(v, bf16x2_t); return __builtin_bit_cast(unsigned, b); }
; __device__ __forceinline__ float sigmoidf_(float x) { return __builtin_amdgcn_rcpf(1.0f + __expf(-x)); }
; __global__ void __launch_bounds__(NTHREADS, 2) fwd_megakernel(Params P) {
;     ...
;                 const float rsn = 1.0f / sqrtf(ss * (1.0f / 256.0f) + NORM_EPS);
;                 const f32x4 wn = *(const f32x4*)(q_mnw + l * 1024 + h * 256 + 4 * lane);
;                 u32x2 ow;
;                 ow.x = pk2(x[0] * rsn * wn[0] * sigmoidf_(bflo(mo[q].x)), x[1] * rsn * wn[1] * sigmoidf_(bfhi(mo[q].x)));
;                 ow.y = pk2(x[2] * rsn * wn[2] * sigmoidf_(bflo(mo[q].y)), x[3] * rsn * wn[3] * sigmoidf_(bfhi(mo[q].y)));
;                 if (ok[q]) *(u32x2*)(q_hcat + (size_t)row * 1024 + h * 256 + 4 * lane) = ow;
	v_add_f32_e32 v193, 1.0, v193
	v_rcp_f32_e32 v190, v190
	v_rcp_f32_e32 v191, v191
	v_rcp_f32_e32 v192, v192
	v_rcp_f32_e32 v193, v193
	v_mul_f32_e32 v166, v190, v166
	v_mul_f32_e32 v167, v191, v167
	v_mul_f32_e32 v168, v192, v168
	v_mul_f32_e32 v169, v193, v169
	v_cvt_pk_bf16_f32 v194, v166, v167
	v_cvt_pk_bf16_f32 v195, v168, v169
	global_store_dwordx2 v33, v[194:195], s[38:39]
	v_add_u32_e32 v33, 0x100000, v33
	v_fmamk_f32 v176, v176, 0x3b800000, v214
	v_cmp_gt_f32_e32 vcc, s66, v176
	v_mul_f32_e32 v190, 0x4f800000, v176
	s_nop 0
	v_cndmask_b32_e32 v176, v176, v190, vcc
	v_sqrt_f32_e32 v190, v176
	s_nop 0
	v_add_u32_e32 v191, -1, v190
	v_fma_f32 v192, -v191, v190, v176
	v_cmp_ge_f32_e64 s[40:41], 0, v192
	v_add_u32_e32 v192, 1, v190
	s_nop 0
	v_cndmask_b32_e64 v191, v190, v191, s[40:41]
	v_fma_f32 v190, -v192, v190, v176
	v_cmp_lt_f32_e64 s[40:41], 0, v190
	s_nop 1
	v_cndmask_b32_e64 v190, v191, v192, s[40:41]
	v_mul_f32_e32 v191, 0x37800000, v190
	v_cndmask_b32_e32 v190, v190, v191, vcc
	v_cmp_class_f32_e32 vcc, v176, v215
	s_nop 1
	v_cndmask_b32_e32 v176, v190, v176, vcc
	v_div_scale_f32 v196, s[52:53], v176, v176, 1.0
	v_rcp_f32_e32 v197, v196
	s_nop 0
	v_fma_f32 v198, -v196, v197, 1.0
	v_fmac_f32_e32 v197, v198, v197
	v_div_scale_f32 v198, vcc, 1.0, v176, 1.0
	v_mul_f32_e32 v199, v198, v197
	v_fma_f32 v195, -v196, v199, v198
	v_fmac_f32_e32 v199, v195, v197
	v_fma_f32 v196, -v196, v199, v198
	v_div_fmas_f32 v196, v196, v197, v199
	v_div_fixup_f32 v195, v196, v176, 1.0
	v_mul_f32_e32 v172, v172, v195
	v_mul_f32_e32 v173, v173, v195
	v_mul_f32_e32 v174, v174, v195
	v_mul_f32_e32 v175, v175, v195
	v_mul_f32_e32 v172, v172, v20
	v_mul_f32_e32 v173, v173, v21
	v_mul_f32_e32 v174, v174, v22
	v_mul_f32_e32 v175, v175, v23
	v_lshlrev_b32_e32 v190, 16, v136
	v_and_b32_e32 v191, 0xffff0000, v136
	v_lshlrev_b32_e32 v192, 16, v137
	v_and_b32_e32 v193, 0xffff0000, v137
	v_mul_f32_e32 v190, 0xbfb8aa3b, v190
	v_mul_f32_e32 v191, 0xbfb8aa3b, v191
	v_mul_f32_e32 v192, 0xbfb8aa3b, v192
	v_mul_f32_e32 v193, 0xbfb8aa3b, v193
	v_exp_f32_e32 v190, v190
	v_exp_f32_e32 v191, v191
	v_exp_f32_e32 v192, v192
	v_exp_f32_e32 v193, v193
	v_add_f32_e32 v190, 1.0, v190
	v_add_f32_e32 v191, 1.0, v191
	v_add_f32_e32 v192, 1.0, v192
	v_add_f32_e32 v193, 1.0, v193
	v_rcp_f32_e32 v190, v190
	v_rcp_f32_e32 v191, v191
	v_rcp_f32_e32 v192, v192
	v_rcp_f32_e32 v193, v193
	v_mul_f32_e32 v172, v190, v172
	v_mul_f32_e32 v173, v191, v173
	v_mul_f32_e32 v174, v192, v174
	v_mul_f32_e32 v175, v193, v175
	v_cvt_pk_bf16_f32 v194, v172, v173
	v_cvt_pk_bf16_f32 v195, v174, v175
	global_store_dwordx2 v33, v[194:195], s[38:39]
	v_add_u32_e32 v33, 0x100000, v33
	v_fmamk_f32 v182, v182, 0x3b800000, v214
	v_cmp_gt_f32_e32 vcc, s66, v182
	v_mul_f32_e32 v190, 0x4f800000, v182
	s_nop 0
	v_cndmask_b32_e32 v182, v182, v190, vcc
	v_sqrt_f32_e32 v190, v182
	s_nop 0
	v_add_u32_e32 v191, -1, v190
	v_fma_f32 v192, -v191, v190, v182
	v_cmp_ge_f32_e64 s[40:41], 0, v192
	v_add_u32_e32 v192, 1, v190
	s_nop 0
	v_cndmask_b32_e64 v191, v190, v191, s[40:41]
	v_fma_f32 v190, -v192, v190, v182
	v_cmp_lt_f32_e64 s[40:41], 0, v190
	s_nop 1
	v_cndmask_b32_e64 v190, v191, v192, s[40:41]
	v_mul_f32_e32 v191, 0x37800000, v190
	v_cndmask_b32_e32 v190, v190, v191, vcc
	v_cmp_class_f32_e32 vcc, v182, v215
	s_nop 1
	v_cndmask_b32_e32 v182, v190, v182, vcc
	v_div_scale_f32 v196, s[52:53], v182, v182, 1.0
	v_rcp_f32_e32 v197, v196
	s_nop 0
	v_fma_f32 v198, -v196, v197, 1.0
	v_fmac_f32_e32 v197, v198, v197
	v_div_scale_f32 v198, vcc, 1.0, v182, 1.0
	v_mul_f32_e32 v199, v198, v197
	v_fma_f32 v195, -v196, v199, v198
; __device__ __forceinline__ unsigned pk2(float lo, float hi) { f32x2_t v = {lo, hi}; bf16x2_t b = __builtin_convertvector(v, bf16x2_t); return __builtin_bit_cast(unsigned, b); }
; __device__ __forceinline__ float sigmoidf_(float x) { return __builtin_amdgcn_rcpf(1.0f + __expf(-x)); }
; __global__ void __launch_bounds__(NTHREADS, 2) fwd_megakernel(Params P) {
;     ...
;                 const float rsn = 1.0f / sqrtf(ss * (1.0f / 256.0f) + NORM_EPS);
;                 const f32x4 wn = *(const f32x4*)(q_mnw + l * 1024 + h * 256 + 4 * lane);
;                 u32x2 ow;
;                 ow.x = pk2(x[0] * rsn * wn[0] * sigmoidf_(bflo(mo[q].x)), x[1] * rsn * wn[1] * sigmoidf_(bfhi(mo[q].x)));
;                 ow.y = pk2(x[2] * rsn * wn[2] * sigmoidf_(bflo(mo[q].y)), x[3] * rsn * wn[3] * sigmoidf_(bfhi(mo[q].y)));
;                 if (ok[q]) *(u32x2*)(q_hcat + (size_t)row * 1024 + h * 256 + 4 * lane) = ow;
	v_fmac_f32_e32 v199, v195, v197
	v_fma_f32 v196, -v196, v199, v198
	v_div_fmas_f32 v196, v196, v197, v199
	v_div_fixup_f32 v195, v196, v182, 1.0
	v_mul_f32_e32 v178, v178, v195
	v_mul_f32_e32 v179, v179, v195
	v_mul_f32_e32 v180, v180, v195
	v_mul_f32_e32 v181, v181, v195
	v_mul_f32_e32 v178, v178, v20
	v_mul_f32_e32 v179, v179, v21
	v_mul_f32_e32 v180, v180, v22
	v_mul_f32_e32 v181, v181, v23
	v_lshlrev_b32_e32 v190, 16, v150
	v_and_b32_e32 v191, 0xffff0000, v150
	v_lshlrev_b32_e32 v192, 16, v151
	v_and_b32_e32 v193, 0xffff0000, v151
	v_mul_f32_e32 v190, 0xbfb8aa3b, v190
	v_mul_f32_e32 v191, 0xbfb8aa3b, v191
	v_mul_f32_e32 v192, 0xbfb8aa3b, v192
	v_mul_f32_e32 v193, 0xbfb8aa3b, v193
	v_exp_f32_e32 v190, v190
	v_exp_f32_e32 v191, v191
	v_exp_f32_e32 v192, v192
	v_exp_f32_e32 v193, v193
	v_add_f32_e32 v190, 1.0, v190
	v_add_f32_e32 v191, 1.0, v191
	v_add_f32_e32 v192, 1.0, v192
	v_add_f32_e32 v193, 1.0, v193
	v_rcp_f32_e32 v190, v190
	v_rcp_f32_e32 v191, v191
	v_rcp_f32_e32 v192, v192
	v_rcp_f32_e32 v193, v193
	v_mul_f32_e32 v178, v190, v178
	v_mul_f32_e32 v179, v191, v179
	v_mul_f32_e32 v180, v192, v180
	v_mul_f32_e32 v181, v193, v181
	v_cvt_pk_bf16_f32 v194, v178, v179
	v_cvt_pk_bf16_f32 v195, v180, v181
	global_store_dwordx2 v33, v[194:195], s[38:39]
	v_add_u32_e32 v33, 0x100000, v33
	v_fmamk_f32 v188, v188, 0x3b800000, v214
	v_cmp_gt_f32_e32 vcc, s66, v188
	v_mul_f32_e32 v190, 0x4f800000, v188
	s_nop 0
	v_cndmask_b32_e32 v188, v188, v190, vcc
	v_sqrt_f32_e32 v190, v188
	s_nop 0
	v_add_u32_e32 v191, -1, v190
	v_fma_f32 v192, -v191, v190, v188
	v_cmp_ge_f32_e64 s[40:41], 0, v192
	v_add_u32_e32 v192, 1, v190
	s_nop 0
	v_cndmask_b32_e64 v191, v190, v191, s[40:41]
	v_fma_f32 v190, -v192, v190, v188
	v_cmp_lt_f32_e64 s[40:41], 0, v190
	s_nop 1
	v_cndmask_b32_e64 v190, v191, v192, s[40:41]
	v_mul_f32_e32 v191, 0x37800000, v190
	v_cndmask_b32_e32 v190, v190, v191, vcc
	v_cmp_class_f32_e32 vcc, v188, v215
	s_nop 1
	v_cndmask_b32_e32 v188, v190, v188, vcc
	v_div_scale_f32 v196, s[52:53], v188, v188, 1.0
	v_rcp_f32_e32 v197, v196
	s_nop 0
	v_fma_f32 v198, -v196, v197, 1.0
	v_fmac_f32_e32 v197, v198, v197
	v_div_scale_f32 v198, vcc, 1.0, v188, 1.0
	v_mul_f32_e32 v199, v198, v197
	v_fma_f32 v195, -v196, v199, v198
	v_fmac_f32_e32 v199, v195, v197
	v_fma_f32 v196, -v196, v199, v198
	v_div_fmas_f32 v196, v196, v197, v199
	v_div_fixup_f32 v195, v196, v188, 1.0
	v_mul_f32_e32 v184, v184, v195
	v_mul_f32_e32 v185, v185, v195
	v_mul_f32_e32 v186, v186, v195
	v_mul_f32_e32 v187, v187, v195
	v_mul_f32_e32 v184, v184, v20
	v_mul_f32_e32 v185, v185, v21
	v_mul_f32_e32 v186, v186, v22
	v_mul_f32_e32 v187, v187, v23
	v_lshlrev_b32_e32 v190, 16, v164
	v_and_b32_e32 v191, 0xffff0000, v164
	v_lshlrev_b32_e32 v192, 16, v165
	v_and_b32_e32 v193, 0xffff0000, v165
	v_mul_f32_e32 v190, 0xbfb8aa3b, v190
	v_mul_f32_e32 v191, 0xbfb8aa3b, v191
	v_mul_f32_e32 v192, 0xbfb8aa3b, v192
	v_mul_f32_e32 v193, 0xbfb8aa3b, v193
	v_exp_f32_e32 v190, v190
	v_exp_f32_e32 v191, v191
	v_exp_f32_e32 v192, v192
	v_exp_f32_e32 v193, v193
	v_add_f32_e32 v190, 1.0, v190
	v_add_f32_e32 v191, 1.0, v191
	v_add_f32_e32 v192, 1.0, v192
	v_add_f32_e32 v193, 1.0, v193
	v_rcp_f32_e32 v190, v190
	v_rcp_f32_e32 v191, v191
	v_rcp_f32_e32 v192, v192
	v_rcp_f32_e32 v193, v193
	v_mul_f32_e32 v184, v190, v184
	v_mul_f32_e32 v185, v191, v185
	v_mul_f32_e32 v186, v192, v186
	v_mul_f32_e32 v187, v193, v187
	v_cvt_pk_bf16_f32 v194, v184, v185
	v_cvt_pk_bf16_f32 v195, v186, v187
	global_store_dwordx2 v33, v[194:195], s[38:39]
	v_add_u32_e32 v33, 0x100000, v33
	s_mov_b64 s[52:53], 0
	s_branch .LBB0_546

; __global__ void __launch_bounds__(NTHREADS, 2) fwd_megakernel(Params P) {
;     ...
;         for (int it0 = bid * NWAVES + wid; it0 < T * 4; it0 += 2 * step) {
;             f32x4 v[2]; u32x2 gg[2]; bool ok[2];
; #pragma unroll
;             for (int q = 0; q < 2; ++q) {
;                 const int it = it0 + q * step; ok[q] = it < T * 4; const int itc = ok[q] ? it : it0;
;                 const int row = itc >> 2, hp = itc & 3; const size_t o = (size_t)row * 1024 + hp * 256 + 4 * lane;
;                 const u32x2 p0 = *(const u32x2*)(q_hp + o), p1 = *(const u32x2*)(q_hp + (size_t)T * 1024 + o);
;                 v[q][0] = bflo(p0.x) + bflo(p1.x); v[q][1] = bfhi(p0.x) + bfhi(p1.x); v[q][2] = bflo(p0.y) + bflo(p1.y); v[q][3] = bfhi(p0.y) + bfhi(p1.y);
;                 gg[q] = *(const u32x2*)(q_proj + (size_t)row * NP + C_GG + hp * 256 + 4 * lane);
;             }
.LBB0_546:
	s_or_b64 exec, exec, s[52:53]
	s_add_u32 s48, s42, 0x2d000000
	s_addc_u32 s49, s43, 0
	v_lshlrev_b32_e32 v2, 2, v6
	v_mov_b32_e32 v3, v0
	v_mov_b32_e32 v9, v0
	s_add_u32 s42, s42, 0x2e000000
	v_lshl_add_u64 v[2:3], s[44:45], 0, v[2:3]
	v_lshl_add_u64 v[4:5], s[46:47], 0, v[8:9]
	s_mov_b64 s[4:5], 0x2c000000
	s_addc_u32 s43, s43, 0
	v_lshl_add_u64 v[10:11], v[4:5], 0, s[4:5]
	v_lshl_add_u64 v[12:13], s[36:37], 2, v[2:3]
	s_mov_b64 s[44:45], 0
	s_cmpk_lg_i32 s78, 0x100
	s_cbranch_scc1 .LBB0_548
	v_readfirstlane_b32 s4, v1
	v_mov_b32_e32 v19, 0
	s_and_b32 s5, s4, 3
	s_lshr_b32 s4, s4, 2
	s_lshl_b32 s6, s4, 11
	s_lshl_b32 s7, s5, 9
	s_add_u32 s6, s6, s7
	v_add_u32_e32 v15, s6, v8
	v_mov_b32_e32 v33, v15
	s_mul_i32 s8, s4, s25
	s_add_u32 s8, s8, s7
	s_add_u32 s8, s8, 0x5000
	v_add_u32_e32 v17, s8, v8
	s_lshl_b32 s9, s5, 10
	v_mov_b32_e32 v18, s9
	v_lshl_add_u64 v[18:19], v[12:13], 0, v[18:19]
	global_load_dwordx4 v[20:23], v[18:19], off
	s_add_u32 s38, s46, 0x2c000000
	s_addc_u32 s39, s47, 0
	global_load_dwordx2 v[54:55], v15, s[48:49]
	global_load_dwordx2 v[56:57], v15, s[42:43]
	global_load_dwordx2 v[58:59], v17, s[34:35]
	v_add_u32_e32 v15, 0x100000, v15
	v_add_u32_e32 v17, 0x1100000, v17
	global_load_dwordx2 v[60:61], v15, s[48:49]
	global_load_dwordx2 v[62:63], v15, s[42:43]
	global_load_dwordx2 v[64:65], v17, s[34:35]
	v_add_u32_e32 v15, 0x100000, v15
	v_add_u32_e32 v17, 0x1100000, v17
	global_load_dwordx2 v[66:67], v15, s[48:49]
	global_load_dwordx2 v[68:69], v15, s[42:43]
	global_load_dwordx2 v[70:71], v17, s[34:35]
	v_add_u32_e32 v15, 0x100000, v15
	v_add_u32_e32 v17, 0x1100000, v17
	global_load_dwordx2 v[72:73], v15, s[48:49]
	global_load_dwordx2 v[74:75], v15, s[42:43]
	global_load_dwordx2 v[76:77], v17, s[34:35]
	v_add_u32_e32 v15, 0x100000, v15
	v_add_u32_e32 v17, 0x1100000, v17
	global_load_dwordx2 v[78:79], v15, s[48:49]
	global_load_dwordx2 v[80:81], v15, s[42:43]
	global_load_dwordx2 v[82:83], v17, s[34:35]
	v_add_u32_e32 v15, 0x100000, v15
	v_add_u32_e32 v17, 0x1100000, v17
	global_load_dwordx2 v[84:85], v15, s[48:49]
	global_load_dwordx2 v[86:87], v15, s[42:43]
	global_load_dwordx2 v[88:89], v17, s[34:35]
	v_add_u32_e32 v15, 0x100000, v15
	v_add_u32_e32 v17, 0x1100000, v17
	global_load_dwordx2 v[90:91], v15, s[48:49]
	global_load_dwordx2 v[92:93], v15, s[42:43]
	global_load_dwordx2 v[94:95], v17, s[34:35]
	v_add_u32_e32 v15, 0x100000, v15
	v_add_u32_e32 v17, 0x1100000, v17
	global_load_dwordx2 v[96:97], v15, s[48:49]
	global_load_dwordx2 v[98:99], v15, s[42:43]
	global_load_dwordx2 v[100:101], v17, s[34:35]
	v_add_u32_e32 v15, 0x100000, v15
	v_add_u32_e32 v17, 0x1100000, v17
	global_load_dwordx2 v[102:103], v15, s[48:49]
	global_load_dwordx2 v[104:105], v15, s[42:43]
	global_load_dwordx2 v[106:107], v17, s[34:35]
	v_add_u32_e32 v15, 0x100000, v15
	v_add_u32_e32 v17, 0x1100000, v17
	global_load_dwordx2 v[108:109], v15, s[48:49]
	global_load_dwordx2 v[110:111], v15, s[42:43]
	global_load_dwordx2 v[112:113], v17, s[34:35]
	v_add_u32_e32 v15, 0x100000, v15
	v_add_u32_e32 v17, 0x1100000, v17
	global_load_dwordx2 v[114:115], v15, s[48:49]
	global_load_dwordx2 v[116:117], v15, s[42:43]
	global_load_dwordx2 v[118:119], v17, s[34:35]
	v_add_u32_e32 v15, 0x100000, v15
	v_add_u32_e32 v17, 0x1100000, v17
	global_load_dwordx2 v[120:121], v15, s[48:49]
	global_load_dwordx2 v[122:123], v15, s[42:43]
	global_load_dwordx2 v[124:125], v17, s[34:35]
	v_add_u32_e32 v15, 0x100000, v15
	v_add_u32_e32 v17, 0x1100000, v17
	global_load_dwordx2 v[126:127], v15, s[48:49]
	global_load_dwordx2 v[128:129], v15, s[42:43]
	global_load_dwordx2 v[130:131], v17, s[34:35]
	v_add_u32_e32 v15, 0x100000, v15
	v_add_u32_e32 v17, 0x1100000, v17
	global_load_dwordx2 v[132:133], v15, s[48:49]
	global_load_dwordx2 v[134:135], v15, s[42:43]
	global_load_dwordx2 v[136:137], v17, s[34:35]
	v_add_u32_e32 v15, 0x100000, v15
	v_add_u32_e32 v17, 0x1100000, v17
	global_load_dwordx2 v[138:139], v15, s[48:49]
	global_load_dwordx2 v[140:141], v15, s[42:43]
	global_load_dwordx2 v[142:143], v17, s[34:35]
	v_add_u32_e32 v15, 0x100000, v15
	v_add_u32_e32 v17, 0x1100000, v17
	global_load_dwordx2 v[144:145], v15, s[48:49]
	global_load_dwordx2 v[146:147], v15, s[42:43]
	global_load_dwordx2 v[148:149], v17, s[34:35]
	v_add_u32_e32 v15, 0x100000, v15
	v_add_u32_e32 v17, 0x1100000, v17
	s_waitcnt vmcnt(24)
; __global__ void __launch_bounds__(NTHREADS, 2) fwd_megakernel(Params P) {
;     ...
;                 const int it = it0 + q * step; ok[q] = it < T * 4; const int itc = ok[q] ? it : it0;
;                 const int row = itc >> 2, hp = itc & 3; const size_t o = (size_t)row * 1024 + hp * 256 + 4 * lane;
;                 const u32x2 p0 = *(const u32x2*)(q_hp + o), p1 = *(const u32x2*)(q_hp + (size_t)T * 1024 + o);
;                 v[q][0] = bflo(p0.x) + bflo(p1.x); v[q][1] = bfhi(p0.x) + bfhi(p1.x); v[q][2] = bflo(p0.y) + bflo(p1.y); v[q][3] = bfhi(p0.y) + bfhi(p1.y);
;                 gg[q] = *(const u32x2*)(q_proj + (size_t)row * NP + C_GG + hp * 256 + 4 * lane);
;             }
; #pragma unroll
;             for (int q = 0; q < 2; ++q) {
;                 const int it = it0 + q * step; const int itc = ok[q] ? it : it0; const int row = itc >> 2, hp = itc & 3; const size_t o = (size_t)row * 1024 + hp * 256 + 4 * lane;
;                 const f32x4 x = v[q];
;                 float ss = (x[0] * x[0] + x[1] * x[1]) + (x[2] * x[2] + x[3] * x[3]);
; #pragma unroll
;                 for (int off = 1; off < 32; off <<= 1) ss += __shfl_xor(ss, off);
	v_lshlrev_b32_e32 v150, 16, v54
	v_and_b32_e32 v151, 0xffff0000, v54
	v_lshlrev_b32_e32 v152, 16, v55
	v_and_b32_e32 v153, 0xffff0000, v55
	v_lshlrev_b32_e32 v24, 16, v56
	v_and_b32_e32 v25, 0xffff0000, v56
	v_lshlrev_b32_e32 v26, 16, v57
	v_and_b32_e32 v27, 0xffff0000, v57
	v_pk_add_f32 v[150:151], v[150:151], v[24:25]
	v_pk_add_f32 v[152:153], v[152:153], v[26:27]
	v_mul_f32_e32 v25, v151, v151
	v_mul_f32_e32 v27, v153, v153
	v_fma_f32 v24, v150, v150, v25
	v_fma_f32 v26, v152, v152, v27
	v_add_f32_e32 v154, v24, v26
	v_lshlrev_b32_e32 v156, 16, v60
	v_and_b32_e32 v157, 0xffff0000, v60
	v_lshlrev_b32_e32 v158, 16, v61
	v_and_b32_e32 v159, 0xffff0000, v61
	v_lshlrev_b32_e32 v24, 16, v62
	v_and_b32_e32 v25, 0xffff0000, v62
	v_lshlrev_b32_e32 v26, 16, v63
	v_and_b32_e32 v27, 0xffff0000, v63
	v_pk_add_f32 v[156:157], v[156:157], v[24:25]
	v_pk_add_f32 v[158:159], v[158:159], v[26:27]
	v_mul_f32_e32 v24, v156, v156
	v_mul_f32_e32 v25, v157, v157
	v_mul_f32_e32 v26, v158, v158
	v_mul_f32_e32 v27, v159, v159
	v_add_f32_e32 v24, v24, v25
	v_add_f32_e32 v26, v26, v27
	v_add_f32_e32 v160, v24, v26
	v_lshlrev_b32_e32 v162, 16, v66
	v_and_b32_e32 v163, 0xffff0000, v66
	v_lshlrev_b32_e32 v164, 16, v67
	v_and_b32_e32 v165, 0xffff0000, v67
	v_lshlrev_b32_e32 v24, 16, v68
	v_and_b32_e32 v25, 0xffff0000, v68
	v_lshlrev_b32_e32 v26, 16, v69
	v_and_b32_e32 v27, 0xffff0000, v69
	v_pk_add_f32 v[162:163], v[162:163], v[24:25]
	v_pk_add_f32 v[164:165], v[164:165], v[26:27]
	v_mul_f32_e32 v25, v163, v163
	v_mul_f32_e32 v27, v165, v165
	v_fma_f32 v24, v162, v162, v25
	v_fma_f32 v26, v164, v164, v27
	v_add_f32_e32 v166, v24, v26
	v_lshlrev_b32_e32 v168, 16, v72
	v_and_b32_e32 v169, 0xffff0000, v72
	v_lshlrev_b32_e32 v170, 16, v73
	v_and_b32_e32 v171, 0xffff0000, v73
	v_lshlrev_b32_e32 v24, 16, v74
	v_and_b32_e32 v25, 0xffff0000, v74
	v_lshlrev_b32_e32 v26, 16, v75
	v_and_b32_e32 v27, 0xffff0000, v75
	v_pk_add_f32 v[168:169], v[168:169], v[24:25]
	v_pk_add_f32 v[170:171], v[170:171], v[26:27]
	v_mul_f32_e32 v24, v168, v168
	v_mul_f32_e32 v25, v169, v169
	v_mul_f32_e32 v26, v170, v170
	v_mul_f32_e32 v27, v171, v171
	v_add_f32_e32 v24, v24, v25
	v_add_f32_e32 v26, v26, v27
	v_add_f32_e32 v172, v24, v26
	v_lshlrev_b32_e32 v174, 16, v78
	v_and_b32_e32 v175, 0xffff0000, v78
	v_lshlrev_b32_e32 v176, 16, v79
	v_and_b32_e32 v177, 0xffff0000, v79
	v_lshlrev_b32_e32 v24, 16, v80
	v_and_b32_e32 v25, 0xffff0000, v80
	v_lshlrev_b32_e32 v26, 16, v81
	v_and_b32_e32 v27, 0xffff0000, v81
	v_pk_add_f32 v[174:175], v[174:175], v[24:25]
	v_pk_add_f32 v[176:177], v[176:177], v[26:27]
	v_mul_f32_e32 v25, v175, v175
	v_mul_f32_e32 v27, v177, v177
	v_fma_f32 v24, v174, v174, v25
	v_fma_f32 v26, v176, v176, v27
	v_add_f32_e32 v178, v24, v26
	v_lshlrev_b32_e32 v180, 16, v84
	v_and_b32_e32 v181, 0xffff0000, v84
	v_lshlrev_b32_e32 v182, 16, v85
	v_and_b32_e32 v183, 0xffff0000, v85
	v_lshlrev_b32_e32 v24, 16, v86
	v_and_b32_e32 v25, 0xffff0000, v86
	v_lshlrev_b32_e32 v26, 16, v87
	v_and_b32_e32 v27, 0xffff0000, v87
	v_pk_add_f32 v[180:181], v[180:181], v[24:25]
	v_pk_add_f32 v[182:183], v[182:183], v[26:27]
	v_mul_f32_e32 v24, v180, v180
	v_mul_f32_e32 v25, v181, v181
	v_mul_f32_e32 v26, v182, v182
	v_mul_f32_e32 v27, v183, v183
	v_add_f32_e32 v24, v24, v25
	v_add_f32_e32 v26, v26, v27
	v_add_f32_e32 v184, v24, v26
	v_lshlrev_b32_e32 v186, 16, v90
	v_and_b32_e32 v187, 0xffff0000, v90
	v_lshlrev_b32_e32 v188, 16, v91
	v_and_b32_e32 v189, 0xffff0000, v91
	v_lshlrev_b32_e32 v24, 16, v92
	v_and_b32_e32 v25, 0xffff0000, v92
	v_lshlrev_b32_e32 v26, 16, v93
	v_and_b32_e32 v27, 0xffff0000, v93
	v_pk_add_f32 v[186:187], v[186:187], v[24:25]
	v_pk_add_f32 v[188:189], v[188:189], v[26:27]
	v_mul_f32_e32 v25, v187, v187
	v_mul_f32_e32 v27, v189, v189
	v_fma_f32 v24, v186, v186, v25
	v_fma_f32 v26, v188, v188, v27
	v_add_f32_e32 v190, v24, v26
	v_lshlrev_b32_e32 v192, 16, v96
	v_and_b32_e32 v193, 0xffff0000, v96
	v_lshlrev_b32_e32 v194, 16, v97
	v_and_b32_e32 v195, 0xffff0000, v97
	v_lshlrev_b32_e32 v24, 16, v98
	v_and_b32_e32 v25, 0xffff0000, v98
	v_lshlrev_b32_e32 v26, 16, v99
	v_and_b32_e32 v27, 0xffff0000, v99
	v_pk_add_f32 v[192:193], v[192:193], v[24:25]
	v_pk_add_f32 v[194:195], v[194:195], v[26:27]
	v_mul_f32_e32 v24, v192, v192
	v_mul_f32_e32 v25, v193, v193
	v_mul_f32_e32 v26, v194, v194
	v_mul_f32_e32 v27, v195, v195
	v_add_f32_e32 v24, v24, v25
	v_add_f32_e32 v26, v26, v27
	v_add_f32_e32 v196, v24, v26
	s_nop 1
	v_mov_b32_dpp v155, v154 quad_perm:[1,0,3,2] row_mask:0xf bank_mask:0xf
	v_mov_b32_dpp v161, v160 quad_perm:[1,0,3,2] row_mask:0xf bank_mask:0xf
	v_mov_b32_dpp v167, v166 quad_perm:[1,0,3,2] row_mask:0xf bank_mask:0xf
	v_mov_b32_dpp v173, v172 quad_perm:[1,0,3,2] row_mask:0xf bank_mask:0xf
	v_mov_b32_dpp v179, v178 quad_perm:[1,0,3,2] row_mask:0xf bank_mask:0xf
	v_mov_b32_dpp v185, v184 quad_perm:[1,0,3,2] row_mask:0xf bank_mask:0xf
	v_mov_b32_dpp v191, v190 quad_perm:[1,0,3,2] row_mask:0xf bank_mask:0xf
	v_mov_b32_dpp v197, v196 quad_perm:[1,0,3,2] row_mask:0xf bank_mask:0xf
	v_add_f32_e32 v154, v154, v155
	v_add_f32_e32 v160, v160, v161
	v_add_f32_e32 v166, v166, v167
	v_add_f32_e32 v172, v172, v173
	v_add_f32_e32 v178, v178, v179
	v_add_f32_e32 v184, v184, v185
	v_add_f32_e32 v190, v190, v191
	v_add_f32_e32 v196, v196, v197
	s_nop 1
	v_mov_b32_dpp v155, v154 quad_perm:[2,3,0,1] row_mask:0xf bank_mask:0xf
	v_mov_b32_dpp v161, v160 quad_perm:[2,3,0,1] row_mask:0xf bank_mask:0xf
	v_mov_b32_dpp v167, v166 quad_perm:[2,3,0,1] row_mask:0xf bank_mask:0xf
	v_mov_b32_dpp v173, v172 quad_perm:[2,3,0,1] row_mask:0xf bank_mask:0xf
	v_mov_b32_dpp v179, v178 quad_perm:[2,3,0,1] row_mask:0xf bank_mask:0xf
; __device__ __forceinline__ unsigned pk2(float lo, float hi) { f32x2_t v = {lo, hi}; bf16x2_t b = __builtin_convertvector(v, bf16x2_t); return __builtin_bit_cast(unsigned, b); }
; __device__ __forceinline__ float siluf_(float x) { return x * __builtin_amdgcn_rcpf(1.0f + __expf(-x)); }
; __global__ void __launch_bounds__(NTHREADS, 2) fwd_megakernel(Params P) {
;     ...
;             for (int q = 0; q < 2; ++q) {
;                 const int it = it0 + q * step; const int itc = ok[q] ? it : it0; const int row = itc >> 2, hp = itc & 3; const size_t o = (size_t)row * 1024 + hp * 256 + 4 * lane;
;                 const f32x4 x = v[q];
;                 float ss = (x[0] * x[0] + x[1] * x[1]) + (x[2] * x[2] + x[3] * x[3]);
; #pragma unroll
;                 for (int off = 1; off < 32; off <<= 1) ss += __shfl_xor(ss, off);
;                 const float rsn = 1.0f / sqrtf(ss * (1.0f / 128.0f) + NORM_EPS);
;                 const f32x4 wn = *(const f32x4*)(q_gnw + l * 1024 + hp * 256 + 4 * lane);
;                 u32x2 ow;
;                 ow.x = pk2(x[0] * rsn * wn[0] * siluf_(bflo(gg[q].x)), x[1] * rsn * wn[1] * siluf_(bfhi(gg[q].x)));
;                 ow.y = pk2(x[2] * rsn * wn[2] * siluf_(bflo(gg[q].y)), x[3] * rsn * wn[3] * siluf_(bfhi(gg[q].y)));
;                 if (ok[q]) *(u32x2*)(q_hcat + (size_t)2 * T * 1024 + o) = ow;
	v_mov_b32_dpp v185, v184 quad_perm:[2,3,0,1] row_mask:0xf bank_mask:0xf
	v_mov_b32_dpp v191, v190 quad_perm:[2,3,0,1] row_mask:0xf bank_mask:0xf
	v_mov_b32_dpp v197, v196 quad_perm:[2,3,0,1] row_mask:0xf bank_mask:0xf
	v_add_f32_e32 v154, v154, v155
	v_add_f32_e32 v160, v160, v161
	v_add_f32_e32 v166, v166, v167
	v_add_f32_e32 v172, v172, v173
	v_add_f32_e32 v178, v178, v179
	v_add_f32_e32 v184, v184, v185
	v_add_f32_e32 v190, v190, v191
	v_add_f32_e32 v196, v196, v197
	s_nop 1
	v_mov_b32_dpp v155, v154 row_half_mirror row_mask:0xf bank_mask:0xf
	v_mov_b32_dpp v161, v160 row_half_mirror row_mask:0xf bank_mask:0xf
	v_mov_b32_dpp v167, v166 row_half_mirror row_mask:0xf bank_mask:0xf
	v_mov_b32_dpp v173, v172 row_half_mirror row_mask:0xf bank_mask:0xf
	v_mov_b32_dpp v179, v178 row_half_mirror row_mask:0xf bank_mask:0xf
	v_mov_b32_dpp v185, v184 row_half_mirror row_mask:0xf bank_mask:0xf
	v_mov_b32_dpp v191, v190 row_half_mirror row_mask:0xf bank_mask:0xf
	v_mov_b32_dpp v197, v196 row_half_mirror row_mask:0xf bank_mask:0xf
	v_add_f32_e32 v154, v154, v155
	v_add_f32_e32 v160, v160, v161
	v_add_f32_e32 v166, v166, v167
	v_add_f32_e32 v172, v172, v173
	v_add_f32_e32 v178, v178, v179
	v_add_f32_e32 v184, v184, v185
	v_add_f32_e32 v190, v190, v191
	v_add_f32_e32 v196, v196, v197
	s_nop 1
	v_mov_b32_dpp v155, v154 row_mirror row_mask:0xf bank_mask:0xf
	v_mov_b32_dpp v161, v160 row_mirror row_mask:0xf bank_mask:0xf
	v_mov_b32_dpp v167, v166 row_mirror row_mask:0xf bank_mask:0xf
	v_mov_b32_dpp v173, v172 row_mirror row_mask:0xf bank_mask:0xf
	v_mov_b32_dpp v179, v178 row_mirror row_mask:0xf bank_mask:0xf
	v_mov_b32_dpp v185, v184 row_mirror row_mask:0xf bank_mask:0xf
	v_mov_b32_dpp v191, v190 row_mirror row_mask:0xf bank_mask:0xf
	v_mov_b32_dpp v197, v196 row_mirror row_mask:0xf bank_mask:0xf
	v_add_f32_e32 v154, v154, v155
	v_add_f32_e32 v160, v160, v161
	v_add_f32_e32 v166, v166, v167
	v_add_f32_e32 v172, v172, v173
	v_add_f32_e32 v178, v178, v179
	v_add_f32_e32 v184, v184, v185
	v_add_f32_e32 v190, v190, v191
	v_add_f32_e32 v196, v196, v197
	v_mov_b32_e32 v155, v154
	v_mov_b32_e32 v161, v160
	v_mov_b32_e32 v167, v166
	v_mov_b32_e32 v173, v172
	v_mov_b32_e32 v179, v178
	v_mov_b32_e32 v185, v184
	v_mov_b32_e32 v191, v190
	v_mov_b32_e32 v197, v196
	s_nop 1
	v_permlane16_swap_b32 v155, v154
	v_permlane16_swap_b32 v161, v160
	v_permlane16_swap_b32 v167, v166
	v_permlane16_swap_b32 v173, v172
	v_permlane16_swap_b32 v179, v178
	v_permlane16_swap_b32 v185, v184
	v_permlane16_swap_b32 v191, v190
	v_permlane16_swap_b32 v197, v196
	v_add_f32_e32 v154, v154, v155
	v_add_f32_e32 v160, v160, v161
	v_add_f32_e32 v166, v166, v167
	v_add_f32_e32 v172, v172, v173
	v_add_f32_e32 v178, v178, v179
	v_add_f32_e32 v184, v184, v185
	v_add_f32_e32 v190, v190, v191
	v_add_f32_e32 v196, v196, v197
	v_fmamk_f32 v154, v154, 0x3c000000, v214
	v_cmp_gt_f32_e32 vcc, s66, v154
	v_mul_f32_e32 v24, 0x4f800000, v154
	s_nop 0
	v_cndmask_b32_e32 v154, v154, v24, vcc
	v_sqrt_f32_e32 v24, v154
	s_nop 0
	v_add_u32_e32 v25, -1, v24
	v_fma_f32 v26, -v25, v24, v154
	v_cmp_ge_f32_e64 s[40:41], 0, v26
	v_add_u32_e32 v26, 1, v24
	s_nop 0
	v_cndmask_b32_e64 v25, v24, v25, s[40:41]
	v_fma_f32 v24, -v26, v24, v154
	v_cmp_lt_f32_e64 s[40:41], 0, v24
	s_nop 1
	v_cndmask_b32_e64 v24, v25, v26, s[40:41]
	v_mul_f32_e32 v25, 0x37800000, v24
	v_cndmask_b32_e32 v24, v24, v25, vcc
	v_cmp_class_f32_e32 vcc, v154, v215
	s_nop 1
	v_cndmask_b32_e32 v154, v24, v154, vcc
	v_div_scale_f32 v30, s[52:53], v154, v154, 1.0
	v_rcp_f32_e32 v31, v30
	s_nop 0
	v_fma_f32 v198, -v30, v31, 1.0
	v_fmac_f32_e32 v31, v198, v31
	v_div_scale_f32 v198, vcc, 1.0, v154, 1.0
	v_mul_f32_e32 v199, v198, v31
	v_fma_f32 v29, -v30, v199, v198
	v_fmac_f32_e32 v199, v29, v31
	v_fma_f32 v30, -v30, v199, v198
	v_div_fmas_f32 v30, v30, v31, v199
	v_div_fixup_f32 v29, v30, v154, 1.0
	v_mul_f32_e32 v150, v150, v29
	v_mul_f32_e32 v151, v151, v29
	v_mul_f32_e32 v152, v152, v29
	v_mul_f32_e32 v153, v153, v29
	v_mul_f32_e32 v150, v150, v20
	v_mul_f32_e32 v151, v151, v21
	v_mul_f32_e32 v152, v152, v22
	v_mul_f32_e32 v153, v153, v23
	v_lshlrev_b32_e32 v24, 16, v58
	v_and_b32_e32 v25, 0xffff0000, v58
	v_lshlrev_b32_e32 v26, 16, v59
	v_and_b32_e32 v27, 0xffff0000, v59
	v_mul_f32_e32 v30, 0xbfb8aa3b, v24
	v_mul_f32_e32 v31, 0xbfb8aa3b, v25
	v_mul_f32_e32 v198, 0xbfb8aa3b, v26
	v_mul_f32_e32 v199, 0xbfb8aa3b, v27
	v_exp_f32_e32 v30, v30
	v_exp_f32_e32 v31, v31
	v_exp_f32_e32 v198, v198
	v_exp_f32_e32 v199, v199
	v_add_f32_e32 v30, 1.0, v30
	v_add_f32_e32 v31, 1.0, v31
	v_add_f32_e32 v198, 1.0, v198
	v_add_f32_e32 v199, 1.0, v199
	v_rcp_f32_e32 v30, v30
	v_rcp_f32_e32 v31, v31
	v_rcp_f32_e32 v198, v198
	v_rcp_f32_e32 v199, v199
	v_mul_f32_e32 v24, v30, v24
	v_mul_f32_e32 v25, v31, v25
	v_mul_f32_e32 v26, v198, v26
	v_mul_f32_e32 v27, v199, v27
	v_mul_f32_e32 v150, v24, v150
	v_mul_f32_e32 v151, v25, v151
	v_mul_f32_e32 v152, v26, v152
	v_mul_f32_e32 v153, v27, v153
	v_cvt_pk_bf16_f32 v28, v150, v151
	v_cvt_pk_bf16_f32 v29, v152, v153
	global_store_dwordx2 v33, v[28:29], s[38:39]
	v_add_u32_e32 v33, 0x100000, v33
	v_fmamk_f32 v160, v160, 0x3c000000, v214
	v_cmp_gt_f32_e32 vcc, s66, v160
	v_mul_f32_e32 v24, 0x4f800000, v160
	s_nop 0
	v_cndmask_b32_e32 v160, v160, v24, vcc
	v_sqrt_f32_e32 v24, v160
	s_nop 0
	v_add_u32_e32 v25, -1, v24
	v_fma_f32 v26, -v25, v24, v160
	v_cmp_ge_f32_e64 s[40:41], 0, v26
	v_add_u32_e32 v26, 1, v24
	s_nop 0
	v_cndmask_b32_e64 v25, v24, v25, s[40:41]
	v_fma_f32 v24, -v26, v24, v160
	v_cmp_lt_f32_e64 s[40:41], 0, v24
	s_nop 1
	v_cndmask_b32_e64 v24, v25, v26, s[40:41]
	v_mul_f32_e32 v25, 0x37800000, v24
	v_cndmask_b32_e32 v24, v24, v25, vcc
; __device__ __forceinline__ unsigned pk2(float lo, float hi) { f32x2_t v = {lo, hi}; bf16x2_t b = __builtin_convertvector(v, bf16x2_t); return __builtin_bit_cast(unsigned, b); }
; __device__ __forceinline__ float siluf_(float x) { return x * __builtin_amdgcn_rcpf(1.0f + __expf(-x)); }
; __global__ void __launch_bounds__(NTHREADS, 2) fwd_megakernel(Params P) {
;     ...
;                 const float rsn = 1.0f / sqrtf(ss * (1.0f / 128.0f) + NORM_EPS);
;                 const f32x4 wn = *(const f32x4*)(q_gnw + l * 1024 + hp * 256 + 4 * lane);
;                 u32x2 ow;
;                 ow.x = pk2(x[0] * rsn * wn[0] * siluf_(bflo(gg[q].x)), x[1] * rsn * wn[1] * siluf_(bfhi(gg[q].x)));
;                 ow.y = pk2(x[2] * rsn * wn[2] * siluf_(bflo(gg[q].y)), x[3] * rsn * wn[3] * siluf_(bfhi(gg[q].y)));
;                 if (ok[q]) *(u32x2*)(q_hcat + (size_t)2 * T * 1024 + o) = ow;
	v_cmp_class_f32_e32 vcc, v160, v215
	s_nop 1
	v_cndmask_b32_e32 v160, v24, v160, vcc
	v_div_scale_f32 v30, s[52:53], v160, v160, 1.0
	v_rcp_f32_e32 v31, v30
	s_nop 0
	v_fma_f32 v198, -v30, v31, 1.0
	v_fmac_f32_e32 v31, v198, v31
	v_div_scale_f32 v198, vcc, 1.0, v160, 1.0
	v_mul_f32_e32 v199, v198, v31
	v_fma_f32 v29, -v30, v199, v198
	v_fmac_f32_e32 v199, v29, v31
	v_fma_f32 v30, -v30, v199, v198
	v_div_fmas_f32 v30, v30, v31, v199
	v_div_fixup_f32 v29, v30, v160, 1.0
	v_mul_f32_e32 v156, v156, v29
	v_mul_f32_e32 v157, v157, v29
	v_mul_f32_e32 v158, v158, v29
	v_mul_f32_e32 v159, v159, v29
	v_mul_f32_e32 v156, v156, v20
	v_mul_f32_e32 v157, v157, v21
	v_mul_f32_e32 v158, v158, v22
	v_mul_f32_e32 v159, v159, v23
	v_lshlrev_b32_e32 v24, 16, v64
	v_and_b32_e32 v25, 0xffff0000, v64
	v_lshlrev_b32_e32 v26, 16, v65
	v_and_b32_e32 v27, 0xffff0000, v65
	v_mul_f32_e32 v30, 0xbfb8aa3b, v24
	v_mul_f32_e32 v31, 0xbfb8aa3b, v25
	v_mul_f32_e32 v198, 0xbfb8aa3b, v26
	v_mul_f32_e32 v199, 0xbfb8aa3b, v27
	v_exp_f32_e32 v30, v30
	v_exp_f32_e32 v31, v31
	v_exp_f32_e32 v198, v198
	v_exp_f32_e32 v199, v199
	v_add_f32_e32 v30, 1.0, v30
	v_add_f32_e32 v31, 1.0, v31
	v_add_f32_e32 v198, 1.0, v198
	v_add_f32_e32 v199, 1.0, v199
	v_rcp_f32_e32 v30, v30
	v_rcp_f32_e32 v31, v31
	v_rcp_f32_e32 v198, v198
	v_rcp_f32_e32 v199, v199
	v_mul_f32_e32 v24, v30, v24
	v_mul_f32_e32 v25, v31, v25
	v_mul_f32_e32 v26, v198, v26
	v_mul_f32_e32 v27, v199, v27
	v_mul_f32_e32 v156, v24, v156
	v_mul_f32_e32 v157, v25, v157
	v_mul_f32_e32 v158, v26, v158
	v_mul_f32_e32 v159, v27, v159
	v_cvt_pk_bf16_f32 v28, v156, v157
	v_cvt_pk_bf16_f32 v29, v158, v159
	global_store_dwordx2 v33, v[28:29], s[38:39]
	v_add_u32_e32 v33, 0x100000, v33
	v_fmamk_f32 v166, v166, 0x3c000000, v214
	v_cmp_gt_f32_e32 vcc, s66, v166
	v_mul_f32_e32 v24, 0x4f800000, v166
	s_nop 0
	v_cndmask_b32_e32 v166, v166, v24, vcc
	v_sqrt_f32_e32 v24, v166
	s_nop 0
	v_add_u32_e32 v25, -1, v24
	v_fma_f32 v26, -v25, v24, v166
	v_cmp_ge_f32_e64 s[40:41], 0, v26
	v_add_u32_e32 v26, 1, v24
	s_nop 0
	v_cndmask_b32_e64 v25, v24, v25, s[40:41]
	v_fma_f32 v24, -v26, v24, v166
	v_cmp_lt_f32_e64 s[40:41], 0, v24
	s_nop 1
	v_cndmask_b32_e64 v24, v25, v26, s[40:41]
	v_mul_f32_e32 v25, 0x37800000, v24
	v_cndmask_b32_e32 v24, v24, v25, vcc
	v_cmp_class_f32_e32 vcc, v166, v215
	s_nop 1
	v_cndmask_b32_e32 v166, v24, v166, vcc
	v_div_scale_f32 v30, s[52:53], v166, v166, 1.0
	v_rcp_f32_e32 v31, v30
	s_nop 0
	v_fma_f32 v198, -v30, v31, 1.0
	v_fmac_f32_e32 v31, v198, v31
	v_div_scale_f32 v198, vcc, 1.0, v166, 1.0
	v_mul_f32_e32 v199, v198, v31
	v_fma_f32 v29, -v30, v199, v198
	v_fmac_f32_e32 v199, v29, v31
	v_fma_f32 v30, -v30, v199, v198
	v_div_fmas_f32 v30, v30, v31, v199
	v_div_fixup_f32 v29, v30, v166, 1.0
	v_mul_f32_e32 v162, v162, v29
	v_mul_f32_e32 v163, v163, v29
	v_mul_f32_e32 v164, v164, v29
	v_mul_f32_e32 v165, v165, v29
	v_mul_f32_e32 v162, v162, v20
	v_mul_f32_e32 v163, v163, v21
	v_mul_f32_e32 v164, v164, v22
	v_mul_f32_e32 v165, v165, v23
	v_lshlrev_b32_e32 v24, 16, v70
	v_and_b32_e32 v25, 0xffff0000, v70
	v_lshlrev_b32_e32 v26, 16, v71
	v_and_b32_e32 v27, 0xffff0000, v71
	v_mul_f32_e32 v30, 0xbfb8aa3b, v24
	v_mul_f32_e32 v31, 0xbfb8aa3b, v25
	v_mul_f32_e32 v198, 0xbfb8aa3b, v26
	v_mul_f32_e32 v199, 0xbfb8aa3b, v27
	v_exp_f32_e32 v30, v30
	v_exp_f32_e32 v31, v31
	v_exp_f32_e32 v198, v198
	v_exp_f32_e32 v199, v199
	v_add_f32_e32 v30, 1.0, v30
	v_add_f32_e32 v31, 1.0, v31
	v_add_f32_e32 v198, 1.0, v198
	v_add_f32_e32 v199, 1.0, v199
	v_rcp_f32_e32 v30, v30
	v_rcp_f32_e32 v31, v31
	v_rcp_f32_e32 v198, v198
	v_rcp_f32_e32 v199, v199
	v_mul_f32_e32 v24, v30, v24
	v_mul_f32_e32 v25, v31, v25
	v_mul_f32_e32 v26, v198, v26
	v_mul_f32_e32 v27, v199, v27
	v_mul_f32_e32 v162, v24, v162
	v_mul_f32_e32 v163, v25, v163
	v_mul_f32_e32 v164, v26, v164
	v_mul_f32_e32 v165, v27, v165
	v_cvt_pk_bf16_f32 v28, v162, v163
	v_cvt_pk_bf16_f32 v29, v164, v165
	global_store_dwordx2 v33, v[28:29], s[38:39]
	v_add_u32_e32 v33, 0x100000, v33
	v_fmamk_f32 v172, v172, 0x3c000000, v214
	v_cmp_gt_f32_e32 vcc, s66, v172
	v_mul_f32_e32 v24, 0x4f800000, v172
	s_nop 0
	v_cndmask_b32_e32 v172, v172, v24, vcc
	v_sqrt_f32_e32 v24, v172
	s_nop 0
	v_add_u32_e32 v25, -1, v24
	v_fma_f32 v26, -v25, v24, v172
	v_cmp_ge_f32_e64 s[40:41], 0, v26
	v_add_u32_e32 v26, 1, v24
	s_nop 0
	v_cndmask_b32_e64 v25, v24, v25, s[40:41]
	v_fma_f32 v24, -v26, v24, v172
	v_cmp_lt_f32_e64 s[40:41], 0, v24
	s_nop 1
	v_cndmask_b32_e64 v24, v25, v26, s[40:41]
	v_mul_f32_e32 v25, 0x37800000, v24
	v_cndmask_b32_e32 v24, v24, v25, vcc
	v_cmp_class_f32_e32 vcc, v172, v215
	s_nop 1
	v_cndmask_b32_e32 v172, v24, v172, vcc
	v_div_scale_f32 v30, s[52:53], v172, v172, 1.0
	v_rcp_f32_e32 v31, v30
	s_nop 0
	v_fma_f32 v198, -v30, v31, 1.0
	v_fmac_f32_e32 v31, v198, v31
	v_div_scale_f32 v198, vcc, 1.0, v172, 1.0
	v_mul_f32_e32 v199, v198, v31
	v_fma_f32 v29, -v30, v199, v198
	v_fmac_f32_e32 v199, v29, v31
	v_fma_f32 v30, -v30, v199, v198
	v_div_fmas_f32 v30, v30, v31, v199
	v_div_fixup_f32 v29, v30, v172, 1.0
	v_mul_f32_e32 v168, v168, v29
	v_mul_f32_e32 v169, v169, v29
	v_mul_f32_e32 v170, v170, v29
	v_mul_f32_e32 v171, v171, v29
	v_mul_f32_e32 v168, v168, v20
	v_mul_f32_e32 v169, v169, v21
	v_mul_f32_e32 v170, v170, v22
	v_mul_f32_e32 v171, v171, v23
	v_lshlrev_b32_e32 v24, 16, v76
	v_and_b32_e32 v25, 0xffff0000, v76
	v_lshlrev_b32_e32 v26, 16, v77
	v_and_b32_e32 v27, 0xffff0000, v77
	v_mul_f32_e32 v30, 0xbfb8aa3b, v24
	v_mul_f32_e32 v31, 0xbfb8aa3b, v25
	v_mul_f32_e32 v198, 0xbfb8aa3b, v26
	v_mul_f32_e32 v199, 0xbfb8aa3b, v27
	v_exp_f32_e32 v30, v30
	v_exp_f32_e32 v31, v31
	v_exp_f32_e32 v198, v198
; __device__ __forceinline__ unsigned pk2(float lo, float hi) { f32x2_t v = {lo, hi}; bf16x2_t b = __builtin_convertvector(v, bf16x2_t); return __builtin_bit_cast(unsigned, b); }
; __device__ __forceinline__ float siluf_(float x) { return x * __builtin_amdgcn_rcpf(1.0f + __expf(-x)); }
; __global__ void __launch_bounds__(NTHREADS, 2) fwd_megakernel(Params P) {
;     ...
;                 const float rsn = 1.0f / sqrtf(ss * (1.0f / 128.0f) + NORM_EPS);
;                 const f32x4 wn = *(const f32x4*)(q_gnw + l * 1024 + hp * 256 + 4 * lane);
;                 u32x2 ow;
;                 ow.x = pk2(x[0] * rsn * wn[0] * siluf_(bflo(gg[q].x)), x[1] * rsn * wn[1] * siluf_(bfhi(gg[q].x)));
;                 ow.y = pk2(x[2] * rsn * wn[2] * siluf_(bflo(gg[q].y)), x[3] * rsn * wn[3] * siluf_(bfhi(gg[q].y)));
;                 if (ok[q]) *(u32x2*)(q_hcat + (size_t)2 * T * 1024 + o) = ow;
	v_exp_f32_e32 v199, v199
	v_add_f32_e32 v30, 1.0, v30
	v_add_f32_e32 v31, 1.0, v31
	v_add_f32_e32 v198, 1.0, v198
	v_add_f32_e32 v199, 1.0, v199
	v_rcp_f32_e32 v30, v30
	v_rcp_f32_e32 v31, v31
	v_rcp_f32_e32 v198, v198
	v_rcp_f32_e32 v199, v199
	v_mul_f32_e32 v24, v30, v24
	v_mul_f32_e32 v25, v31, v25
	v_mul_f32_e32 v26, v198, v26
	v_mul_f32_e32 v27, v199, v27
	v_mul_f32_e32 v168, v24, v168
	v_mul_f32_e32 v169, v25, v169
	v_mul_f32_e32 v170, v26, v170
	v_mul_f32_e32 v171, v27, v171
	v_cvt_pk_bf16_f32 v28, v168, v169
	v_cvt_pk_bf16_f32 v29, v170, v171
	global_store_dwordx2 v33, v[28:29], s[38:39]
	v_add_u32_e32 v33, 0x100000, v33
	v_fmamk_f32 v178, v178, 0x3c000000, v214
	v_cmp_gt_f32_e32 vcc, s66, v178
	v_mul_f32_e32 v24, 0x4f800000, v178
	s_nop 0
	v_cndmask_b32_e32 v178, v178, v24, vcc
	v_sqrt_f32_e32 v24, v178
	s_nop 0
	v_add_u32_e32 v25, -1, v24
	v_fma_f32 v26, -v25, v24, v178
	v_cmp_ge_f32_e64 s[40:41], 0, v26
	v_add_u32_e32 v26, 1, v24
	s_nop 0
	v_cndmask_b32_e64 v25, v24, v25, s[40:41]
	v_fma_f32 v24, -v26, v24, v178
	v_cmp_lt_f32_e64 s[40:41], 0, v24
	s_nop 1
	v_cndmask_b32_e64 v24, v25, v26, s[40:41]
	v_mul_f32_e32 v25, 0x37800000, v24
	v_cndmask_b32_e32 v24, v24, v25, vcc
	v_cmp_class_f32_e32 vcc, v178, v215
	s_nop 1
	v_cndmask_b32_e32 v178, v24, v178, vcc
	v_div_scale_f32 v30, s[52:53], v178, v178, 1.0
	v_rcp_f32_e32 v31, v30
	s_nop 0
	v_fma_f32 v198, -v30, v31, 1.0
	v_fmac_f32_e32 v31, v198, v31
	v_div_scale_f32 v198, vcc, 1.0, v178, 1.0
	v_mul_f32_e32 v199, v198, v31
	v_fma_f32 v29, -v30, v199, v198
	v_fmac_f32_e32 v199, v29, v31
	v_fma_f32 v30, -v30, v199, v198
	v_div_fmas_f32 v30, v30, v31, v199
	v_div_fixup_f32 v29, v30, v178, 1.0
	v_mul_f32_e32 v174, v174, v29
	v_mul_f32_e32 v175, v175, v29
	v_mul_f32_e32 v176, v176, v29
	v_mul_f32_e32 v177, v177, v29
	v_mul_f32_e32 v174, v174, v20
	v_mul_f32_e32 v175, v175, v21
	v_mul_f32_e32 v176, v176, v22
	v_mul_f32_e32 v177, v177, v23
	v_lshlrev_b32_e32 v24, 16, v82
	v_and_b32_e32 v25, 0xffff0000, v82
	v_lshlrev_b32_e32 v26, 16, v83
	v_and_b32_e32 v27, 0xffff0000, v83
	v_mul_f32_e32 v30, 0xbfb8aa3b, v24
	v_mul_f32_e32 v31, 0xbfb8aa3b, v25
	v_mul_f32_e32 v198, 0xbfb8aa3b, v26
	v_mul_f32_e32 v199, 0xbfb8aa3b, v27
	v_exp_f32_e32 v30, v30
	v_exp_f32_e32 v31, v31
	v_exp_f32_e32 v198, v198
	v_exp_f32_e32 v199, v199
	v_add_f32_e32 v30, 1.0, v30
	v_add_f32_e32 v31, 1.0, v31
	v_add_f32_e32 v198, 1.0, v198
	v_add_f32_e32 v199, 1.0, v199
	v_rcp_f32_e32 v30, v30
	v_rcp_f32_e32 v31, v31
	v_rcp_f32_e32 v198, v198
	v_rcp_f32_e32 v199, v199
	v_mul_f32_e32 v24, v30, v24
	v_mul_f32_e32 v25, v31, v25
	v_mul_f32_e32 v26, v198, v26
	v_mul_f32_e32 v27, v199, v27
	v_mul_f32_e32 v174, v24, v174
	v_mul_f32_e32 v175, v25, v175
	v_mul_f32_e32 v176, v26, v176
	v_mul_f32_e32 v177, v27, v177
	v_cvt_pk_bf16_f32 v28, v174, v175
	v_cvt_pk_bf16_f32 v29, v176, v177
	global_store_dwordx2 v33, v[28:29], s[38:39]
	v_add_u32_e32 v33, 0x100000, v33
	v_fmamk_f32 v184, v184, 0x3c000000, v214
	v_cmp_gt_f32_e32 vcc, s66, v184
	v_mul_f32_e32 v24, 0x4f800000, v184
	s_nop 0
	v_cndmask_b32_e32 v184, v184, v24, vcc
	v_sqrt_f32_e32 v24, v184
	s_nop 0
	v_add_u32_e32 v25, -1, v24
	v_fma_f32 v26, -v25, v24, v184
	v_cmp_ge_f32_e64 s[40:41], 0, v26
	v_add_u32_e32 v26, 1, v24
	s_nop 0
	v_cndmask_b32_e64 v25, v24, v25, s[40:41]
	v_fma_f32 v24, -v26, v24, v184
	v_cmp_lt_f32_e64 s[40:41], 0, v24
	s_nop 1
	v_cndmask_b32_e64 v24, v25, v26, s[40:41]
	v_mul_f32_e32 v25, 0x37800000, v24
	v_cndmask_b32_e32 v24, v24, v25, vcc
	v_cmp_class_f32_e32 vcc, v184, v215
	s_nop 1
	v_cndmask_b32_e32 v184, v24, v184, vcc
	v_div_scale_f32 v30, s[52:53], v184, v184, 1.0
	v_rcp_f32_e32 v31, v30
	s_nop 0
	v_fma_f32 v198, -v30, v31, 1.0
	v_fmac_f32_e32 v31, v198, v31
	v_div_scale_f32 v198, vcc, 1.0, v184, 1.0
	v_mul_f32_e32 v199, v198, v31
	v_fma_f32 v29, -v30, v199, v198
	v_fmac_f32_e32 v199, v29, v31
	v_fma_f32 v30, -v30, v199, v198
	v_div_fmas_f32 v30, v30, v31, v199
	v_div_fixup_f32 v29, v30, v184, 1.0
	v_mul_f32_e32 v180, v180, v29
	v_mul_f32_e32 v181, v181, v29
	v_mul_f32_e32 v182, v182, v29
	v_mul_f32_e32 v183, v183, v29
	v_mul_f32_e32 v180, v180, v20
	v_mul_f32_e32 v181, v181, v21
	v_mul_f32_e32 v182, v182, v22
	v_mul_f32_e32 v183, v183, v23
	v_lshlrev_b32_e32 v24, 16, v88
	v_and_b32_e32 v25, 0xffff0000, v88
	v_lshlrev_b32_e32 v26, 16, v89
	v_and_b32_e32 v27, 0xffff0000, v89
	v_mul_f32_e32 v30, 0xbfb8aa3b, v24
	v_mul_f32_e32 v31, 0xbfb8aa3b, v25
	v_mul_f32_e32 v198, 0xbfb8aa3b, v26
	v_mul_f32_e32 v199, 0xbfb8aa3b, v27
	v_exp_f32_e32 v30, v30
	v_exp_f32_e32 v31, v31
	v_exp_f32_e32 v198, v198
	v_exp_f32_e32 v199, v199
	v_add_f32_e32 v30, 1.0, v30
	v_add_f32_e32 v31, 1.0, v31
	v_add_f32_e32 v198, 1.0, v198
	v_add_f32_e32 v199, 1.0, v199
	v_rcp_f32_e32 v30, v30
	v_rcp_f32_e32 v31, v31
	v_rcp_f32_e32 v198, v198
	v_rcp_f32_e32 v199, v199
	v_mul_f32_e32 v24, v30, v24
	v_mul_f32_e32 v25, v31, v25
	v_mul_f32_e32 v26, v198, v26
	v_mul_f32_e32 v27, v199, v27
	v_mul_f32_e32 v180, v24, v180
	v_mul_f32_e32 v181, v25, v181
	v_mul_f32_e32 v182, v26, v182
	v_mul_f32_e32 v183, v27, v183
	v_cvt_pk_bf16_f32 v28, v180, v181
	v_cvt_pk_bf16_f32 v29, v182, v183
	global_store_dwordx2 v33, v[28:29], s[38:39]
	v_add_u32_e32 v33, 0x100000, v33
	v_fmamk_f32 v190, v190, 0x3c000000, v214
	v_cmp_gt_f32_e32 vcc, s66, v190
	v_mul_f32_e32 v24, 0x4f800000, v190
	s_nop 0
	v_cndmask_b32_e32 v190, v190, v24, vcc
	v_sqrt_f32_e32 v24, v190
	s_nop 0
	v_add_u32_e32 v25, -1, v24
	v_fma_f32 v26, -v25, v24, v190
	v_cmp_ge_f32_e64 s[40:41], 0, v26
	v_add_u32_e32 v26, 1, v24
	s_nop 0
	v_cndmask_b32_e64 v25, v24, v25, s[40:41]
	v_fma_f32 v24, -v26, v24, v190
	v_cmp_lt_f32_e64 s[40:41], 0, v24
	s_nop 1
; __device__ __forceinline__ unsigned pk2(float lo, float hi) { f32x2_t v = {lo, hi}; bf16x2_t b = __builtin_convertvector(v, bf16x2_t); return __builtin_bit_cast(unsigned, b); }
; __device__ __forceinline__ float siluf_(float x) { return x * __builtin_amdgcn_rcpf(1.0f + __expf(-x)); }
; __global__ void __launch_bounds__(NTHREADS, 2) fwd_megakernel(Params P) {
;     ...
;                 const int row = itc >> 2, hp = itc & 3; const size_t o = (size_t)row * 1024 + hp * 256 + 4 * lane;
;                 const u32x2 p0 = *(const u32x2*)(q_hp + o), p1 = *(const u32x2*)(q_hp + (size_t)T * 1024 + o);
;                 v[q][0] = bflo(p0.x) + bflo(p1.x); v[q][1] = bfhi(p0.x) + bfhi(p1.x); v[q][2] = bflo(p0.y) + bflo(p1.y); v[q][3] = bfhi(p0.y) + bfhi(p1.y);
;                 gg[q] = *(const u32x2*)(q_proj + (size_t)row * NP + C_GG + hp * 256 + 4 * lane);
;             }
; #pragma unroll
;             for (int q = 0; q < 2; ++q) {
;                 const int it = it0 + q * step; const int itc = ok[q] ? it : it0; const int row = itc >> 2, hp = itc & 3; const size_t o = (size_t)row * 1024 + hp * 256 + 4 * lane;
;                 const f32x4 x = v[q];
;                 float ss = (x[0] * x[0] + x[1] * x[1]) + (x[2] * x[2] + x[3] * x[3]);
; #pragma unroll
;                 for (int off = 1; off < 32; off <<= 1) ss += __shfl_xor(ss, off);
;                 const float rsn = 1.0f / sqrtf(ss * (1.0f / 128.0f) + NORM_EPS);
;                 const f32x4 wn = *(const f32x4*)(q_gnw + l * 1024 + hp * 256 + 4 * lane);
;                 u32x2 ow;
;                 ow.x = pk2(x[0] * rsn * wn[0] * siluf_(bflo(gg[q].x)), x[1] * rsn * wn[1] * siluf_(bfhi(gg[q].x)));
;                 ow.y = pk2(x[2] * rsn * wn[2] * siluf_(bflo(gg[q].y)), x[3] * rsn * wn[3] * siluf_(bfhi(gg[q].y)));
;                 if (ok[q]) *(u32x2*)(q_hcat + (size_t)2 * T * 1024 + o) = ow;
	v_cndmask_b32_e64 v24, v25, v26, s[40:41]
	v_mul_f32_e32 v25, 0x37800000, v24
	v_cndmask_b32_e32 v24, v24, v25, vcc
	v_cmp_class_f32_e32 vcc, v190, v215
	s_nop 1
	v_cndmask_b32_e32 v190, v24, v190, vcc
	v_div_scale_f32 v30, s[52:53], v190, v190, 1.0
	v_rcp_f32_e32 v31, v30
	s_nop 0
	v_fma_f32 v198, -v30, v31, 1.0
	v_fmac_f32_e32 v31, v198, v31
	v_div_scale_f32 v198, vcc, 1.0, v190, 1.0
	v_mul_f32_e32 v199, v198, v31
	v_fma_f32 v29, -v30, v199, v198
	v_fmac_f32_e32 v199, v29, v31
	v_fma_f32 v30, -v30, v199, v198
	v_div_fmas_f32 v30, v30, v31, v199
	v_div_fixup_f32 v29, v30, v190, 1.0
	v_mul_f32_e32 v186, v186, v29
	v_mul_f32_e32 v187, v187, v29
	v_mul_f32_e32 v188, v188, v29
	v_mul_f32_e32 v189, v189, v29
	v_mul_f32_e32 v186, v186, v20
	v_mul_f32_e32 v187, v187, v21
	v_mul_f32_e32 v188, v188, v22
	v_mul_f32_e32 v189, v189, v23
	v_lshlrev_b32_e32 v24, 16, v94
	v_and_b32_e32 v25, 0xffff0000, v94
	v_lshlrev_b32_e32 v26, 16, v95
	v_and_b32_e32 v27, 0xffff0000, v95
	v_mul_f32_e32 v30, 0xbfb8aa3b, v24
	v_mul_f32_e32 v31, 0xbfb8aa3b, v25
	v_mul_f32_e32 v198, 0xbfb8aa3b, v26
	v_mul_f32_e32 v199, 0xbfb8aa3b, v27
	v_exp_f32_e32 v30, v30
	v_exp_f32_e32 v31, v31
	v_exp_f32_e32 v198, v198
	v_exp_f32_e32 v199, v199
	v_add_f32_e32 v30, 1.0, v30
	v_add_f32_e32 v31, 1.0, v31
	v_add_f32_e32 v198, 1.0, v198
	v_add_f32_e32 v199, 1.0, v199
	v_rcp_f32_e32 v30, v30
	v_rcp_f32_e32 v31, v31
	v_rcp_f32_e32 v198, v198
	v_rcp_f32_e32 v199, v199
	v_mul_f32_e32 v24, v30, v24
	v_mul_f32_e32 v25, v31, v25
	v_mul_f32_e32 v26, v198, v26
	v_mul_f32_e32 v27, v199, v27
	v_mul_f32_e32 v186, v24, v186
	v_mul_f32_e32 v187, v25, v187
	v_mul_f32_e32 v188, v26, v188
	v_mul_f32_e32 v189, v27, v189
	v_cvt_pk_bf16_f32 v28, v186, v187
	v_cvt_pk_bf16_f32 v29, v188, v189
	global_store_dwordx2 v33, v[28:29], s[38:39]
	v_add_u32_e32 v33, 0x100000, v33
	v_fmamk_f32 v196, v196, 0x3c000000, v214
	v_cmp_gt_f32_e32 vcc, s66, v196
	v_mul_f32_e32 v24, 0x4f800000, v196
	s_nop 0
	v_cndmask_b32_e32 v196, v196, v24, vcc
	v_sqrt_f32_e32 v24, v196
	s_nop 0
	v_add_u32_e32 v25, -1, v24
	v_fma_f32 v26, -v25, v24, v196
	v_cmp_ge_f32_e64 s[40:41], 0, v26
	v_add_u32_e32 v26, 1, v24
	s_nop 0
	v_cndmask_b32_e64 v25, v24, v25, s[40:41]
	v_fma_f32 v24, -v26, v24, v196
	v_cmp_lt_f32_e64 s[40:41], 0, v24
	s_nop 1
	v_cndmask_b32_e64 v24, v25, v26, s[40:41]
	v_mul_f32_e32 v25, 0x37800000, v24
	v_cndmask_b32_e32 v24, v24, v25, vcc
	v_cmp_class_f32_e32 vcc, v196, v215
	s_nop 1
	v_cndmask_b32_e32 v196, v24, v196, vcc
	v_div_scale_f32 v30, s[52:53], v196, v196, 1.0
	v_rcp_f32_e32 v31, v30
	s_nop 0
	v_fma_f32 v198, -v30, v31, 1.0
	v_fmac_f32_e32 v31, v198, v31
	v_div_scale_f32 v198, vcc, 1.0, v196, 1.0
	v_mul_f32_e32 v199, v198, v31
	v_fma_f32 v29, -v30, v199, v198
	v_fmac_f32_e32 v199, v29, v31
	v_fma_f32 v30, -v30, v199, v198
	v_div_fmas_f32 v30, v30, v31, v199
	v_div_fixup_f32 v29, v30, v196, 1.0
	v_mul_f32_e32 v192, v192, v29
	v_mul_f32_e32 v193, v193, v29
	v_mul_f32_e32 v194, v194, v29
	v_mul_f32_e32 v195, v195, v29
	v_mul_f32_e32 v192, v192, v20
	v_mul_f32_e32 v193, v193, v21
	v_mul_f32_e32 v194, v194, v22
	v_mul_f32_e32 v195, v195, v23
	v_lshlrev_b32_e32 v24, 16, v100
	v_and_b32_e32 v25, 0xffff0000, v100
	v_lshlrev_b32_e32 v26, 16, v101
	v_and_b32_e32 v27, 0xffff0000, v101
	v_mul_f32_e32 v30, 0xbfb8aa3b, v24
	v_mul_f32_e32 v31, 0xbfb8aa3b, v25
	v_mul_f32_e32 v198, 0xbfb8aa3b, v26
	v_mul_f32_e32 v199, 0xbfb8aa3b, v27
	v_exp_f32_e32 v30, v30
	v_exp_f32_e32 v31, v31
	v_exp_f32_e32 v198, v198
	v_exp_f32_e32 v199, v199
	v_add_f32_e32 v30, 1.0, v30
	v_add_f32_e32 v31, 1.0, v31
	v_add_f32_e32 v198, 1.0, v198
	v_add_f32_e32 v199, 1.0, v199
	v_rcp_f32_e32 v30, v30
	v_rcp_f32_e32 v31, v31
	v_rcp_f32_e32 v198, v198
	v_rcp_f32_e32 v199, v199
	v_mul_f32_e32 v24, v30, v24
	v_mul_f32_e32 v25, v31, v25
	v_mul_f32_e32 v26, v198, v26
	v_mul_f32_e32 v27, v199, v27
	v_mul_f32_e32 v192, v24, v192
	v_mul_f32_e32 v193, v25, v193
	v_mul_f32_e32 v194, v26, v194
	v_mul_f32_e32 v195, v27, v195
	v_cvt_pk_bf16_f32 v28, v192, v193
	v_cvt_pk_bf16_f32 v29, v194, v195
	global_store_dwordx2 v33, v[28:29], s[38:39]
	v_add_u32_e32 v33, 0x100000, v33
	s_waitcnt vmcnt(8)
	v_lshlrev_b32_e32 v150, 16, v102
	v_and_b32_e32 v151, 0xffff0000, v102
	v_lshlrev_b32_e32 v152, 16, v103
	v_and_b32_e32 v153, 0xffff0000, v103
	v_lshlrev_b32_e32 v24, 16, v104
	v_and_b32_e32 v25, 0xffff0000, v104
	v_lshlrev_b32_e32 v26, 16, v105
	v_and_b32_e32 v27, 0xffff0000, v105
	v_pk_add_f32 v[150:151], v[150:151], v[24:25]
	v_pk_add_f32 v[152:153], v[152:153], v[26:27]
	v_mul_f32_e32 v25, v151, v151
	v_mul_f32_e32 v27, v153, v153
	v_fma_f32 v24, v150, v150, v25
	v_fma_f32 v26, v152, v152, v27
	v_add_f32_e32 v154, v24, v26
	v_lshlrev_b32_e32 v156, 16, v108
	v_and_b32_e32 v157, 0xffff0000, v108
	v_lshlrev_b32_e32 v158, 16, v109
	v_and_b32_e32 v159, 0xffff0000, v109
	v_lshlrev_b32_e32 v24, 16, v110
	v_and_b32_e32 v25, 0xffff0000, v110
	v_lshlrev_b32_e32 v26, 16, v111
	v_and_b32_e32 v27, 0xffff0000, v111
	v_pk_add_f32 v[156:157], v[156:157], v[24:25]
	v_pk_add_f32 v[158:159], v[158:159], v[26:27]
	v_mul_f32_e32 v24, v156, v156
	v_mul_f32_e32 v25, v157, v157
	v_mul_f32_e32 v26, v158, v158
	v_mul_f32_e32 v27, v159, v159
	v_add_f32_e32 v24, v24, v25
	v_add_f32_e32 v26, v26, v27
	v_add_f32_e32 v160, v24, v26
	v_lshlrev_b32_e32 v162, 16, v114
	v_and_b32_e32 v163, 0xffff0000, v114
	v_lshlrev_b32_e32 v164, 16, v115
	v_and_b32_e32 v165, 0xffff0000, v115
	v_lshlrev_b32_e32 v24, 16, v116
	v_and_b32_e32 v25, 0xffff0000, v116
	v_lshlrev_b32_e32 v26, 16, v117
	v_and_b32_e32 v27, 0xffff0000, v117
	v_pk_add_f32 v[162:163], v[162:163], v[24:25]
	v_pk_add_f32 v[164:165], v[164:165], v[26:27]
; __global__ void __launch_bounds__(NTHREADS, 2) fwd_megakernel(Params P) {
;     ...
;                 const int row = itc >> 2, hp = itc & 3; const size_t o = (size_t)row * 1024 + hp * 256 + 4 * lane;
;                 const u32x2 p0 = *(const u32x2*)(q_hp + o), p1 = *(const u32x2*)(q_hp + (size_t)T * 1024 + o);
;                 v[q][0] = bflo(p0.x) + bflo(p1.x); v[q][1] = bfhi(p0.x) + bfhi(p1.x); v[q][2] = bflo(p0.y) + bflo(p1.y); v[q][3] = bfhi(p0.y) + bfhi(p1.y);
;                 gg[q] = *(const u32x2*)(q_proj + (size_t)row * NP + C_GG + hp * 256 + 4 * lane);
;             }
; #pragma unroll
;             for (int q = 0; q < 2; ++q) {
;                 const int it = it0 + q * step; const int itc = ok[q] ? it : it0; const int row = itc >> 2, hp = itc & 3; const size_t o = (size_t)row * 1024 + hp * 256 + 4 * lane;
;                 const f32x4 x = v[q];
;                 float ss = (x[0] * x[0] + x[1] * x[1]) + (x[2] * x[2] + x[3] * x[3]);
; #pragma unroll
;                 for (int off = 1; off < 32; off <<= 1) ss += __shfl_xor(ss, off);
	v_mul_f32_e32 v25, v163, v163
	v_mul_f32_e32 v27, v165, v165
	v_fma_f32 v24, v162, v162, v25
	v_fma_f32 v26, v164, v164, v27
	v_add_f32_e32 v166, v24, v26
	v_lshlrev_b32_e32 v168, 16, v120
	v_and_b32_e32 v169, 0xffff0000, v120
	v_lshlrev_b32_e32 v170, 16, v121
	v_and_b32_e32 v171, 0xffff0000, v121
	v_lshlrev_b32_e32 v24, 16, v122
	v_and_b32_e32 v25, 0xffff0000, v122
	v_lshlrev_b32_e32 v26, 16, v123
	v_and_b32_e32 v27, 0xffff0000, v123
	v_pk_add_f32 v[168:169], v[168:169], v[24:25]
	v_pk_add_f32 v[170:171], v[170:171], v[26:27]
	v_mul_f32_e32 v24, v168, v168
	v_mul_f32_e32 v25, v169, v169
	v_mul_f32_e32 v26, v170, v170
	v_mul_f32_e32 v27, v171, v171
	v_add_f32_e32 v24, v24, v25
	v_add_f32_e32 v26, v26, v27
	v_add_f32_e32 v172, v24, v26
	v_lshlrev_b32_e32 v174, 16, v126
	v_and_b32_e32 v175, 0xffff0000, v126
	v_lshlrev_b32_e32 v176, 16, v127
	v_and_b32_e32 v177, 0xffff0000, v127
	v_lshlrev_b32_e32 v24, 16, v128
	v_and_b32_e32 v25, 0xffff0000, v128
	v_lshlrev_b32_e32 v26, 16, v129
	v_and_b32_e32 v27, 0xffff0000, v129
	v_pk_add_f32 v[174:175], v[174:175], v[24:25]
	v_pk_add_f32 v[176:177], v[176:177], v[26:27]
	v_mul_f32_e32 v25, v175, v175
	v_mul_f32_e32 v27, v177, v177
	v_fma_f32 v24, v174, v174, v25
	v_fma_f32 v26, v176, v176, v27
	v_add_f32_e32 v178, v24, v26
	v_lshlrev_b32_e32 v180, 16, v132
	v_and_b32_e32 v181, 0xffff0000, v132
	v_lshlrev_b32_e32 v182, 16, v133
	v_and_b32_e32 v183, 0xffff0000, v133
	v_lshlrev_b32_e32 v24, 16, v134
	v_and_b32_e32 v25, 0xffff0000, v134
	v_lshlrev_b32_e32 v26, 16, v135
	v_and_b32_e32 v27, 0xffff0000, v135
	v_pk_add_f32 v[180:181], v[180:181], v[24:25]
	v_pk_add_f32 v[182:183], v[182:183], v[26:27]
	v_mul_f32_e32 v24, v180, v180
	v_mul_f32_e32 v25, v181, v181
	v_mul_f32_e32 v26, v182, v182
	v_mul_f32_e32 v27, v183, v183
	v_add_f32_e32 v24, v24, v25
	v_add_f32_e32 v26, v26, v27
	v_add_f32_e32 v184, v24, v26
	v_lshlrev_b32_e32 v186, 16, v138
	v_and_b32_e32 v187, 0xffff0000, v138
	v_lshlrev_b32_e32 v188, 16, v139
	v_and_b32_e32 v189, 0xffff0000, v139
	v_lshlrev_b32_e32 v24, 16, v140
	v_and_b32_e32 v25, 0xffff0000, v140
	v_lshlrev_b32_e32 v26, 16, v141
	v_and_b32_e32 v27, 0xffff0000, v141
	v_pk_add_f32 v[186:187], v[186:187], v[24:25]
	v_pk_add_f32 v[188:189], v[188:189], v[26:27]
	v_mul_f32_e32 v25, v187, v187
	v_mul_f32_e32 v27, v189, v189
	v_fma_f32 v24, v186, v186, v25
	v_fma_f32 v26, v188, v188, v27
	v_add_f32_e32 v190, v24, v26
	v_lshlrev_b32_e32 v192, 16, v144
	v_and_b32_e32 v193, 0xffff0000, v144
	v_lshlrev_b32_e32 v194, 16, v145
	v_and_b32_e32 v195, 0xffff0000, v145
	v_lshlrev_b32_e32 v24, 16, v146
	v_and_b32_e32 v25, 0xffff0000, v146
	v_lshlrev_b32_e32 v26, 16, v147
	v_and_b32_e32 v27, 0xffff0000, v147
	v_pk_add_f32 v[192:193], v[192:193], v[24:25]
	v_pk_add_f32 v[194:195], v[194:195], v[26:27]
	v_mul_f32_e32 v24, v192, v192
	v_mul_f32_e32 v25, v193, v193
	v_mul_f32_e32 v26, v194, v194
	v_mul_f32_e32 v27, v195, v195
	v_add_f32_e32 v24, v24, v25
	v_add_f32_e32 v26, v26, v27
	v_add_f32_e32 v196, v24, v26
	s_nop 1
	v_mov_b32_dpp v155, v154 quad_perm:[1,0,3,2] row_mask:0xf bank_mask:0xf
	v_mov_b32_dpp v161, v160 quad_perm:[1,0,3,2] row_mask:0xf bank_mask:0xf
	v_mov_b32_dpp v167, v166 quad_perm:[1,0,3,2] row_mask:0xf bank_mask:0xf
	v_mov_b32_dpp v173, v172 quad_perm:[1,0,3,2] row_mask:0xf bank_mask:0xf
	v_mov_b32_dpp v179, v178 quad_perm:[1,0,3,2] row_mask:0xf bank_mask:0xf
	v_mov_b32_dpp v185, v184 quad_perm:[1,0,3,2] row_mask:0xf bank_mask:0xf
	v_mov_b32_dpp v191, v190 quad_perm:[1,0,3,2] row_mask:0xf bank_mask:0xf
	v_mov_b32_dpp v197, v196 quad_perm:[1,0,3,2] row_mask:0xf bank_mask:0xf
	v_add_f32_e32 v154, v154, v155
	v_add_f32_e32 v160, v160, v161
	v_add_f32_e32 v166, v166, v167
	v_add_f32_e32 v172, v172, v173
	v_add_f32_e32 v178, v178, v179
	v_add_f32_e32 v184, v184, v185
	v_add_f32_e32 v190, v190, v191
	v_add_f32_e32 v196, v196, v197
	s_nop 1
	v_mov_b32_dpp v155, v154 quad_perm:[2,3,0,1] row_mask:0xf bank_mask:0xf
	v_mov_b32_dpp v161, v160 quad_perm:[2,3,0,1] row_mask:0xf bank_mask:0xf
	v_mov_b32_dpp v167, v166 quad_perm:[2,3,0,1] row_mask:0xf bank_mask:0xf
	v_mov_b32_dpp v173, v172 quad_perm:[2,3,0,1] row_mask:0xf bank_mask:0xf
	v_mov_b32_dpp v179, v178 quad_perm:[2,3,0,1] row_mask:0xf bank_mask:0xf
	v_mov_b32_dpp v185, v184 quad_perm:[2,3,0,1] row_mask:0xf bank_mask:0xf
	v_mov_b32_dpp v191, v190 quad_perm:[2,3,0,1] row_mask:0xf bank_mask:0xf
	v_mov_b32_dpp v197, v196 quad_perm:[2,3,0,1] row_mask:0xf bank_mask:0xf
	v_add_f32_e32 v154, v154, v155
	v_add_f32_e32 v160, v160, v161
	v_add_f32_e32 v166, v166, v167
	v_add_f32_e32 v172, v172, v173
	v_add_f32_e32 v178, v178, v179
	v_add_f32_e32 v184, v184, v185
	v_add_f32_e32 v190, v190, v191
	v_add_f32_e32 v196, v196, v197
	s_nop 1
	v_mov_b32_dpp v155, v154 row_half_mirror row_mask:0xf bank_mask:0xf
	v_mov_b32_dpp v161, v160 row_half_mirror row_mask:0xf bank_mask:0xf
	v_mov_b32_dpp v167, v166 row_half_mirror row_mask:0xf bank_mask:0xf
	v_mov_b32_dpp v173, v172 row_half_mirror row_mask:0xf bank_mask:0xf
	v_mov_b32_dpp v179, v178 row_half_mirror row_mask:0xf bank_mask:0xf
	v_mov_b32_dpp v185, v184 row_half_mirror row_mask:0xf bank_mask:0xf
	v_mov_b32_dpp v191, v190 row_half_mirror row_mask:0xf bank_mask:0xf
	v_mov_b32_dpp v197, v196 row_half_mirror row_mask:0xf bank_mask:0xf
	v_add_f32_e32 v154, v154, v155
	v_add_f32_e32 v160, v160, v161
	v_add_f32_e32 v166, v166, v167
	v_add_f32_e32 v172, v172, v173
	v_add_f32_e32 v178, v178, v179
	v_add_f32_e32 v184, v184, v185
	v_add_f32_e32 v190, v190, v191
	v_add_f32_e32 v196, v196, v197
	s_nop 1
	v_mov_b32_dpp v155, v154 row_mirror row_mask:0xf bank_mask:0xf
	v_mov_b32_dpp v161, v160 row_mirror row_mask:0xf bank_mask:0xf
; __device__ __forceinline__ unsigned pk2(float lo, float hi) { f32x2_t v = {lo, hi}; bf16x2_t b = __builtin_convertvector(v, bf16x2_t); return __builtin_bit_cast(unsigned, b); }
; __device__ __forceinline__ float siluf_(float x) { return x * __builtin_amdgcn_rcpf(1.0f + __expf(-x)); }
; __global__ void __launch_bounds__(NTHREADS, 2) fwd_megakernel(Params P) {
;     ...
;                 const f32x4 x = v[q];
;                 float ss = (x[0] * x[0] + x[1] * x[1]) + (x[2] * x[2] + x[3] * x[3]);
; #pragma unroll
;                 for (int off = 1; off < 32; off <<= 1) ss += __shfl_xor(ss, off);
;                 const float rsn = 1.0f / sqrtf(ss * (1.0f / 128.0f) + NORM_EPS);
;                 const f32x4 wn = *(const f32x4*)(q_gnw + l * 1024 + hp * 256 + 4 * lane);
;                 u32x2 ow;
;                 ow.x = pk2(x[0] * rsn * wn[0] * siluf_(bflo(gg[q].x)), x[1] * rsn * wn[1] * siluf_(bfhi(gg[q].x)));
;                 ow.y = pk2(x[2] * rsn * wn[2] * siluf_(bflo(gg[q].y)), x[3] * rsn * wn[3] * siluf_(bfhi(gg[q].y)));
;                 if (ok[q]) *(u32x2*)(q_hcat + (size_t)2 * T * 1024 + o) = ow;
	v_mov_b32_dpp v167, v166 row_mirror row_mask:0xf bank_mask:0xf
	v_mov_b32_dpp v173, v172 row_mirror row_mask:0xf bank_mask:0xf
	v_mov_b32_dpp v179, v178 row_mirror row_mask:0xf bank_mask:0xf
	v_mov_b32_dpp v185, v184 row_mirror row_mask:0xf bank_mask:0xf
	v_mov_b32_dpp v191, v190 row_mirror row_mask:0xf bank_mask:0xf
	v_mov_b32_dpp v197, v196 row_mirror row_mask:0xf bank_mask:0xf
	v_add_f32_e32 v154, v154, v155
	v_add_f32_e32 v160, v160, v161
	v_add_f32_e32 v166, v166, v167
	v_add_f32_e32 v172, v172, v173
	v_add_f32_e32 v178, v178, v179
	v_add_f32_e32 v184, v184, v185
	v_add_f32_e32 v190, v190, v191
	v_add_f32_e32 v196, v196, v197
	v_mov_b32_e32 v155, v154
	v_mov_b32_e32 v161, v160
	v_mov_b32_e32 v167, v166
	v_mov_b32_e32 v173, v172
	v_mov_b32_e32 v179, v178
	v_mov_b32_e32 v185, v184
	v_mov_b32_e32 v191, v190
	v_mov_b32_e32 v197, v196
	s_nop 1
	v_permlane16_swap_b32 v155, v154
	v_permlane16_swap_b32 v161, v160
	v_permlane16_swap_b32 v167, v166
	v_permlane16_swap_b32 v173, v172
	v_permlane16_swap_b32 v179, v178
	v_permlane16_swap_b32 v185, v184
	v_permlane16_swap_b32 v191, v190
	v_permlane16_swap_b32 v197, v196
	v_add_f32_e32 v154, v154, v155
	v_add_f32_e32 v160, v160, v161
	v_add_f32_e32 v166, v166, v167
	v_add_f32_e32 v172, v172, v173
	v_add_f32_e32 v178, v178, v179
	v_add_f32_e32 v184, v184, v185
	v_add_f32_e32 v190, v190, v191
	v_add_f32_e32 v196, v196, v197
	v_fmamk_f32 v154, v154, 0x3c000000, v214
	v_cmp_gt_f32_e32 vcc, s66, v154
	v_mul_f32_e32 v24, 0x4f800000, v154
	s_nop 0
	v_cndmask_b32_e32 v154, v154, v24, vcc
	v_sqrt_f32_e32 v24, v154
	s_nop 0
	v_add_u32_e32 v25, -1, v24
	v_fma_f32 v26, -v25, v24, v154
	v_cmp_ge_f32_e64 s[40:41], 0, v26
	v_add_u32_e32 v26, 1, v24
	s_nop 0
	v_cndmask_b32_e64 v25, v24, v25, s[40:41]
	v_fma_f32 v24, -v26, v24, v154
	v_cmp_lt_f32_e64 s[40:41], 0, v24
	s_nop 1
	v_cndmask_b32_e64 v24, v25, v26, s[40:41]
	v_mul_f32_e32 v25, 0x37800000, v24
	v_cndmask_b32_e32 v24, v24, v25, vcc
	v_cmp_class_f32_e32 vcc, v154, v215
	s_nop 1
	v_cndmask_b32_e32 v154, v24, v154, vcc
	v_div_scale_f32 v30, s[52:53], v154, v154, 1.0
	v_rcp_f32_e32 v31, v30
	s_nop 0
	v_fma_f32 v198, -v30, v31, 1.0
	v_fmac_f32_e32 v31, v198, v31
	v_div_scale_f32 v198, vcc, 1.0, v154, 1.0
	v_mul_f32_e32 v199, v198, v31
	v_fma_f32 v29, -v30, v199, v198
	v_fmac_f32_e32 v199, v29, v31
	v_fma_f32 v30, -v30, v199, v198
	v_div_fmas_f32 v30, v30, v31, v199
	v_div_fixup_f32 v29, v30, v154, 1.0
	v_mul_f32_e32 v150, v150, v29
	v_mul_f32_e32 v151, v151, v29
	v_mul_f32_e32 v152, v152, v29
	v_mul_f32_e32 v153, v153, v29
	v_mul_f32_e32 v150, v150, v20
	v_mul_f32_e32 v151, v151, v21
	v_mul_f32_e32 v152, v152, v22
	v_mul_f32_e32 v153, v153, v23
	v_lshlrev_b32_e32 v24, 16, v106
	v_and_b32_e32 v25, 0xffff0000, v106
	v_lshlrev_b32_e32 v26, 16, v107
	v_and_b32_e32 v27, 0xffff0000, v107
	v_mul_f32_e32 v30, 0xbfb8aa3b, v24
	v_mul_f32_e32 v31, 0xbfb8aa3b, v25
	v_mul_f32_e32 v198, 0xbfb8aa3b, v26
	v_mul_f32_e32 v199, 0xbfb8aa3b, v27
	v_exp_f32_e32 v30, v30
	v_exp_f32_e32 v31, v31
	v_exp_f32_e32 v198, v198
	v_exp_f32_e32 v199, v199
	v_add_f32_e32 v30, 1.0, v30
	v_add_f32_e32 v31, 1.0, v31
	v_add_f32_e32 v198, 1.0, v198
	v_add_f32_e32 v199, 1.0, v199
	v_rcp_f32_e32 v30, v30
	v_rcp_f32_e32 v31, v31
	v_rcp_f32_e32 v198, v198
	v_rcp_f32_e32 v199, v199
	v_mul_f32_e32 v24, v30, v24
	v_mul_f32_e32 v25, v31, v25
	v_mul_f32_e32 v26, v198, v26
	v_mul_f32_e32 v27, v199, v27
	v_mul_f32_e32 v150, v24, v150
	v_mul_f32_e32 v151, v25, v151
	v_mul_f32_e32 v152, v26, v152
	v_mul_f32_e32 v153, v27, v153
	v_cvt_pk_bf16_f32 v28, v150, v151
	v_cvt_pk_bf16_f32 v29, v152, v153
	global_store_dwordx2 v33, v[28:29], s[38:39]
	v_add_u32_e32 v33, 0x100000, v33
	v_fmamk_f32 v160, v160, 0x3c000000, v214
	v_cmp_gt_f32_e32 vcc, s66, v160
	v_mul_f32_e32 v24, 0x4f800000, v160
	s_nop 0
	v_cndmask_b32_e32 v160, v160, v24, vcc
	v_sqrt_f32_e32 v24, v160
	s_nop 0
	v_add_u32_e32 v25, -1, v24
	v_fma_f32 v26, -v25, v24, v160
	v_cmp_ge_f32_e64 s[40:41], 0, v26
	v_add_u32_e32 v26, 1, v24
	s_nop 0
	v_cndmask_b32_e64 v25, v24, v25, s[40:41]
	v_fma_f32 v24, -v26, v24, v160
	v_cmp_lt_f32_e64 s[40:41], 0, v24
	s_nop 1
	v_cndmask_b32_e64 v24, v25, v26, s[40:41]
	v_mul_f32_e32 v25, 0x37800000, v24
	v_cndmask_b32_e32 v24, v24, v25, vcc
	v_cmp_class_f32_e32 vcc, v160, v215
	s_nop 1
	v_cndmask_b32_e32 v160, v24, v160, vcc
	v_div_scale_f32 v30, s[52:53], v160, v160, 1.0
	v_rcp_f32_e32 v31, v30
	s_nop 0
	v_fma_f32 v198, -v30, v31, 1.0
	v_fmac_f32_e32 v31, v198, v31
	v_div_scale_f32 v198, vcc, 1.0, v160, 1.0
	v_mul_f32_e32 v199, v198, v31
	v_fma_f32 v29, -v30, v199, v198
	v_fmac_f32_e32 v199, v29, v31
	v_fma_f32 v30, -v30, v199, v198
	v_div_fmas_f32 v30, v30, v31, v199
	v_div_fixup_f32 v29, v30, v160, 1.0
	v_mul_f32_e32 v156, v156, v29
	v_mul_f32_e32 v157, v157, v29
	v_mul_f32_e32 v158, v158, v29
	v_mul_f32_e32 v159, v159, v29
	v_mul_f32_e32 v156, v156, v20
	v_mul_f32_e32 v157, v157, v21
	v_mul_f32_e32 v158, v158, v22
	v_mul_f32_e32 v159, v159, v23
	v_lshlrev_b32_e32 v24, 16, v112
	v_and_b32_e32 v25, 0xffff0000, v112
	v_lshlrev_b32_e32 v26, 16, v113
	v_and_b32_e32 v27, 0xffff0000, v113
	v_mul_f32_e32 v30, 0xbfb8aa3b, v24
	v_mul_f32_e32 v31, 0xbfb8aa3b, v25
	v_mul_f32_e32 v198, 0xbfb8aa3b, v26
	v_mul_f32_e32 v199, 0xbfb8aa3b, v27
	v_exp_f32_e32 v30, v30
	v_exp_f32_e32 v31, v31
	v_exp_f32_e32 v198, v198
	v_exp_f32_e32 v199, v199
	v_add_f32_e32 v30, 1.0, v30
	v_add_f32_e32 v31, 1.0, v31
	v_add_f32_e32 v198, 1.0, v198
	v_add_f32_e32 v199, 1.0, v199
	v_rcp_f32_e32 v30, v30
	v_rcp_f32_e32 v31, v31
	v_rcp_f32_e32 v198, v198
	v_rcp_f32_e32 v199, v199
	v_mul_f32_e32 v24, v30, v24
	v_mul_f32_e32 v25, v31, v25
	v_mul_f32_e32 v26, v198, v26
; __device__ __forceinline__ unsigned pk2(float lo, float hi) { f32x2_t v = {lo, hi}; bf16x2_t b = __builtin_convertvector(v, bf16x2_t); return __builtin_bit_cast(unsigned, b); }
; __device__ __forceinline__ float siluf_(float x) { return x * __builtin_amdgcn_rcpf(1.0f + __expf(-x)); }
; __global__ void __launch_bounds__(NTHREADS, 2) fwd_megakernel(Params P) {
;     ...
;                 const float rsn = 1.0f / sqrtf(ss * (1.0f / 128.0f) + NORM_EPS);
;                 const f32x4 wn = *(const f32x4*)(q_gnw + l * 1024 + hp * 256 + 4 * lane);
;                 u32x2 ow;
;                 ow.x = pk2(x[0] * rsn * wn[0] * siluf_(bflo(gg[q].x)), x[1] * rsn * wn[1] * siluf_(bfhi(gg[q].x)));
;                 ow.y = pk2(x[2] * rsn * wn[2] * siluf_(bflo(gg[q].y)), x[3] * rsn * wn[3] * siluf_(bfhi(gg[q].y)));
;                 if (ok[q]) *(u32x2*)(q_hcat + (size_t)2 * T * 1024 + o) = ow;
	v_mul_f32_e32 v27, v199, v27
	v_mul_f32_e32 v156, v24, v156
	v_mul_f32_e32 v157, v25, v157
	v_mul_f32_e32 v158, v26, v158
	v_mul_f32_e32 v159, v27, v159
	v_cvt_pk_bf16_f32 v28, v156, v157
	v_cvt_pk_bf16_f32 v29, v158, v159
	global_store_dwordx2 v33, v[28:29], s[38:39]
	v_add_u32_e32 v33, 0x100000, v33
	v_fmamk_f32 v166, v166, 0x3c000000, v214
	v_cmp_gt_f32_e32 vcc, s66, v166
	v_mul_f32_e32 v24, 0x4f800000, v166
	s_nop 0
	v_cndmask_b32_e32 v166, v166, v24, vcc
	v_sqrt_f32_e32 v24, v166
	s_nop 0
	v_add_u32_e32 v25, -1, v24
	v_fma_f32 v26, -v25, v24, v166
	v_cmp_ge_f32_e64 s[40:41], 0, v26
	v_add_u32_e32 v26, 1, v24
	s_nop 0
	v_cndmask_b32_e64 v25, v24, v25, s[40:41]
	v_fma_f32 v24, -v26, v24, v166
	v_cmp_lt_f32_e64 s[40:41], 0, v24
	s_nop 1
	v_cndmask_b32_e64 v24, v25, v26, s[40:41]
	v_mul_f32_e32 v25, 0x37800000, v24
	v_cndmask_b32_e32 v24, v24, v25, vcc
	v_cmp_class_f32_e32 vcc, v166, v215
	s_nop 1
	v_cndmask_b32_e32 v166, v24, v166, vcc
	v_div_scale_f32 v30, s[52:53], v166, v166, 1.0
	v_rcp_f32_e32 v31, v30
	s_nop 0
	v_fma_f32 v198, -v30, v31, 1.0
	v_fmac_f32_e32 v31, v198, v31
	v_div_scale_f32 v198, vcc, 1.0, v166, 1.0
	v_mul_f32_e32 v199, v198, v31
	v_fma_f32 v29, -v30, v199, v198
	v_fmac_f32_e32 v199, v29, v31
	v_fma_f32 v30, -v30, v199, v198
	v_div_fmas_f32 v30, v30, v31, v199
	v_div_fixup_f32 v29, v30, v166, 1.0
	v_mul_f32_e32 v162, v162, v29
	v_mul_f32_e32 v163, v163, v29
	v_mul_f32_e32 v164, v164, v29
	v_mul_f32_e32 v165, v165, v29
	v_mul_f32_e32 v162, v162, v20
	v_mul_f32_e32 v163, v163, v21
	v_mul_f32_e32 v164, v164, v22
	v_mul_f32_e32 v165, v165, v23
	v_lshlrev_b32_e32 v24, 16, v118
	v_and_b32_e32 v25, 0xffff0000, v118
	v_lshlrev_b32_e32 v26, 16, v119
	v_and_b32_e32 v27, 0xffff0000, v119
	v_mul_f32_e32 v30, 0xbfb8aa3b, v24
	v_mul_f32_e32 v31, 0xbfb8aa3b, v25
	v_mul_f32_e32 v198, 0xbfb8aa3b, v26
	v_mul_f32_e32 v199, 0xbfb8aa3b, v27
	v_exp_f32_e32 v30, v30
	v_exp_f32_e32 v31, v31
	v_exp_f32_e32 v198, v198
	v_exp_f32_e32 v199, v199
	v_add_f32_e32 v30, 1.0, v30
	v_add_f32_e32 v31, 1.0, v31
	v_add_f32_e32 v198, 1.0, v198
	v_add_f32_e32 v199, 1.0, v199
	v_rcp_f32_e32 v30, v30
	v_rcp_f32_e32 v31, v31
	v_rcp_f32_e32 v198, v198
	v_rcp_f32_e32 v199, v199
	v_mul_f32_e32 v24, v30, v24
	v_mul_f32_e32 v25, v31, v25
	v_mul_f32_e32 v26, v198, v26
	v_mul_f32_e32 v27, v199, v27
	v_mul_f32_e32 v162, v24, v162
	v_mul_f32_e32 v163, v25, v163
	v_mul_f32_e32 v164, v26, v164
	v_mul_f32_e32 v165, v27, v165
	v_cvt_pk_bf16_f32 v28, v162, v163
	v_cvt_pk_bf16_f32 v29, v164, v165
	global_store_dwordx2 v33, v[28:29], s[38:39]
	v_add_u32_e32 v33, 0x100000, v33
	v_fmamk_f32 v172, v172, 0x3c000000, v214
	v_cmp_gt_f32_e32 vcc, s66, v172
	v_mul_f32_e32 v24, 0x4f800000, v172
	s_nop 0
	v_cndmask_b32_e32 v172, v172, v24, vcc
	v_sqrt_f32_e32 v24, v172
	s_nop 0
	v_add_u32_e32 v25, -1, v24
	v_fma_f32 v26, -v25, v24, v172
	v_cmp_ge_f32_e64 s[40:41], 0, v26
	v_add_u32_e32 v26, 1, v24
	s_nop 0
	v_cndmask_b32_e64 v25, v24, v25, s[40:41]
	v_fma_f32 v24, -v26, v24, v172
	v_cmp_lt_f32_e64 s[40:41], 0, v24
	s_nop 1
	v_cndmask_b32_e64 v24, v25, v26, s[40:41]
	v_mul_f32_e32 v25, 0x37800000, v24
	v_cndmask_b32_e32 v24, v24, v25, vcc
	v_cmp_class_f32_e32 vcc, v172, v215
	s_nop 1
	v_cndmask_b32_e32 v172, v24, v172, vcc
	v_div_scale_f32 v30, s[52:53], v172, v172, 1.0
	v_rcp_f32_e32 v31, v30
	s_nop 0
	v_fma_f32 v198, -v30, v31, 1.0
	v_fmac_f32_e32 v31, v198, v31
	v_div_scale_f32 v198, vcc, 1.0, v172, 1.0
	v_mul_f32_e32 v199, v198, v31
	v_fma_f32 v29, -v30, v199, v198
	v_fmac_f32_e32 v199, v29, v31
	v_fma_f32 v30, -v30, v199, v198
	v_div_fmas_f32 v30, v30, v31, v199
	v_div_fixup_f32 v29, v30, v172, 1.0
	v_mul_f32_e32 v168, v168, v29
	v_mul_f32_e32 v169, v169, v29
	v_mul_f32_e32 v170, v170, v29
	v_mul_f32_e32 v171, v171, v29
	v_mul_f32_e32 v168, v168, v20
	v_mul_f32_e32 v169, v169, v21
	v_mul_f32_e32 v170, v170, v22
	v_mul_f32_e32 v171, v171, v23
	v_lshlrev_b32_e32 v24, 16, v124
	v_and_b32_e32 v25, 0xffff0000, v124
	v_lshlrev_b32_e32 v26, 16, v125
	v_and_b32_e32 v27, 0xffff0000, v125
	v_mul_f32_e32 v30, 0xbfb8aa3b, v24
	v_mul_f32_e32 v31, 0xbfb8aa3b, v25
	v_mul_f32_e32 v198, 0xbfb8aa3b, v26
	v_mul_f32_e32 v199, 0xbfb8aa3b, v27
	v_exp_f32_e32 v30, v30
	v_exp_f32_e32 v31, v31
	v_exp_f32_e32 v198, v198
	v_exp_f32_e32 v199, v199
	v_add_f32_e32 v30, 1.0, v30
	v_add_f32_e32 v31, 1.0, v31
	v_add_f32_e32 v198, 1.0, v198
	v_add_f32_e32 v199, 1.0, v199
	v_rcp_f32_e32 v30, v30
	v_rcp_f32_e32 v31, v31
	v_rcp_f32_e32 v198, v198
	v_rcp_f32_e32 v199, v199
	v_mul_f32_e32 v24, v30, v24
	v_mul_f32_e32 v25, v31, v25
	v_mul_f32_e32 v26, v198, v26
	v_mul_f32_e32 v27, v199, v27
	v_mul_f32_e32 v168, v24, v168
	v_mul_f32_e32 v169, v25, v169
	v_mul_f32_e32 v170, v26, v170
	v_mul_f32_e32 v171, v27, v171
	v_cvt_pk_bf16_f32 v28, v168, v169
	v_cvt_pk_bf16_f32 v29, v170, v171
	global_store_dwordx2 v33, v[28:29], s[38:39]
	v_add_u32_e32 v33, 0x100000, v33
	v_fmamk_f32 v178, v178, 0x3c000000, v214
	v_cmp_gt_f32_e32 vcc, s66, v178
	v_mul_f32_e32 v24, 0x4f800000, v178
	s_nop 0
	v_cndmask_b32_e32 v178, v178, v24, vcc
	v_sqrt_f32_e32 v24, v178
	s_nop 0
	v_add_u32_e32 v25, -1, v24
	v_fma_f32 v26, -v25, v24, v178
	v_cmp_ge_f32_e64 s[40:41], 0, v26
	v_add_u32_e32 v26, 1, v24
	s_nop 0
	v_cndmask_b32_e64 v25, v24, v25, s[40:41]
	v_fma_f32 v24, -v26, v24, v178
	v_cmp_lt_f32_e64 s[40:41], 0, v24
	s_nop 1
	v_cndmask_b32_e64 v24, v25, v26, s[40:41]
	v_mul_f32_e32 v25, 0x37800000, v24
	v_cndmask_b32_e32 v24, v24, v25, vcc
	v_cmp_class_f32_e32 vcc, v178, v215
	s_nop 1
	v_cndmask_b32_e32 v178, v24, v178, vcc
	v_div_scale_f32 v30, s[52:53], v178, v178, 1.0
	v_rcp_f32_e32 v31, v30
	s_nop 0
	v_fma_f32 v198, -v30, v31, 1.0
; __device__ __forceinline__ unsigned pk2(float lo, float hi) { f32x2_t v = {lo, hi}; bf16x2_t b = __builtin_convertvector(v, bf16x2_t); return __builtin_bit_cast(unsigned, b); }
; __device__ __forceinline__ float siluf_(float x) { return x * __builtin_amdgcn_rcpf(1.0f + __expf(-x)); }
; __global__ void __launch_bounds__(NTHREADS, 2) fwd_megakernel(Params P) {
;     ...
;                 const float rsn = 1.0f / sqrtf(ss * (1.0f / 128.0f) + NORM_EPS);
;                 const f32x4 wn = *(const f32x4*)(q_gnw + l * 1024 + hp * 256 + 4 * lane);
;                 u32x2 ow;
;                 ow.x = pk2(x[0] * rsn * wn[0] * siluf_(bflo(gg[q].x)), x[1] * rsn * wn[1] * siluf_(bfhi(gg[q].x)));
;                 ow.y = pk2(x[2] * rsn * wn[2] * siluf_(bflo(gg[q].y)), x[3] * rsn * wn[3] * siluf_(bfhi(gg[q].y)));
;                 if (ok[q]) *(u32x2*)(q_hcat + (size_t)2 * T * 1024 + o) = ow;
	v_fmac_f32_e32 v31, v198, v31
	v_div_scale_f32 v198, vcc, 1.0, v178, 1.0
	v_mul_f32_e32 v199, v198, v31
	v_fma_f32 v29, -v30, v199, v198
	v_fmac_f32_e32 v199, v29, v31
	v_fma_f32 v30, -v30, v199, v198
	v_div_fmas_f32 v30, v30, v31, v199
	v_div_fixup_f32 v29, v30, v178, 1.0
	v_mul_f32_e32 v174, v174, v29
	v_mul_f32_e32 v175, v175, v29
	v_mul_f32_e32 v176, v176, v29
	v_mul_f32_e32 v177, v177, v29
	v_mul_f32_e32 v174, v174, v20
	v_mul_f32_e32 v175, v175, v21
	v_mul_f32_e32 v176, v176, v22
	v_mul_f32_e32 v177, v177, v23
	v_lshlrev_b32_e32 v24, 16, v130
	v_and_b32_e32 v25, 0xffff0000, v130
	v_lshlrev_b32_e32 v26, 16, v131
	v_and_b32_e32 v27, 0xffff0000, v131
	v_mul_f32_e32 v30, 0xbfb8aa3b, v24
	v_mul_f32_e32 v31, 0xbfb8aa3b, v25
	v_mul_f32_e32 v198, 0xbfb8aa3b, v26
	v_mul_f32_e32 v199, 0xbfb8aa3b, v27
	v_exp_f32_e32 v30, v30
	v_exp_f32_e32 v31, v31
	v_exp_f32_e32 v198, v198
	v_exp_f32_e32 v199, v199
	v_add_f32_e32 v30, 1.0, v30
	v_add_f32_e32 v31, 1.0, v31
	v_add_f32_e32 v198, 1.0, v198
	v_add_f32_e32 v199, 1.0, v199
	v_rcp_f32_e32 v30, v30
	v_rcp_f32_e32 v31, v31
	v_rcp_f32_e32 v198, v198
	v_rcp_f32_e32 v199, v199
	v_mul_f32_e32 v24, v30, v24
	v_mul_f32_e32 v25, v31, v25
	v_mul_f32_e32 v26, v198, v26
	v_mul_f32_e32 v27, v199, v27
	v_mul_f32_e32 v174, v24, v174
	v_mul_f32_e32 v175, v25, v175
	v_mul_f32_e32 v176, v26, v176
	v_mul_f32_e32 v177, v27, v177
	v_cvt_pk_bf16_f32 v28, v174, v175
	v_cvt_pk_bf16_f32 v29, v176, v177
	global_store_dwordx2 v33, v[28:29], s[38:39]
	v_add_u32_e32 v33, 0x100000, v33
	v_fmamk_f32 v184, v184, 0x3c000000, v214
	v_cmp_gt_f32_e32 vcc, s66, v184
	v_mul_f32_e32 v24, 0x4f800000, v184
	s_nop 0
	v_cndmask_b32_e32 v184, v184, v24, vcc
	v_sqrt_f32_e32 v24, v184
	s_nop 0
	v_add_u32_e32 v25, -1, v24
	v_fma_f32 v26, -v25, v24, v184
	v_cmp_ge_f32_e64 s[40:41], 0, v26
	v_add_u32_e32 v26, 1, v24
	s_nop 0
	v_cndmask_b32_e64 v25, v24, v25, s[40:41]
	v_fma_f32 v24, -v26, v24, v184
	v_cmp_lt_f32_e64 s[40:41], 0, v24
	s_nop 1
	v_cndmask_b32_e64 v24, v25, v26, s[40:41]
	v_mul_f32_e32 v25, 0x37800000, v24
	v_cndmask_b32_e32 v24, v24, v25, vcc
	v_cmp_class_f32_e32 vcc, v184, v215
	s_nop 1
	v_cndmask_b32_e32 v184, v24, v184, vcc
	v_div_scale_f32 v30, s[52:53], v184, v184, 1.0
	v_rcp_f32_e32 v31, v30
	s_nop 0
	v_fma_f32 v198, -v30, v31, 1.0
	v_fmac_f32_e32 v31, v198, v31
	v_div_scale_f32 v198, vcc, 1.0, v184, 1.0
	v_mul_f32_e32 v199, v198, v31
	v_fma_f32 v29, -v30, v199, v198
	v_fmac_f32_e32 v199, v29, v31
	v_fma_f32 v30, -v30, v199, v198
	v_div_fmas_f32 v30, v30, v31, v199
	v_div_fixup_f32 v29, v30, v184, 1.0
	v_mul_f32_e32 v180, v180, v29
	v_mul_f32_e32 v181, v181, v29
	v_mul_f32_e32 v182, v182, v29
	v_mul_f32_e32 v183, v183, v29
	v_mul_f32_e32 v180, v180, v20
	v_mul_f32_e32 v181, v181, v21
	v_mul_f32_e32 v182, v182, v22
	v_mul_f32_e32 v183, v183, v23
	v_lshlrev_b32_e32 v24, 16, v136
	v_and_b32_e32 v25, 0xffff0000, v136
	v_lshlrev_b32_e32 v26, 16, v137
	v_and_b32_e32 v27, 0xffff0000, v137
	v_mul_f32_e32 v30, 0xbfb8aa3b, v24
	v_mul_f32_e32 v31, 0xbfb8aa3b, v25
	v_mul_f32_e32 v198, 0xbfb8aa3b, v26
	v_mul_f32_e32 v199, 0xbfb8aa3b, v27
	v_exp_f32_e32 v30, v30
	v_exp_f32_e32 v31, v31
	v_exp_f32_e32 v198, v198
	v_exp_f32_e32 v199, v199
	v_add_f32_e32 v30, 1.0, v30
	v_add_f32_e32 v31, 1.0, v31
	v_add_f32_e32 v198, 1.0, v198
	v_add_f32_e32 v199, 1.0, v199
	v_rcp_f32_e32 v30, v30
	v_rcp_f32_e32 v31, v31
	v_rcp_f32_e32 v198, v198
	v_rcp_f32_e32 v199, v199
	v_mul_f32_e32 v24, v30, v24
	v_mul_f32_e32 v25, v31, v25
	v_mul_f32_e32 v26, v198, v26
	v_mul_f32_e32 v27, v199, v27
	v_mul_f32_e32 v180, v24, v180
	v_mul_f32_e32 v181, v25, v181
	v_mul_f32_e32 v182, v26, v182
	v_mul_f32_e32 v183, v27, v183
	v_cvt_pk_bf16_f32 v28, v180, v181
	v_cvt_pk_bf16_f32 v29, v182, v183
	global_store_dwordx2 v33, v[28:29], s[38:39]
	v_add_u32_e32 v33, 0x100000, v33
	v_fmamk_f32 v190, v190, 0x3c000000, v214
	v_cmp_gt_f32_e32 vcc, s66, v190
	v_mul_f32_e32 v24, 0x4f800000, v190
	s_nop 0
	v_cndmask_b32_e32 v190, v190, v24, vcc
	v_sqrt_f32_e32 v24, v190
	s_nop 0
	v_add_u32_e32 v25, -1, v24
	v_fma_f32 v26, -v25, v24, v190
	v_cmp_ge_f32_e64 s[40:41], 0, v26
	v_add_u32_e32 v26, 1, v24
	s_nop 0
	v_cndmask_b32_e64 v25, v24, v25, s[40:41]
	v_fma_f32 v24, -v26, v24, v190
; __device__ __forceinline__ unsigned pk2(float lo, float hi) { f32x2_t v = {lo, hi}; bf16x2_t b = __builtin_convertvector(v, bf16x2_t); return __builtin_bit_cast(unsigned, b); }
; __device__ __forceinline__ float siluf_(float x) { return x * __builtin_amdgcn_rcpf(1.0f + __expf(-x)); }
; __global__ void __launch_bounds__(NTHREADS, 2) fwd_megakernel(Params P) {
;     ...
;                 const float rsn = 1.0f / sqrtf(ss * (1.0f / 128.0f) + NORM_EPS);
;                 const f32x4 wn = *(const f32x4*)(q_gnw + l * 1024 + hp * 256 + 4 * lane);
;                 u32x2 ow;
;                 ow.x = pk2(x[0] * rsn * wn[0] * siluf_(bflo(gg[q].x)), x[1] * rsn * wn[1] * siluf_(bfhi(gg[q].x)));
;                 ow.y = pk2(x[2] * rsn * wn[2] * siluf_(bflo(gg[q].y)), x[3] * rsn * wn[3] * siluf_(bfhi(gg[q].y)));
;                 if (ok[q]) *(u32x2*)(q_hcat + (size_t)2 * T * 1024 + o) = ow;
	v_cmp_lt_f32_e64 s[40:41], 0, v24
	s_nop 1
	v_cndmask_b32_e64 v24, v25, v26, s[40:41]
	v_mul_f32_e32 v25, 0x37800000, v24
	v_cndmask_b32_e32 v24, v24, v25, vcc
	v_cmp_class_f32_e32 vcc, v190, v215
	s_nop 1
	v_cndmask_b32_e32 v190, v24, v190, vcc
	v_div_scale_f32 v30, s[52:53], v190, v190, 1.0
	v_rcp_f32_e32 v31, v30
	s_nop 0
	v_fma_f32 v198, -v30, v31, 1.0
	v_fmac_f32_e32 v31, v198, v31
	v_div_scale_f32 v198, vcc, 1.0, v190, 1.0
	v_mul_f32_e32 v199, v198, v31
	v_fma_f32 v29, -v30, v199, v198
	v_fmac_f32_e32 v199, v29, v31
	v_fma_f32 v30, -v30, v199, v198
	v_div_fmas_f32 v30, v30, v31, v199
	v_div_fixup_f32 v29, v30, v190, 1.0
	v_mul_f32_e32 v186, v186, v29
	v_mul_f32_e32 v187, v187, v29
	v_mul_f32_e32 v188, v188, v29
	v_mul_f32_e32 v189, v189, v29
	v_mul_f32_e32 v186, v186, v20
	v_mul_f32_e32 v187, v187, v21
	v_mul_f32_e32 v188, v188, v22
	v_mul_f32_e32 v189, v189, v23
	v_lshlrev_b32_e32 v24, 16, v142
	v_and_b32_e32 v25, 0xffff0000, v142
	v_lshlrev_b32_e32 v26, 16, v143
	v_and_b32_e32 v27, 0xffff0000, v143
	v_mul_f32_e32 v30, 0xbfb8aa3b, v24
	v_mul_f32_e32 v31, 0xbfb8aa3b, v25
	v_mul_f32_e32 v198, 0xbfb8aa3b, v26
	v_mul_f32_e32 v199, 0xbfb8aa3b, v27
	v_exp_f32_e32 v30, v30
	v_exp_f32_e32 v31, v31
	v_exp_f32_e32 v198, v198
	v_exp_f32_e32 v199, v199
	v_add_f32_e32 v30, 1.0, v30
	v_add_f32_e32 v31, 1.0, v31
	v_add_f32_e32 v198, 1.0, v198
	v_add_f32_e32 v199, 1.0, v199
	v_rcp_f32_e32 v30, v30
	v_rcp_f32_e32 v31, v31
	v_rcp_f32_e32 v198, v198
	v_rcp_f32_e32 v199, v199
	v_mul_f32_e32 v24, v30, v24
	v_mul_f32_e32 v25, v31, v25
	v_mul_f32_e32 v26, v198, v26
	v_mul_f32_e32 v27, v199, v27
	v_mul_f32_e32 v186, v24, v186
	v_mul_f32_e32 v187, v25, v187
	v_mul_f32_e32 v188, v26, v188
	v_mul_f32_e32 v189, v27, v189
	v_cvt_pk_bf16_f32 v28, v186, v187
	v_cvt_pk_bf16_f32 v29, v188, v189
	global_store_dwordx2 v33, v[28:29], s[38:39]
	v_add_u32_e32 v33, 0x100000, v33
	v_fmamk_f32 v196, v196, 0x3c000000, v214
	v_cmp_gt_f32_e32 vcc, s66, v196
	v_mul_f32_e32 v24, 0x4f800000, v196
	s_nop 0
	v_cndmask_b32_e32 v196, v196, v24, vcc
	v_sqrt_f32_e32 v24, v196
	s_nop 0
	v_add_u32_e32 v25, -1, v24
	v_fma_f32 v26, -v25, v24, v196
	v_cmp_ge_f32_e64 s[40:41], 0, v26
	v_add_u32_e32 v26, 1, v24
	s_nop 0
	v_cndmask_b32_e64 v25, v24, v25, s[40:41]
	v_fma_f32 v24, -v26, v24, v196
	v_cmp_lt_f32_e64 s[40:41], 0, v24
	s_nop 1
	v_cndmask_b32_e64 v24, v25, v26, s[40:41]
	v_mul_f32_e32 v25, 0x37800000, v24
	v_cndmask_b32_e32 v24, v24, v25, vcc
	v_cmp_class_f32_e32 vcc, v196, v215
	s_nop 1
	v_cndmask_b32_e32 v196, v24, v196, vcc
	v_div_scale_f32 v30, s[52:53], v196, v196, 1.0
	v_rcp_f32_e32 v31, v30
	s_nop 0
	v_fma_f32 v198, -v30, v31, 1.0
	v_fmac_f32_e32 v31, v198, v31
	v_div_scale_f32 v198, vcc, 1.0, v196, 1.0
	v_mul_f32_e32 v199, v198, v31
	v_fma_f32 v29, -v30, v199, v198
	v_fmac_f32_e32 v199, v29, v31
	v_fma_f32 v30, -v30, v199, v198
	v_div_fmas_f32 v30, v30, v31, v199
	v_div_fixup_f32 v29, v30, v196, 1.0
	v_mul_f32_e32 v192, v192, v29
	v_mul_f32_e32 v193, v193, v29
	v_mul_f32_e32 v194, v194, v29
	v_mul_f32_e32 v195, v195, v29
	v_mul_f32_e32 v192, v192, v20
	v_mul_f32_e32 v193, v193, v21
	v_mul_f32_e32 v194, v194, v22
	v_mul_f32_e32 v195, v195, v23
	v_lshlrev_b32_e32 v24, 16, v148
	v_and_b32_e32 v25, 0xffff0000, v148
	v_lshlrev_b32_e32 v26, 16, v149
	v_and_b32_e32 v27, 0xffff0000, v149
	v_mul_f32_e32 v30, 0xbfb8aa3b, v24
	v_mul_f32_e32 v31, 0xbfb8aa3b, v25
	v_mul_f32_e32 v198, 0xbfb8aa3b, v26
	v_mul_f32_e32 v199, 0xbfb8aa3b, v27
	v_exp_f32_e32 v30, v30
	v_exp_f32_e32 v31, v31
	v_exp_f32_e32 v198, v198
	v_exp_f32_e32 v199, v199
	v_add_f32_e32 v30, 1.0, v30
	v_add_f32_e32 v31, 1.0, v31
	v_add_f32_e32 v198, 1.0, v198
	v_add_f32_e32 v199, 1.0, v199
	v_rcp_f32_e32 v30, v30
	v_rcp_f32_e32 v31, v31
	v_rcp_f32_e32 v198, v198
	v_rcp_f32_e32 v199, v199
	v_mul_f32_e32 v24, v30, v24
	v_mul_f32_e32 v25, v31, v25
	v_mul_f32_e32 v26, v198, v26
	v_mul_f32_e32 v27, v199, v27
	v_mul_f32_e32 v192, v24, v192
	v_mul_f32_e32 v193, v25, v193
	v_mul_f32_e32 v194, v26, v194
	v_mul_f32_e32 v195, v27, v195
	v_cvt_pk_bf16_f32 v28, v192, v193
	v_cvt_pk_bf16_f32 v29, v194, v195
	global_store_dwordx2 v33, v[28:29], s[38:39]
	v_add_u32_e32 v33, 0x100000, v33
	s_branch .LBB0_550
